# retention unit epilogue: 8 gate rows per half prefetched with counted vmcnt
# baseline (speedup 1.0000x reference)
; DI void ret_unit(LAS unsigned char* lds, bf16_t* MX, const bf16_t* VT, bf16_t* ST, int b, int hh, int qt, float lgf, float nlgb, int wave, const int mode) {
;     ...
;     f32x16 nrm;
; #pragma unroll
;     for (int i = 0; i < 16; ++i) {
;         float ss = 0.f;
; #pragma unroll
;         for (int db = 0; db < 8; ++db) ss += z[db][i] * z[db][i];
;         ss += shx(ss, 1); ss += shx(ss, 2); ss += shx(ss, 4); ss += shx(ss, 8); ss += shx(ss, 16);
;         nrm[i] = 1.0f / sqrtf(ss * (1.0f / 256.0f) + EPS);
;     }
.LBB0_154:
	v_mul_f32_e32 v128, v96, v96
	v_fmac_f32_e32 v128, v112, v112
	v_fmac_f32_e32 v128, v80, v80
	v_fmac_f32_e32 v128, v64, v64
	v_fmac_f32_e32 v128, v48, v48
	v_mbcnt_lo_u32_b32 v137, -1, 0
	v_mbcnt_hi_u32_b32 v137, -1, v137
	v_fmac_f32_e32 v128, v32, v32
	v_mbcnt_lo_u32_b32 v129, -1, 0
	v_mbcnt_hi_u32_b32 v129, -1, v129
	v_fmac_f32_e32 v128, v16, v16
	v_lshlrev_b32_e32 v129, 2, v129
	v_fmac_f32_e32 v128, v0, v0
	v_xor_b32_e32 v129, 4, v129
	ds_bpermute_b32 v129, v129, v128
	s_mov_b32 s11, 0xf800000
	s_waitcnt lgkmcnt(0)
	v_add_f32_e32 v128, v128, v129
	v_mbcnt_lo_u32_b32 v129, -1, 0
	v_mbcnt_hi_u32_b32 v129, -1, v129
	s_nop 0
	v_lshlrev_b32_e32 v129, 2, v129
	v_xor_b32_e32 v129, 8, v129
	ds_bpermute_b32 v129, v129, v128
	s_waitcnt lgkmcnt(0)
	v_add_f32_e32 v128, v128, v129
	v_mbcnt_lo_u32_b32 v129, -1, 0
	v_mbcnt_hi_u32_b32 v129, -1, v129
	s_nop 0
	v_lshlrev_b32_e32 v129, 2, v129
	v_xor_b32_e32 v129, 16, v129
	ds_bpermute_b32 v129, v129, v128
	s_waitcnt lgkmcnt(0)
	v_add_f32_e32 v128, v128, v129
	v_mbcnt_lo_u32_b32 v129, -1, 0
	v_mbcnt_hi_u32_b32 v129, -1, v129
	s_nop 0
	v_lshlrev_b32_e32 v129, 2, v129
	v_xor_b32_e32 v129, 32, v129
	ds_bpermute_b32 v129, v129, v128
	s_waitcnt lgkmcnt(0)
	v_add_f32_e32 v128, v128, v129
	v_mbcnt_lo_u32_b32 v129, -1, 0
	v_mbcnt_hi_u32_b32 v129, -1, v129
	s_nop 0
	v_lshlrev_b32_e32 v129, 2, v129
	v_xor_b32_e32 v129, 64, v129
	ds_bpermute_b32 v129, v129, v128
	s_waitcnt lgkmcnt(0)
	v_add_f32_e32 v128, v128, v129
	v_fmamk_f32 v128, v128, 0x3b800000, v237
	v_cmp_gt_f32_e32 vcc, s11, v128
	v_mul_f32_e32 v129, 0x4f800000, v128
	s_nop 0
	v_cndmask_b32_e32 v128, v128, v129, vcc
	v_sqrt_f32_e32 v129, v128
	s_nop 0
	v_add_u32_e32 v130, -1, v129
	v_fma_f32 v131, -v130, v129, v128
	v_cmp_ge_f32_e64 s[4:5], 0, v131
	v_add_u32_e32 v131, 1, v129
	s_nop 0
	v_cndmask_b32_e64 v130, v129, v130, s[4:5]
	v_fma_f32 v129, -v131, v129, v128
	v_cmp_lt_f32_e64 s[4:5], 0, v129
	s_nop 1
	v_cndmask_b32_e64 v129, v130, v131, s[4:5]
	v_mul_f32_e32 v130, 0x37800000, v129
	v_cndmask_b32_e32 v129, v129, v130, vcc
	v_cmp_class_f32_e32 vcc, v128, v238
	s_nop 1
	v_cndmask_b32_e32 v128, v129, v128, vcc
	v_div_scale_f32 v129, s[4:5], v128, v128, 1.0
	v_rcp_f32_e32 v130, v129
	s_nop 0
	v_fma_f32 v131, -v129, v130, 1.0
	v_fmac_f32_e32 v130, v131, v130
	v_div_scale_f32 v131, vcc, 1.0, v128, 1.0
	v_mul_f32_e32 v132, v131, v130
	v_fma_f32 v133, -v129, v132, v131
	v_fmac_f32_e32 v132, v133, v130
	v_fma_f32 v129, -v129, v132, v131
	v_div_fmas_f32 v129, v129, v130, v132
	v_div_fixup_f32 v128, v129, v128, 1.0
	v_mul_f32_e32 v129, v97, v97
	v_fmac_f32_e32 v129, v113, v113
	v_fmac_f32_e32 v129, v81, v81
	v_fmac_f32_e32 v129, v65, v65
	v_fmac_f32_e32 v129, v49, v49
	v_fmac_f32_e32 v129, v33, v33
	v_mbcnt_lo_u32_b32 v130, -1, 0
	v_mbcnt_hi_u32_b32 v130, -1, v130
	v_fmac_f32_e32 v129, v17, v17
	v_lshlrev_b32_e32 v130, 2, v130
	v_fmac_f32_e32 v129, v1, v1
	v_xor_b32_e32 v130, 4, v130
	ds_bpermute_b32 v130, v130, v129
	v_mul_f32_e32 v112, v112, v128
	v_mul_f32_e32 v96, v96, v128
	v_mul_f32_e32 v80, v80, v128
	v_mul_f32_e32 v64, v64, v128
	s_waitcnt lgkmcnt(0)
	v_add_f32_e32 v129, v129, v130
	v_mbcnt_lo_u32_b32 v130, -1, 0
	v_mbcnt_hi_u32_b32 v130, -1, v130
	v_mul_f32_e32 v48, v48, v128
	v_lshlrev_b32_e32 v130, 2, v130
	v_xor_b32_e32 v130, 8, v130
	ds_bpermute_b32 v130, v130, v129
	v_mul_f32_e32 v32, v32, v128
	v_mul_f32_e32 v16, v16, v128
	v_mul_f32_e32 v0, v0, v128
	s_waitcnt lgkmcnt(0)
	v_add_f32_e32 v129, v129, v130
	v_mbcnt_lo_u32_b32 v130, -1, 0
	v_mbcnt_hi_u32_b32 v130, -1, v130
	s_nop 0
	v_lshlrev_b32_e32 v130, 2, v130
	v_xor_b32_e32 v130, 16, v130
	ds_bpermute_b32 v130, v130, v129
	s_waitcnt lgkmcnt(0)
	v_add_f32_e32 v129, v129, v130
	v_mbcnt_lo_u32_b32 v130, -1, 0
	v_mbcnt_hi_u32_b32 v130, -1, v130
	s_nop 0
	v_lshlrev_b32_e32 v130, 2, v130
	v_xor_b32_e32 v130, 32, v130
	ds_bpermute_b32 v130, v130, v129
	s_waitcnt lgkmcnt(0)
	v_add_f32_e32 v129, v129, v130
	v_mbcnt_lo_u32_b32 v130, -1, 0
	v_mbcnt_hi_u32_b32 v130, -1, v130
	s_nop 0
	v_lshlrev_b32_e32 v130, 2, v130
	v_xor_b32_e32 v130, 64, v130
	ds_bpermute_b32 v130, v130, v129
	s_waitcnt lgkmcnt(0)
	v_add_f32_e32 v129, v129, v130
	v_fmamk_f32 v129, v129, 0x3b800000, v237
	v_cmp_gt_f32_e32 vcc, s11, v129
	v_mul_f32_e32 v130, 0x4f800000, v129
	s_nop 0
	v_cndmask_b32_e32 v129, v129, v130, vcc
	v_sqrt_f32_e32 v130, v129
	s_nop 0
	v_add_u32_e32 v131, -1, v130
	v_fma_f32 v132, -v131, v130, v129
	v_cmp_ge_f32_e64 s[4:5], 0, v132
	v_add_u32_e32 v132, 1, v130
	s_nop 0
	v_cndmask_b32_e64 v131, v130, v131, s[4:5]
	v_fma_f32 v130, -v132, v130, v129
	v_cmp_lt_f32_e64 s[4:5], 0, v130
	s_nop 1
	v_cndmask_b32_e64 v130, v131, v132, s[4:5]
	v_mul_f32_e32 v131, 0x37800000, v130
	v_cndmask_b32_e32 v130, v130, v131, vcc
	v_cmp_class_f32_e32 vcc, v129, v238
	s_nop 1
	v_cndmask_b32_e32 v129, v130, v129, vcc
	v_div_scale_f32 v130, s[4:5], v129, v129, 1.0
	v_rcp_f32_e32 v131, v130
	s_nop 0
	v_fma_f32 v132, -v130, v131, 1.0
	v_fmac_f32_e32 v131, v132, v131
	v_div_scale_f32 v132, vcc, 1.0, v129, 1.0
	v_mul_f32_e32 v133, v132, v131
	v_fma_f32 v134, -v130, v133, v132
	v_fmac_f32_e32 v133, v134, v131
	v_fma_f32 v130, -v130, v133, v132
	v_div_fmas_f32 v130, v130, v131, v133
	v_div_fixup_f32 v129, v130, v129, 1.0
	v_mul_f32_e32 v130, v98, v98
	v_fmac_f32_e32 v130, v114, v114
	v_fmac_f32_e32 v130, v82, v82
	v_fmac_f32_e32 v130, v66, v66
	v_fmac_f32_e32 v130, v50, v50
	v_fmac_f32_e32 v130, v34, v34
	v_mbcnt_lo_u32_b32 v131, -1, 0
	v_mbcnt_hi_u32_b32 v131, -1, v131
	v_fmac_f32_e32 v130, v18, v18
	v_lshlrev_b32_e32 v131, 2, v131
	v_fmac_f32_e32 v130, v2, v2
	v_xor_b32_e32 v131, 4, v131
	ds_bpermute_b32 v131, v131, v130
	s_waitcnt lgkmcnt(0)
; DI void ret_unit(LAS unsigned char* lds, bf16_t* MX, const bf16_t* VT, bf16_t* ST, int b, int hh, int qt, float lgf, float nlgb, int wave, const int mode) {
;     ...
;     for (int i = 0; i < 16; ++i) {
;         float ss = 0.f;
; #pragma unroll
;         for (int db = 0; db < 8; ++db) ss += z[db][i] * z[db][i];
;         ss += shx(ss, 1); ss += shx(ss, 2); ss += shx(ss, 4); ss += shx(ss, 8); ss += shx(ss, 16);
;         nrm[i] = 1.0f / sqrtf(ss * (1.0f / 256.0f) + EPS);
	v_add_f32_e32 v130, v130, v131
	v_mbcnt_lo_u32_b32 v131, -1, 0
	v_mbcnt_hi_u32_b32 v131, -1, v131
	s_nop 0
	v_lshlrev_b32_e32 v131, 2, v131
	v_xor_b32_e32 v131, 8, v131
	ds_bpermute_b32 v131, v131, v130
	s_waitcnt lgkmcnt(0)
	v_add_f32_e32 v130, v130, v131
	v_mbcnt_lo_u32_b32 v131, -1, 0
	v_mbcnt_hi_u32_b32 v131, -1, v131
	s_nop 0
	v_lshlrev_b32_e32 v131, 2, v131
	v_xor_b32_e32 v131, 16, v131
	ds_bpermute_b32 v131, v131, v130
	s_waitcnt lgkmcnt(0)
	v_add_f32_e32 v130, v130, v131
	v_mbcnt_lo_u32_b32 v131, -1, 0
	v_mbcnt_hi_u32_b32 v131, -1, v131
	s_nop 0
	v_lshlrev_b32_e32 v131, 2, v131
	v_xor_b32_e32 v131, 32, v131
	ds_bpermute_b32 v131, v131, v130
	s_waitcnt lgkmcnt(0)
	v_add_f32_e32 v130, v130, v131
	v_mbcnt_lo_u32_b32 v131, -1, 0
	v_mbcnt_hi_u32_b32 v131, -1, v131
	s_nop 0
	v_lshlrev_b32_e32 v131, 2, v131
	v_xor_b32_e32 v131, 64, v131
	ds_bpermute_b32 v131, v131, v130
	s_waitcnt lgkmcnt(0)
	v_add_f32_e32 v130, v130, v131
	v_fmamk_f32 v130, v130, 0x3b800000, v237
	v_cmp_gt_f32_e32 vcc, s11, v130
	v_mul_f32_e32 v131, 0x4f800000, v130
	s_nop 0
	v_cndmask_b32_e32 v130, v130, v131, vcc
	v_sqrt_f32_e32 v131, v130
	s_nop 0
	v_add_u32_e32 v132, -1, v131
	v_fma_f32 v133, -v132, v131, v130
	v_cmp_ge_f32_e64 s[4:5], 0, v133
	v_add_u32_e32 v133, 1, v131
	s_nop 0
	v_cndmask_b32_e64 v132, v131, v132, s[4:5]
	v_fma_f32 v131, -v133, v131, v130
	v_cmp_lt_f32_e64 s[4:5], 0, v131
	s_nop 1
	v_cndmask_b32_e64 v131, v132, v133, s[4:5]
	v_mul_f32_e32 v132, 0x37800000, v131
	v_cndmask_b32_e32 v131, v131, v132, vcc
	v_cmp_class_f32_e32 vcc, v130, v238
	s_nop 1
	v_cndmask_b32_e32 v130, v131, v130, vcc
	v_div_scale_f32 v131, s[4:5], v130, v130, 1.0
	v_rcp_f32_e32 v132, v131
	s_nop 0
	v_fma_f32 v133, -v131, v132, 1.0
	v_fmac_f32_e32 v132, v133, v132
	v_div_scale_f32 v133, vcc, 1.0, v130, 1.0
	v_mul_f32_e32 v134, v133, v132
	v_fma_f32 v135, -v131, v134, v133
	v_fmac_f32_e32 v134, v135, v132
	v_fma_f32 v131, -v131, v134, v133
	v_div_fmas_f32 v131, v131, v132, v134
	v_div_fixup_f32 v130, v131, v130, 1.0
	v_mul_f32_e32 v131, v99, v99
	v_fmac_f32_e32 v131, v115, v115
	v_fmac_f32_e32 v131, v83, v83
	v_fmac_f32_e32 v131, v67, v67
	v_fmac_f32_e32 v131, v51, v51
	v_fmac_f32_e32 v131, v35, v35
	v_mbcnt_lo_u32_b32 v132, -1, 0
	v_mbcnt_hi_u32_b32 v132, -1, v132
	v_fmac_f32_e32 v131, v19, v19
	v_lshlrev_b32_e32 v132, 2, v132
	v_fmac_f32_e32 v131, v3, v3
	v_xor_b32_e32 v132, 4, v132
	ds_bpermute_b32 v132, v132, v131
	s_waitcnt lgkmcnt(0)
	v_add_f32_e32 v131, v131, v132
	v_mbcnt_lo_u32_b32 v132, -1, 0
	v_mbcnt_hi_u32_b32 v132, -1, v132
	s_nop 0
	v_lshlrev_b32_e32 v132, 2, v132
	v_xor_b32_e32 v132, 8, v132
	ds_bpermute_b32 v132, v132, v131
	s_waitcnt lgkmcnt(0)
	v_add_f32_e32 v131, v131, v132
	v_mbcnt_lo_u32_b32 v132, -1, 0
	v_mbcnt_hi_u32_b32 v132, -1, v132
	s_nop 0
	v_lshlrev_b32_e32 v132, 2, v132
	v_xor_b32_e32 v132, 16, v132
	ds_bpermute_b32 v132, v132, v131
	s_waitcnt lgkmcnt(0)
	v_add_f32_e32 v131, v131, v132
	v_mbcnt_lo_u32_b32 v132, -1, 0
	v_mbcnt_hi_u32_b32 v132, -1, v132
	s_nop 0
	v_lshlrev_b32_e32 v132, 2, v132
	v_xor_b32_e32 v132, 32, v132
	ds_bpermute_b32 v132, v132, v131
	s_waitcnt lgkmcnt(0)
	v_add_f32_e32 v131, v131, v132
	v_mbcnt_lo_u32_b32 v132, -1, 0
	v_mbcnt_hi_u32_b32 v132, -1, v132
	s_nop 0
	v_lshlrev_b32_e32 v132, 2, v132
	v_xor_b32_e32 v132, 64, v132
	ds_bpermute_b32 v132, v132, v131
	s_waitcnt lgkmcnt(0)
	v_add_f32_e32 v131, v131, v132
	v_fmamk_f32 v131, v131, 0x3b800000, v237
	v_cmp_gt_f32_e32 vcc, s11, v131
	v_mul_f32_e32 v132, 0x4f800000, v131
	s_nop 0
	v_cndmask_b32_e32 v131, v131, v132, vcc
	v_sqrt_f32_e32 v132, v131
	s_nop 0
	v_add_u32_e32 v133, -1, v132
	v_fma_f32 v134, -v133, v132, v131
	v_cmp_ge_f32_e64 s[4:5], 0, v134
	v_add_u32_e32 v134, 1, v132
	s_nop 0
	v_cndmask_b32_e64 v133, v132, v133, s[4:5]
	v_fma_f32 v132, -v134, v132, v131
	v_cmp_lt_f32_e64 s[4:5], 0, v132
	s_nop 1
	v_cndmask_b32_e64 v132, v133, v134, s[4:5]
	v_mul_f32_e32 v133, 0x37800000, v132
	v_cndmask_b32_e32 v132, v132, v133, vcc
	v_cmp_class_f32_e32 vcc, v131, v238
	s_nop 1
	v_cndmask_b32_e32 v131, v132, v131, vcc
	v_div_scale_f32 v132, s[4:5], v131, v131, 1.0
	v_rcp_f32_e32 v133, v132
	s_nop 0
	v_fma_f32 v134, -v132, v133, 1.0
	v_fmac_f32_e32 v133, v134, v133
	v_div_scale_f32 v134, vcc, 1.0, v131, 1.0
	v_mul_f32_e32 v135, v134, v133
	v_fma_f32 v136, -v132, v135, v134
	v_fmac_f32_e32 v135, v136, v133
	v_fma_f32 v132, -v132, v135, v134
	v_div_fmas_f32 v132, v132, v133, v135
	v_div_fixup_f32 v131, v132, v131, 1.0
	v_mul_f32_e32 v132, v100, v100
	v_fmac_f32_e32 v132, v116, v116
	v_fmac_f32_e32 v132, v84, v84
	v_fmac_f32_e32 v132, v68, v68
	v_fmac_f32_e32 v132, v52, v52
	v_fmac_f32_e32 v132, v36, v36
	v_mbcnt_lo_u32_b32 v133, -1, 0
	v_mbcnt_hi_u32_b32 v133, -1, v133
	v_fmac_f32_e32 v132, v20, v20
	v_lshlrev_b32_e32 v133, 2, v133
	v_fmac_f32_e32 v132, v4, v4
	v_xor_b32_e32 v133, 4, v133
	ds_bpermute_b32 v133, v133, v132
	s_waitcnt lgkmcnt(0)
	v_add_f32_e32 v132, v132, v133
	v_mbcnt_lo_u32_b32 v133, -1, 0
	v_mbcnt_hi_u32_b32 v133, -1, v133
	s_nop 0
	v_lshlrev_b32_e32 v133, 2, v133
	v_xor_b32_e32 v133, 8, v133
	ds_bpermute_b32 v133, v133, v132
	s_waitcnt lgkmcnt(0)
	v_add_f32_e32 v132, v132, v133
	v_mbcnt_lo_u32_b32 v133, -1, 0
	v_mbcnt_hi_u32_b32 v133, -1, v133
	s_nop 0
	v_lshlrev_b32_e32 v133, 2, v133
	v_xor_b32_e32 v133, 16, v133
	ds_bpermute_b32 v133, v133, v132
	s_waitcnt lgkmcnt(0)
	v_add_f32_e32 v132, v132, v133
	v_mbcnt_lo_u32_b32 v133, -1, 0
	v_mbcnt_hi_u32_b32 v133, -1, v133
	s_nop 0
	v_lshlrev_b32_e32 v133, 2, v133
	v_xor_b32_e32 v133, 32, v133
	ds_bpermute_b32 v133, v133, v132
	s_waitcnt lgkmcnt(0)
; DI void ret_unit(LAS unsigned char* lds, bf16_t* MX, const bf16_t* VT, bf16_t* ST, int b, int hh, int qt, float lgf, float nlgb, int wave, const int mode) {
;     ...
;     for (int i = 0; i < 16; ++i) {
;         float ss = 0.f;
; #pragma unroll
;         for (int db = 0; db < 8; ++db) ss += z[db][i] * z[db][i];
;         ss += shx(ss, 1); ss += shx(ss, 2); ss += shx(ss, 4); ss += shx(ss, 8); ss += shx(ss, 16);
;         nrm[i] = 1.0f / sqrtf(ss * (1.0f / 256.0f) + EPS);
	v_add_f32_e32 v132, v132, v133
	v_mbcnt_lo_u32_b32 v133, -1, 0
	v_mbcnt_hi_u32_b32 v133, -1, v133
	s_nop 0
	v_lshlrev_b32_e32 v133, 2, v133
	v_xor_b32_e32 v133, 64, v133
	ds_bpermute_b32 v133, v133, v132
	s_waitcnt lgkmcnt(0)
	v_add_f32_e32 v132, v132, v133
	v_fmamk_f32 v132, v132, 0x3b800000, v237
	v_cmp_gt_f32_e32 vcc, s11, v132
	v_mul_f32_e32 v133, 0x4f800000, v132
	s_nop 0
	v_cndmask_b32_e32 v132, v132, v133, vcc
	v_sqrt_f32_e32 v133, v132
	s_nop 0
	v_add_u32_e32 v134, -1, v133
	v_fma_f32 v135, -v134, v133, v132
	v_cmp_ge_f32_e64 s[4:5], 0, v135
	v_add_u32_e32 v135, 1, v133
	s_nop 0
	v_cndmask_b32_e64 v134, v133, v134, s[4:5]
	v_fma_f32 v133, -v135, v133, v132
	v_cmp_lt_f32_e64 s[4:5], 0, v133
	s_nop 1
	v_cndmask_b32_e64 v133, v134, v135, s[4:5]
	v_mul_f32_e32 v134, 0x37800000, v133
	v_cndmask_b32_e32 v133, v133, v134, vcc
	v_cmp_class_f32_e32 vcc, v132, v238
	s_nop 1
	v_cndmask_b32_e32 v132, v133, v132, vcc
	v_div_scale_f32 v133, s[4:5], v132, v132, 1.0
	v_rcp_f32_e32 v134, v133
	s_nop 0
	v_fma_f32 v135, -v133, v134, 1.0
	v_fmac_f32_e32 v134, v135, v134
	v_div_scale_f32 v135, vcc, 1.0, v132, 1.0
	v_mul_f32_e32 v136, v135, v134
	v_fma_f32 v138, -v133, v136, v135
	v_fmac_f32_e32 v136, v138, v134
	v_fma_f32 v133, -v133, v136, v135
	v_div_fmas_f32 v133, v133, v134, v136
	v_div_fixup_f32 v132, v133, v132, 1.0
	v_mul_f32_e32 v133, v101, v101
	v_fmac_f32_e32 v133, v117, v117
	v_fmac_f32_e32 v133, v85, v85
	v_fmac_f32_e32 v133, v69, v69
	v_fmac_f32_e32 v133, v53, v53
	v_fmac_f32_e32 v133, v37, v37
	v_mbcnt_lo_u32_b32 v134, -1, 0
	v_mbcnt_hi_u32_b32 v134, -1, v134
	v_fmac_f32_e32 v133, v21, v21
	v_lshlrev_b32_e32 v134, 2, v134
	v_fmac_f32_e32 v133, v5, v5
	v_xor_b32_e32 v134, 4, v134
	ds_bpermute_b32 v134, v134, v133
	s_waitcnt lgkmcnt(0)
	v_add_f32_e32 v133, v133, v134
	v_mbcnt_lo_u32_b32 v134, -1, 0
	v_mbcnt_hi_u32_b32 v134, -1, v134
	s_nop 0
	v_lshlrev_b32_e32 v134, 2, v134
	v_xor_b32_e32 v134, 8, v134
	ds_bpermute_b32 v134, v134, v133
	s_waitcnt lgkmcnt(0)
	v_add_f32_e32 v133, v133, v134
	v_mbcnt_lo_u32_b32 v134, -1, 0
	v_mbcnt_hi_u32_b32 v134, -1, v134
	s_nop 0
	v_lshlrev_b32_e32 v134, 2, v134
	v_xor_b32_e32 v134, 16, v134
	ds_bpermute_b32 v134, v134, v133
	s_waitcnt lgkmcnt(0)
	v_add_f32_e32 v133, v133, v134
	v_mbcnt_lo_u32_b32 v134, -1, 0
	v_mbcnt_hi_u32_b32 v134, -1, v134
	s_nop 0
	v_lshlrev_b32_e32 v134, 2, v134
	v_xor_b32_e32 v134, 32, v134
	ds_bpermute_b32 v134, v134, v133
	s_waitcnt lgkmcnt(0)
	v_add_f32_e32 v133, v133, v134
	v_mbcnt_lo_u32_b32 v134, -1, 0
	v_mbcnt_hi_u32_b32 v134, -1, v134
	s_nop 0
	v_lshlrev_b32_e32 v134, 2, v134
	v_xor_b32_e32 v134, 64, v134
	ds_bpermute_b32 v134, v134, v133
	s_waitcnt lgkmcnt(0)
	v_add_f32_e32 v133, v133, v134
	v_fmamk_f32 v133, v133, 0x3b800000, v237
	v_cmp_gt_f32_e32 vcc, s11, v133
	v_mul_f32_e32 v134, 0x4f800000, v133
	s_nop 0
	v_cndmask_b32_e32 v133, v133, v134, vcc
	v_sqrt_f32_e32 v134, v133
	s_nop 0
	v_add_u32_e32 v135, -1, v134
	v_fma_f32 v136, -v135, v134, v133
	v_cmp_ge_f32_e64 s[4:5], 0, v136
	v_add_u32_e32 v136, 1, v134
	s_nop 0
	v_cndmask_b32_e64 v135, v134, v135, s[4:5]
	v_fma_f32 v134, -v136, v134, v133
	v_cmp_lt_f32_e64 s[4:5], 0, v134
	s_nop 1
	v_cndmask_b32_e64 v134, v135, v136, s[4:5]
	v_mul_f32_e32 v135, 0x37800000, v134
	v_cndmask_b32_e32 v134, v134, v135, vcc
	v_cmp_class_f32_e32 vcc, v133, v238
	s_nop 1
	v_cndmask_b32_e32 v133, v134, v133, vcc
	v_div_scale_f32 v134, s[4:5], v133, v133, 1.0
	v_rcp_f32_e32 v135, v134
	s_nop 0
	v_fma_f32 v136, -v134, v135, 1.0
	v_fmac_f32_e32 v135, v136, v135
	v_div_scale_f32 v136, vcc, 1.0, v133, 1.0
	v_mul_f32_e32 v138, v136, v135
	v_fma_f32 v139, -v134, v138, v136
	v_fmac_f32_e32 v138, v139, v135
	v_fma_f32 v134, -v134, v138, v136
	v_div_fmas_f32 v134, v134, v135, v138
	v_div_fixup_f32 v133, v134, v133, 1.0
	v_mul_f32_e32 v134, v102, v102
	v_fmac_f32_e32 v134, v118, v118
	v_fmac_f32_e32 v134, v86, v86
	v_fmac_f32_e32 v134, v70, v70
	v_fmac_f32_e32 v134, v54, v54
	v_fmac_f32_e32 v134, v38, v38
	v_mbcnt_lo_u32_b32 v135, -1, 0
	v_mbcnt_hi_u32_b32 v135, -1, v135
	v_fmac_f32_e32 v134, v22, v22
	v_lshlrev_b32_e32 v135, 2, v135
	v_fmac_f32_e32 v134, v6, v6
	v_xor_b32_e32 v135, 4, v135
	ds_bpermute_b32 v135, v135, v134
	s_waitcnt lgkmcnt(0)
	v_add_f32_e32 v134, v134, v135
	v_mbcnt_lo_u32_b32 v135, -1, 0
	v_mbcnt_hi_u32_b32 v135, -1, v135
	s_nop 0
	v_lshlrev_b32_e32 v135, 2, v135
	v_xor_b32_e32 v135, 8, v135
	ds_bpermute_b32 v135, v135, v134
	s_waitcnt lgkmcnt(0)
	v_add_f32_e32 v134, v134, v135
	v_mbcnt_lo_u32_b32 v135, -1, 0
	v_mbcnt_hi_u32_b32 v135, -1, v135
	s_nop 0
	v_lshlrev_b32_e32 v135, 2, v135
	v_xor_b32_e32 v135, 16, v135
	ds_bpermute_b32 v135, v135, v134
	s_waitcnt lgkmcnt(0)
	v_add_f32_e32 v134, v134, v135
	v_mbcnt_lo_u32_b32 v135, -1, 0
	v_mbcnt_hi_u32_b32 v135, -1, v135
	s_nop 0
	v_lshlrev_b32_e32 v135, 2, v135
	v_xor_b32_e32 v135, 32, v135
	ds_bpermute_b32 v135, v135, v134
	s_waitcnt lgkmcnt(0)
	v_add_f32_e32 v134, v134, v135
	v_mbcnt_lo_u32_b32 v135, -1, 0
	v_mbcnt_hi_u32_b32 v135, -1, v135
	s_nop 0
	v_lshlrev_b32_e32 v135, 2, v135
	v_xor_b32_e32 v135, 64, v135
	ds_bpermute_b32 v135, v135, v134
	s_waitcnt lgkmcnt(0)
; DI void ret_unit(LAS unsigned char* lds, bf16_t* MX, const bf16_t* VT, bf16_t* ST, int b, int hh, int qt, float lgf, float nlgb, int wave, const int mode) {
;     ...
;     for (int i = 0; i < 16; ++i) {
;         float ss = 0.f;
; #pragma unroll
;         for (int db = 0; db < 8; ++db) ss += z[db][i] * z[db][i];
;         ss += shx(ss, 1); ss += shx(ss, 2); ss += shx(ss, 4); ss += shx(ss, 8); ss += shx(ss, 16);
;         nrm[i] = 1.0f / sqrtf(ss * (1.0f / 256.0f) + EPS);
	v_add_f32_e32 v134, v134, v135
	v_fmamk_f32 v134, v134, 0x3b800000, v237
	v_cmp_gt_f32_e32 vcc, s11, v134
	v_mul_f32_e32 v135, 0x4f800000, v134
	s_nop 0
	v_cndmask_b32_e32 v134, v134, v135, vcc
	v_sqrt_f32_e32 v135, v134
	s_nop 0
	v_add_u32_e32 v136, -1, v135
	v_fma_f32 v138, -v136, v135, v134
	v_cmp_ge_f32_e64 s[4:5], 0, v138
	v_add_u32_e32 v138, 1, v135
	s_nop 0
	v_cndmask_b32_e64 v136, v135, v136, s[4:5]
	v_fma_f32 v135, -v138, v135, v134
	v_cmp_lt_f32_e64 s[4:5], 0, v135
	s_nop 1
	v_cndmask_b32_e64 v135, v136, v138, s[4:5]
	v_mul_f32_e32 v136, 0x37800000, v135
	v_cndmask_b32_e32 v135, v135, v136, vcc
	v_cmp_class_f32_e32 vcc, v134, v238
	s_nop 1
	v_cndmask_b32_e32 v134, v135, v134, vcc
	v_div_scale_f32 v135, s[4:5], v134, v134, 1.0
	v_rcp_f32_e32 v136, v135
	s_nop 0
	v_fma_f32 v138, -v135, v136, 1.0
	v_fmac_f32_e32 v136, v138, v136
	v_div_scale_f32 v138, vcc, 1.0, v134, 1.0
	v_mul_f32_e32 v139, v138, v136
	v_fma_f32 v140, -v135, v139, v138
	v_fmac_f32_e32 v139, v140, v136
	v_fma_f32 v135, -v135, v139, v138
	v_div_fmas_f32 v135, v135, v136, v139
	v_div_fixup_f32 v134, v135, v134, 1.0
	v_mul_f32_e32 v135, v103, v103
	v_fmac_f32_e32 v135, v119, v119
	v_fmac_f32_e32 v135, v87, v87
	v_fmac_f32_e32 v135, v71, v71
	v_fmac_f32_e32 v135, v55, v55
	v_fmac_f32_e32 v135, v39, v39
	v_mbcnt_lo_u32_b32 v136, -1, 0
	v_mbcnt_hi_u32_b32 v136, -1, v136
	v_fmac_f32_e32 v135, v23, v23
	v_lshlrev_b32_e32 v136, 2, v136
	v_fmac_f32_e32 v135, v7, v7
	v_xor_b32_e32 v136, 4, v136
	ds_bpermute_b32 v136, v136, v135
	s_waitcnt lgkmcnt(0)
	v_add_f32_e32 v135, v135, v136
	v_mbcnt_lo_u32_b32 v136, -1, 0
	v_mbcnt_hi_u32_b32 v136, -1, v136
	s_nop 0
	v_lshlrev_b32_e32 v136, 2, v136
	v_xor_b32_e32 v136, 8, v136
	ds_bpermute_b32 v136, v136, v135
	s_waitcnt lgkmcnt(0)
	v_add_f32_e32 v135, v135, v136
	v_mbcnt_lo_u32_b32 v136, -1, 0
	v_mbcnt_hi_u32_b32 v136, -1, v136
	s_nop 0
	v_lshlrev_b32_e32 v136, 2, v136
	v_xor_b32_e32 v136, 16, v136
	ds_bpermute_b32 v136, v136, v135
	s_waitcnt lgkmcnt(0)
	v_add_f32_e32 v135, v135, v136
	v_mbcnt_lo_u32_b32 v136, -1, 0
	v_mbcnt_hi_u32_b32 v136, -1, v136
	s_nop 0
	v_lshlrev_b32_e32 v136, 2, v136
	v_xor_b32_e32 v136, 32, v136
	ds_bpermute_b32 v136, v136, v135
	s_waitcnt lgkmcnt(0)
	v_add_f32_e32 v135, v135, v136
	v_mbcnt_lo_u32_b32 v136, -1, 0
	v_mbcnt_hi_u32_b32 v136, -1, v136
	s_nop 0
	v_lshlrev_b32_e32 v136, 2, v136
	v_xor_b32_e32 v136, 64, v136
	ds_bpermute_b32 v136, v136, v135
	s_waitcnt lgkmcnt(0)
	v_add_f32_e32 v135, v135, v136
	v_fmamk_f32 v135, v135, 0x3b800000, v237
	v_cmp_gt_f32_e32 vcc, s11, v135
	v_mul_f32_e32 v136, 0x4f800000, v135
	s_nop 0
	v_cndmask_b32_e32 v135, v135, v136, vcc
	v_sqrt_f32_e32 v136, v135
	s_nop 0
	v_add_u32_e32 v138, -1, v136
	v_fma_f32 v139, -v138, v136, v135
	v_cmp_ge_f32_e64 s[4:5], 0, v139
	v_add_u32_e32 v139, 1, v136
	s_nop 0
	v_cndmask_b32_e64 v138, v136, v138, s[4:5]
	v_fma_f32 v136, -v139, v136, v135
	v_cmp_lt_f32_e64 s[4:5], 0, v136
	s_nop 1
	v_cndmask_b32_e64 v136, v138, v139, s[4:5]
	v_mul_f32_e32 v138, 0x37800000, v136
	v_cndmask_b32_e32 v136, v136, v138, vcc
	v_cmp_class_f32_e32 vcc, v135, v238
	s_nop 1
	v_cndmask_b32_e32 v135, v136, v135, vcc
	v_div_scale_f32 v136, s[4:5], v135, v135, 1.0
	v_rcp_f32_e32 v138, v136
	s_nop 0
	v_fma_f32 v139, -v136, v138, 1.0
	v_fmac_f32_e32 v138, v139, v138
	v_div_scale_f32 v139, vcc, 1.0, v135, 1.0
	v_mul_f32_e32 v140, v139, v138
	v_fma_f32 v141, -v136, v140, v139
	v_fmac_f32_e32 v140, v141, v138
	v_fma_f32 v136, -v136, v140, v139
	v_div_fmas_f32 v136, v136, v138, v140
	v_div_fixup_f32 v135, v136, v135, 1.0
	v_mul_f32_e32 v136, v104, v104
	v_fmac_f32_e32 v136, v120, v120
	v_fmac_f32_e32 v136, v88, v88
	v_fmac_f32_e32 v136, v72, v72
	v_fmac_f32_e32 v136, v56, v56
	v_fmac_f32_e32 v136, v40, v40
	v_mbcnt_lo_u32_b32 v138, -1, 0
	v_mbcnt_hi_u32_b32 v138, -1, v138
	v_fmac_f32_e32 v136, v24, v24
	v_lshlrev_b32_e32 v138, 2, v138
	v_fmac_f32_e32 v136, v8, v8
	v_xor_b32_e32 v138, 4, v138
	ds_bpermute_b32 v138, v138, v136
	s_waitcnt lgkmcnt(0)
	v_add_f32_e32 v136, v136, v138
	v_mbcnt_lo_u32_b32 v138, -1, 0
	v_mbcnt_hi_u32_b32 v138, -1, v138
	s_nop 0
	v_lshlrev_b32_e32 v138, 2, v138
	v_xor_b32_e32 v138, 8, v138
	ds_bpermute_b32 v138, v138, v136
	s_waitcnt lgkmcnt(0)
	v_add_f32_e32 v136, v136, v138
	v_mbcnt_lo_u32_b32 v138, -1, 0
	v_mbcnt_hi_u32_b32 v138, -1, v138
	s_nop 0
	v_lshlrev_b32_e32 v138, 2, v138
	v_xor_b32_e32 v138, 16, v138
	ds_bpermute_b32 v138, v138, v136
	s_waitcnt lgkmcnt(0)
	v_add_f32_e32 v136, v136, v138
	v_mbcnt_lo_u32_b32 v138, -1, 0
	v_mbcnt_hi_u32_b32 v138, -1, v138
	s_nop 0
	v_lshlrev_b32_e32 v138, 2, v138
	v_xor_b32_e32 v138, 32, v138
	ds_bpermute_b32 v138, v138, v136
	s_waitcnt lgkmcnt(0)
	v_add_f32_e32 v136, v136, v138
	v_mbcnt_lo_u32_b32 v138, -1, 0
	v_mbcnt_hi_u32_b32 v138, -1, v138
	s_nop 0
	v_lshlrev_b32_e32 v138, 2, v138
	v_xor_b32_e32 v138, 64, v138
	ds_bpermute_b32 v138, v138, v136
	s_waitcnt lgkmcnt(0)
; DI void ret_unit(LAS unsigned char* lds, bf16_t* MX, const bf16_t* VT, bf16_t* ST, int b, int hh, int qt, float lgf, float nlgb, int wave, const int mode) {
;     ...
;     for (int i = 0; i < 16; ++i) {
;         float ss = 0.f;
; #pragma unroll
;         for (int db = 0; db < 8; ++db) ss += z[db][i] * z[db][i];
;         ss += shx(ss, 1); ss += shx(ss, 2); ss += shx(ss, 4); ss += shx(ss, 8); ss += shx(ss, 16);
;         nrm[i] = 1.0f / sqrtf(ss * (1.0f / 256.0f) + EPS);
	v_add_f32_e32 v136, v136, v138
	v_fmamk_f32 v136, v136, 0x3b800000, v237
	v_cmp_gt_f32_e32 vcc, s11, v136
	v_mul_f32_e32 v138, 0x4f800000, v136
	s_nop 0
	v_cndmask_b32_e32 v136, v136, v138, vcc
	v_sqrt_f32_e32 v138, v136
	s_nop 0
	v_add_u32_e32 v139, -1, v138
	v_fma_f32 v140, -v139, v138, v136
	v_cmp_ge_f32_e64 s[4:5], 0, v140
	v_add_u32_e32 v140, 1, v138
	s_nop 0
	v_cndmask_b32_e64 v139, v138, v139, s[4:5]
	v_fma_f32 v138, -v140, v138, v136
	v_cmp_lt_f32_e64 s[4:5], 0, v138
	s_nop 1
	v_cndmask_b32_e64 v138, v139, v140, s[4:5]
	v_mul_f32_e32 v139, 0x37800000, v138
	v_cndmask_b32_e32 v138, v138, v139, vcc
	v_cmp_class_f32_e32 vcc, v136, v238
	s_nop 1
	v_cndmask_b32_e32 v136, v138, v136, vcc
	v_div_scale_f32 v138, s[4:5], v136, v136, 1.0
	v_rcp_f32_e32 v139, v138
	s_nop 0
	v_fma_f32 v140, -v138, v139, 1.0
	v_fmac_f32_e32 v139, v140, v139
	v_div_scale_f32 v140, vcc, 1.0, v136, 1.0
	v_mul_f32_e32 v141, v140, v139
	v_fma_f32 v142, -v138, v141, v140
	v_fmac_f32_e32 v141, v142, v139
	v_fma_f32 v138, -v138, v141, v140
	v_div_fmas_f32 v138, v138, v139, v141
	v_div_fixup_f32 v136, v138, v136, 1.0
	v_mul_f32_e32 v138, v105, v105
	v_fmac_f32_e32 v138, v121, v121
	v_fmac_f32_e32 v138, v89, v89
	v_fmac_f32_e32 v138, v73, v73
	v_fmac_f32_e32 v138, v57, v57
	v_fmac_f32_e32 v138, v41, v41
	v_mbcnt_lo_u32_b32 v139, -1, 0
	v_mbcnt_hi_u32_b32 v139, -1, v139
	v_fmac_f32_e32 v138, v25, v25
	v_lshlrev_b32_e32 v139, 2, v139
	v_fmac_f32_e32 v138, v9, v9
	v_xor_b32_e32 v139, 4, v139
	ds_bpermute_b32 v139, v139, v138
	s_waitcnt lgkmcnt(0)
	v_add_f32_e32 v138, v138, v139
	v_mbcnt_lo_u32_b32 v139, -1, 0
	v_mbcnt_hi_u32_b32 v139, -1, v139
	s_nop 0
	v_lshlrev_b32_e32 v139, 2, v139
	v_xor_b32_e32 v139, 8, v139
	ds_bpermute_b32 v139, v139, v138
	s_waitcnt lgkmcnt(0)
	v_add_f32_e32 v138, v138, v139
	v_mbcnt_lo_u32_b32 v139, -1, 0
	v_mbcnt_hi_u32_b32 v139, -1, v139
	s_nop 0
	v_lshlrev_b32_e32 v139, 2, v139
	v_xor_b32_e32 v139, 16, v139
	ds_bpermute_b32 v139, v139, v138
	s_waitcnt lgkmcnt(0)
	v_add_f32_e32 v138, v138, v139
	v_mbcnt_lo_u32_b32 v139, -1, 0
	v_mbcnt_hi_u32_b32 v139, -1, v139
	s_nop 0
	v_lshlrev_b32_e32 v139, 2, v139
	v_xor_b32_e32 v139, 32, v139
	ds_bpermute_b32 v139, v139, v138
	s_waitcnt lgkmcnt(0)
	v_add_f32_e32 v138, v138, v139
	v_mbcnt_lo_u32_b32 v139, -1, 0
	v_mbcnt_hi_u32_b32 v139, -1, v139
	s_nop 0
	v_lshlrev_b32_e32 v139, 2, v139
	v_xor_b32_e32 v139, 64, v139
	ds_bpermute_b32 v139, v139, v138
	s_waitcnt lgkmcnt(0)
	v_add_f32_e32 v138, v138, v139
	v_fmamk_f32 v138, v138, 0x3b800000, v237
	v_cmp_gt_f32_e32 vcc, s11, v138
	v_mul_f32_e32 v139, 0x4f800000, v138
	s_nop 0
	v_cndmask_b32_e32 v138, v138, v139, vcc
	v_sqrt_f32_e32 v139, v138
	s_nop 0
	v_add_u32_e32 v140, -1, v139
	v_fma_f32 v141, -v140, v139, v138
	v_cmp_ge_f32_e64 s[4:5], 0, v141
	v_add_u32_e32 v141, 1, v139
	s_nop 0
	v_cndmask_b32_e64 v140, v139, v140, s[4:5]
	v_fma_f32 v139, -v141, v139, v138
	v_cmp_lt_f32_e64 s[4:5], 0, v139
	s_nop 1
	v_cndmask_b32_e64 v139, v140, v141, s[4:5]
	v_mul_f32_e32 v140, 0x37800000, v139
	v_cndmask_b32_e32 v139, v139, v140, vcc
	v_cmp_class_f32_e32 vcc, v138, v238
	s_nop 1
	v_cndmask_b32_e32 v138, v139, v138, vcc
	v_div_scale_f32 v139, s[4:5], v138, v138, 1.0
	v_rcp_f32_e32 v140, v139
	s_nop 0
	v_fma_f32 v141, -v139, v140, 1.0
	v_fmac_f32_e32 v140, v141, v140
	v_div_scale_f32 v141, vcc, 1.0, v138, 1.0
	v_mul_f32_e32 v142, v141, v140
	v_fma_f32 v143, -v139, v142, v141
	v_fmac_f32_e32 v142, v143, v140
	v_fma_f32 v139, -v139, v142, v141
	v_div_fmas_f32 v139, v139, v140, v142
	v_div_fixup_f32 v138, v139, v138, 1.0
	v_mul_f32_e32 v139, v106, v106
	v_fmac_f32_e32 v139, v122, v122
	v_fmac_f32_e32 v139, v90, v90
	v_fmac_f32_e32 v139, v74, v74
	v_fmac_f32_e32 v139, v58, v58
	v_fmac_f32_e32 v139, v42, v42
	v_mbcnt_lo_u32_b32 v140, -1, 0
	v_mbcnt_hi_u32_b32 v140, -1, v140
	v_fmac_f32_e32 v139, v26, v26
	v_lshlrev_b32_e32 v140, 2, v140
	v_fmac_f32_e32 v139, v10, v10
	v_xor_b32_e32 v140, 4, v140
	ds_bpermute_b32 v140, v140, v139
	s_waitcnt lgkmcnt(0)
	v_add_f32_e32 v139, v139, v140
	v_mbcnt_lo_u32_b32 v140, -1, 0
	v_mbcnt_hi_u32_b32 v140, -1, v140
	s_nop 0
	v_lshlrev_b32_e32 v140, 2, v140
	v_xor_b32_e32 v140, 8, v140
	ds_bpermute_b32 v140, v140, v139
	s_waitcnt lgkmcnt(0)
	v_add_f32_e32 v139, v139, v140
	v_mbcnt_lo_u32_b32 v140, -1, 0
	v_mbcnt_hi_u32_b32 v140, -1, v140
	s_nop 0
	v_lshlrev_b32_e32 v140, 2, v140
	v_xor_b32_e32 v140, 16, v140
	ds_bpermute_b32 v140, v140, v139
	s_waitcnt lgkmcnt(0)
	v_add_f32_e32 v139, v139, v140
	v_mbcnt_lo_u32_b32 v140, -1, 0
	v_mbcnt_hi_u32_b32 v140, -1, v140
	s_nop 0
	v_lshlrev_b32_e32 v140, 2, v140
	v_xor_b32_e32 v140, 32, v140
	ds_bpermute_b32 v140, v140, v139
	s_waitcnt lgkmcnt(0)
	v_add_f32_e32 v139, v139, v140
	v_mbcnt_lo_u32_b32 v140, -1, 0
	v_mbcnt_hi_u32_b32 v140, -1, v140
	s_nop 0
	v_lshlrev_b32_e32 v140, 2, v140
	v_xor_b32_e32 v140, 64, v140
	ds_bpermute_b32 v140, v140, v139
	s_waitcnt lgkmcnt(0)
; DI void ret_unit(LAS unsigned char* lds, bf16_t* MX, const bf16_t* VT, bf16_t* ST, int b, int hh, int qt, float lgf, float nlgb, int wave, const int mode) {
;     ...
;     for (int i = 0; i < 16; ++i) {
;         float ss = 0.f;
; #pragma unroll
;         for (int db = 0; db < 8; ++db) ss += z[db][i] * z[db][i];
;         ss += shx(ss, 1); ss += shx(ss, 2); ss += shx(ss, 4); ss += shx(ss, 8); ss += shx(ss, 16);
;         nrm[i] = 1.0f / sqrtf(ss * (1.0f / 256.0f) + EPS);
	v_add_f32_e32 v139, v139, v140
	v_fmamk_f32 v139, v139, 0x3b800000, v237
	v_cmp_gt_f32_e32 vcc, s11, v139
	v_mul_f32_e32 v140, 0x4f800000, v139
	s_nop 0
	v_cndmask_b32_e32 v139, v139, v140, vcc
	v_sqrt_f32_e32 v140, v139
	s_nop 0
	v_add_u32_e32 v141, -1, v140
	v_fma_f32 v142, -v141, v140, v139
	v_cmp_ge_f32_e64 s[4:5], 0, v142
	v_add_u32_e32 v142, 1, v140
	s_nop 0
	v_cndmask_b32_e64 v141, v140, v141, s[4:5]
	v_fma_f32 v140, -v142, v140, v139
	v_cmp_lt_f32_e64 s[4:5], 0, v140
	s_nop 1
	v_cndmask_b32_e64 v140, v141, v142, s[4:5]
	v_mul_f32_e32 v141, 0x37800000, v140
	v_cndmask_b32_e32 v140, v140, v141, vcc
	v_cmp_class_f32_e32 vcc, v139, v238
	s_nop 1
	v_cndmask_b32_e32 v139, v140, v139, vcc
	v_div_scale_f32 v140, s[4:5], v139, v139, 1.0
	v_rcp_f32_e32 v141, v140
	s_nop 0
	v_fma_f32 v142, -v140, v141, 1.0
	v_fmac_f32_e32 v141, v142, v141
	v_div_scale_f32 v142, vcc, 1.0, v139, 1.0
	v_mul_f32_e32 v143, v142, v141
	v_fma_f32 v144, -v140, v143, v142
	v_fmac_f32_e32 v143, v144, v141
	v_fma_f32 v140, -v140, v143, v142
	v_div_fmas_f32 v140, v140, v141, v143
	v_div_fixup_f32 v139, v140, v139, 1.0
	v_mul_f32_e32 v140, v107, v107
	v_fmac_f32_e32 v140, v123, v123
	v_fmac_f32_e32 v140, v91, v91
	v_fmac_f32_e32 v140, v75, v75
	v_fmac_f32_e32 v140, v59, v59
	v_fmac_f32_e32 v140, v43, v43
	v_mbcnt_lo_u32_b32 v141, -1, 0
	v_mbcnt_hi_u32_b32 v141, -1, v141
	v_fmac_f32_e32 v140, v27, v27
	v_lshlrev_b32_e32 v141, 2, v141
	v_fmac_f32_e32 v140, v11, v11
	v_xor_b32_e32 v141, 4, v141
	ds_bpermute_b32 v141, v141, v140
	s_waitcnt lgkmcnt(0)
	v_add_f32_e32 v140, v140, v141
	v_mbcnt_lo_u32_b32 v141, -1, 0
	v_mbcnt_hi_u32_b32 v141, -1, v141
	s_nop 0
	v_lshlrev_b32_e32 v141, 2, v141
	v_xor_b32_e32 v141, 8, v141
	ds_bpermute_b32 v141, v141, v140
	s_waitcnt lgkmcnt(0)
	v_add_f32_e32 v140, v140, v141
	v_mbcnt_lo_u32_b32 v141, -1, 0
	v_mbcnt_hi_u32_b32 v141, -1, v141
	s_nop 0
	v_lshlrev_b32_e32 v141, 2, v141
	v_xor_b32_e32 v141, 16, v141
	ds_bpermute_b32 v141, v141, v140
	s_waitcnt lgkmcnt(0)
	v_add_f32_e32 v140, v140, v141
	v_mbcnt_lo_u32_b32 v141, -1, 0
	v_mbcnt_hi_u32_b32 v141, -1, v141
	s_nop 0
	v_lshlrev_b32_e32 v141, 2, v141
	v_xor_b32_e32 v141, 32, v141
	ds_bpermute_b32 v141, v141, v140
	s_waitcnt lgkmcnt(0)
	v_add_f32_e32 v140, v140, v141
	v_mbcnt_lo_u32_b32 v141, -1, 0
	v_mbcnt_hi_u32_b32 v141, -1, v141
	s_nop 0
	v_lshlrev_b32_e32 v141, 2, v141
	v_xor_b32_e32 v141, 64, v141
	ds_bpermute_b32 v141, v141, v140
	s_waitcnt lgkmcnt(0)
	v_add_f32_e32 v140, v140, v141
	v_fmamk_f32 v140, v140, 0x3b800000, v237
	v_cmp_gt_f32_e32 vcc, s11, v140
	v_mul_f32_e32 v141, 0x4f800000, v140
	s_nop 0
	v_cndmask_b32_e32 v140, v140, v141, vcc
	v_sqrt_f32_e32 v141, v140
	s_nop 0
	v_add_u32_e32 v142, -1, v141
	v_fma_f32 v143, -v142, v141, v140
	v_cmp_ge_f32_e64 s[4:5], 0, v143
	v_add_u32_e32 v143, 1, v141
	s_nop 0
	v_cndmask_b32_e64 v142, v141, v142, s[4:5]
	v_fma_f32 v141, -v143, v141, v140
	v_cmp_lt_f32_e64 s[4:5], 0, v141
	s_nop 1
	v_cndmask_b32_e64 v141, v142, v143, s[4:5]
	v_mul_f32_e32 v142, 0x37800000, v141
	v_cndmask_b32_e32 v141, v141, v142, vcc
	v_cmp_class_f32_e32 vcc, v140, v238
	s_nop 1
	v_cndmask_b32_e32 v140, v141, v140, vcc
	v_div_scale_f32 v141, s[4:5], v140, v140, 1.0
	v_rcp_f32_e32 v142, v141
	s_nop 0
	v_fma_f32 v143, -v141, v142, 1.0
	v_fmac_f32_e32 v142, v143, v142
	v_div_scale_f32 v143, vcc, 1.0, v140, 1.0
	v_mul_f32_e32 v144, v143, v142
	v_fma_f32 v145, -v141, v144, v143
	v_fmac_f32_e32 v144, v145, v142
	v_fma_f32 v141, -v141, v144, v143
	v_div_fmas_f32 v141, v141, v142, v144
	v_div_fixup_f32 v140, v141, v140, 1.0
	v_mul_f32_e32 v141, v108, v108
	v_fmac_f32_e32 v141, v124, v124
	v_fmac_f32_e32 v141, v92, v92
	v_fmac_f32_e32 v141, v76, v76
	v_fmac_f32_e32 v141, v60, v60
	v_fmac_f32_e32 v141, v44, v44
	v_mbcnt_lo_u32_b32 v142, -1, 0
	v_mbcnt_hi_u32_b32 v142, -1, v142
	v_fmac_f32_e32 v141, v28, v28
	v_lshlrev_b32_e32 v142, 2, v142
	v_fmac_f32_e32 v141, v12, v12
	v_xor_b32_e32 v142, 4, v142
	ds_bpermute_b32 v142, v142, v141
	s_waitcnt lgkmcnt(0)
	v_add_f32_e32 v141, v141, v142
	v_mbcnt_lo_u32_b32 v142, -1, 0
	v_mbcnt_hi_u32_b32 v142, -1, v142
	s_nop 0
	v_lshlrev_b32_e32 v142, 2, v142
	v_xor_b32_e32 v142, 8, v142
	ds_bpermute_b32 v142, v142, v141
	s_waitcnt lgkmcnt(0)
	v_add_f32_e32 v141, v141, v142
	v_mbcnt_lo_u32_b32 v142, -1, 0
	v_mbcnt_hi_u32_b32 v142, -1, v142
	s_nop 0
	v_lshlrev_b32_e32 v142, 2, v142
	v_xor_b32_e32 v142, 16, v142
	ds_bpermute_b32 v142, v142, v141
	s_waitcnt lgkmcnt(0)
	v_add_f32_e32 v141, v141, v142
	v_mbcnt_lo_u32_b32 v142, -1, 0
	v_mbcnt_hi_u32_b32 v142, -1, v142
	s_nop 0
	v_lshlrev_b32_e32 v142, 2, v142
	v_xor_b32_e32 v142, 32, v142
	ds_bpermute_b32 v142, v142, v141
	s_waitcnt lgkmcnt(0)
	v_add_f32_e32 v141, v141, v142
	v_mbcnt_lo_u32_b32 v142, -1, 0
	v_mbcnt_hi_u32_b32 v142, -1, v142
	s_nop 0
	v_lshlrev_b32_e32 v142, 2, v142
	v_xor_b32_e32 v142, 64, v142
	ds_bpermute_b32 v142, v142, v141
	s_waitcnt lgkmcnt(0)
; DI void ret_unit(LAS unsigned char* lds, bf16_t* MX, const bf16_t* VT, bf16_t* ST, int b, int hh, int qt, float lgf, float nlgb, int wave, const int mode) {
;     ...
;     for (int i = 0; i < 16; ++i) {
;         float ss = 0.f;
; #pragma unroll
;         for (int db = 0; db < 8; ++db) ss += z[db][i] * z[db][i];
;         ss += shx(ss, 1); ss += shx(ss, 2); ss += shx(ss, 4); ss += shx(ss, 8); ss += shx(ss, 16);
;         nrm[i] = 1.0f / sqrtf(ss * (1.0f / 256.0f) + EPS);
	v_add_f32_e32 v141, v141, v142
	v_fmamk_f32 v141, v141, 0x3b800000, v237
	v_cmp_gt_f32_e32 vcc, s11, v141
	v_mul_f32_e32 v142, 0x4f800000, v141
	s_nop 0
	v_cndmask_b32_e32 v141, v141, v142, vcc
	v_sqrt_f32_e32 v142, v141
	s_nop 0
	v_add_u32_e32 v143, -1, v142
	v_fma_f32 v144, -v143, v142, v141
	v_cmp_ge_f32_e64 s[4:5], 0, v144
	v_add_u32_e32 v144, 1, v142
	s_nop 0
	v_cndmask_b32_e64 v143, v142, v143, s[4:5]
	v_fma_f32 v142, -v144, v142, v141
	v_cmp_lt_f32_e64 s[4:5], 0, v142
	s_nop 1
	v_cndmask_b32_e64 v142, v143, v144, s[4:5]
	v_mul_f32_e32 v143, 0x37800000, v142
	v_cndmask_b32_e32 v142, v142, v143, vcc
	v_cmp_class_f32_e32 vcc, v141, v238
	s_nop 1
	v_cndmask_b32_e32 v141, v142, v141, vcc
	v_div_scale_f32 v142, s[4:5], v141, v141, 1.0
	v_rcp_f32_e32 v143, v142
	s_nop 0
	v_fma_f32 v144, -v142, v143, 1.0
	v_fmac_f32_e32 v143, v144, v143
	v_div_scale_f32 v144, vcc, 1.0, v141, 1.0
	v_mul_f32_e32 v145, v144, v143
	v_fma_f32 v146, -v142, v145, v144
	v_fmac_f32_e32 v145, v146, v143
	v_fma_f32 v142, -v142, v145, v144
	v_div_fmas_f32 v142, v142, v143, v145
	v_div_fixup_f32 v141, v142, v141, 1.0
	v_mul_f32_e32 v142, v109, v109
	v_fmac_f32_e32 v142, v125, v125
	v_fmac_f32_e32 v142, v93, v93
	v_fmac_f32_e32 v142, v77, v77
	v_fmac_f32_e32 v142, v61, v61
	v_fmac_f32_e32 v142, v45, v45
	v_mbcnt_lo_u32_b32 v143, -1, 0
	v_mbcnt_hi_u32_b32 v143, -1, v143
	v_fmac_f32_e32 v142, v29, v29
	v_lshlrev_b32_e32 v143, 2, v143
	v_fmac_f32_e32 v142, v13, v13
	v_xor_b32_e32 v143, 4, v143
	ds_bpermute_b32 v143, v143, v142
	s_waitcnt lgkmcnt(0)
	v_add_f32_e32 v142, v142, v143
	v_mbcnt_lo_u32_b32 v143, -1, 0
	v_mbcnt_hi_u32_b32 v143, -1, v143
	s_nop 0
	v_lshlrev_b32_e32 v143, 2, v143
	v_xor_b32_e32 v143, 8, v143
	ds_bpermute_b32 v143, v143, v142
	s_waitcnt lgkmcnt(0)
	v_add_f32_e32 v142, v142, v143
	v_mbcnt_lo_u32_b32 v143, -1, 0
	v_mbcnt_hi_u32_b32 v143, -1, v143
	s_nop 0
	v_lshlrev_b32_e32 v143, 2, v143
	v_xor_b32_e32 v143, 16, v143
	ds_bpermute_b32 v143, v143, v142
	s_waitcnt lgkmcnt(0)
	v_add_f32_e32 v142, v142, v143
	v_mbcnt_lo_u32_b32 v143, -1, 0
	v_mbcnt_hi_u32_b32 v143, -1, v143
	s_nop 0
	v_lshlrev_b32_e32 v143, 2, v143
	v_xor_b32_e32 v143, 32, v143
	ds_bpermute_b32 v143, v143, v142
	s_waitcnt lgkmcnt(0)
	v_add_f32_e32 v142, v142, v143
	v_mbcnt_lo_u32_b32 v143, -1, 0
	v_mbcnt_hi_u32_b32 v143, -1, v143
	s_nop 0
	v_lshlrev_b32_e32 v143, 2, v143
	v_xor_b32_e32 v143, 64, v143
	ds_bpermute_b32 v143, v143, v142
	s_waitcnt lgkmcnt(0)
	v_add_f32_e32 v142, v142, v143
	v_fmamk_f32 v142, v142, 0x3b800000, v237
	v_cmp_gt_f32_e32 vcc, s11, v142
	v_mul_f32_e32 v143, 0x4f800000, v142
	s_nop 0
	v_cndmask_b32_e32 v142, v142, v143, vcc
	v_sqrt_f32_e32 v143, v142
	s_nop 0
	v_add_u32_e32 v144, -1, v143
	v_fma_f32 v145, -v144, v143, v142
	v_cmp_ge_f32_e64 s[4:5], 0, v145
	v_add_u32_e32 v145, 1, v143
	s_nop 0
	v_cndmask_b32_e64 v144, v143, v144, s[4:5]
	v_fma_f32 v143, -v145, v143, v142
	v_cmp_lt_f32_e64 s[4:5], 0, v143
	s_nop 1
	v_cndmask_b32_e64 v143, v144, v145, s[4:5]
	v_mul_f32_e32 v144, 0x37800000, v143
	v_cndmask_b32_e32 v143, v143, v144, vcc
	v_cmp_class_f32_e32 vcc, v142, v238
	s_nop 1
	v_cndmask_b32_e32 v142, v143, v142, vcc
	v_div_scale_f32 v143, s[4:5], v142, v142, 1.0
	v_rcp_f32_e32 v144, v143
	s_nop 0
	v_fma_f32 v145, -v143, v144, 1.0
	v_fmac_f32_e32 v144, v145, v144
	v_div_scale_f32 v145, vcc, 1.0, v142, 1.0
	v_mul_f32_e32 v146, v145, v144
	v_fma_f32 v147, -v143, v146, v145
	v_fmac_f32_e32 v146, v147, v144
	v_fma_f32 v143, -v143, v146, v145
	v_div_fmas_f32 v143, v143, v144, v146
	v_div_fixup_f32 v142, v143, v142, 1.0
	v_mul_f32_e32 v143, v110, v110
	v_fmac_f32_e32 v143, v126, v126
	v_fmac_f32_e32 v143, v94, v94
	v_fmac_f32_e32 v143, v78, v78
	v_fmac_f32_e32 v143, v62, v62
	v_fmac_f32_e32 v143, v46, v46
	v_mbcnt_lo_u32_b32 v144, -1, 0
	v_mbcnt_hi_u32_b32 v144, -1, v144
	v_fmac_f32_e32 v143, v30, v30
	v_lshlrev_b32_e32 v144, 2, v144
	v_fmac_f32_e32 v143, v14, v14
	v_xor_b32_e32 v144, 4, v144
	ds_bpermute_b32 v144, v144, v143
	s_waitcnt lgkmcnt(0)
	v_add_f32_e32 v143, v143, v144
	v_mbcnt_lo_u32_b32 v144, -1, 0
	v_mbcnt_hi_u32_b32 v144, -1, v144
	s_nop 0
	v_lshlrev_b32_e32 v144, 2, v144
	v_xor_b32_e32 v144, 8, v144
	ds_bpermute_b32 v144, v144, v143
	s_waitcnt lgkmcnt(0)
	v_add_f32_e32 v143, v143, v144
	v_mbcnt_lo_u32_b32 v144, -1, 0
	v_mbcnt_hi_u32_b32 v144, -1, v144
	s_nop 0
	v_lshlrev_b32_e32 v144, 2, v144
	v_xor_b32_e32 v144, 16, v144
	ds_bpermute_b32 v144, v144, v143
	s_waitcnt lgkmcnt(0)
	v_add_f32_e32 v143, v143, v144
	v_mbcnt_lo_u32_b32 v144, -1, 0
	v_mbcnt_hi_u32_b32 v144, -1, v144
	s_nop 0
	v_lshlrev_b32_e32 v144, 2, v144
	v_xor_b32_e32 v144, 32, v144
	ds_bpermute_b32 v144, v144, v143
	s_waitcnt lgkmcnt(0)
	v_add_f32_e32 v143, v143, v144
	v_mbcnt_lo_u32_b32 v144, -1, 0
	v_mbcnt_hi_u32_b32 v144, -1, v144
	s_nop 0
	v_lshlrev_b32_e32 v144, 2, v144
	v_xor_b32_e32 v144, 64, v144
	ds_bpermute_b32 v144, v144, v143
	s_waitcnt lgkmcnt(0)
; #define LAS __attribute__((address_space(3)))
; DI unsigned f2bf(float f) { unsigned u = __builtin_bit_cast(unsigned, f); return (u + 0x7fffu + ((u >> 16) & 1u)) >> 16; }
; DI void ret_unit(LAS unsigned char* lds, bf16_t* MX, const bf16_t* VT, bf16_t* ST, int b, int hh, int qt, float lgf, float nlgb, int wave, const int mode) {
;     ...
;     for (int i = 0; i < 16; ++i) {
;         float ss = 0.f;
; #pragma unroll
;         for (int db = 0; db < 8; ++db) ss += z[db][i] * z[db][i];
;         ss += shx(ss, 1); ss += shx(ss, 2); ss += shx(ss, 4); ss += shx(ss, 8); ss += shx(ss, 16);
;         nrm[i] = 1.0f / sqrtf(ss * (1.0f / 256.0f) + EPS);
;     }
;     __syncthreads();
;     LAS unsigned char* T = lds + wave * 8704;
; #pragma unroll
;     for (int hf = 0; hf < 2; ++hf) {
; #pragma unroll
;         for (int i = 0; i < 16; ++i) { const int q = (i & 3) + 8 * (i >> 2) + 4 * he;
; #pragma unroll
;             for (int d4 = 0; d4 < 4; ++d4) *(LAS bf16_t*)(T + q * 272 + (d4 * 32 + re) * 2) = (bf16_t)f2bf(z[hf * 4 + d4][i] * nrm[i]); }
	v_add_f32_e32 v143, v143, v144
	v_fmamk_f32 v143, v143, 0x3b800000, v237
	v_cmp_gt_f32_e32 vcc, s11, v143
	v_mul_f32_e32 v144, 0x4f800000, v143
	s_nop 0
	v_cndmask_b32_e32 v143, v143, v144, vcc
	v_sqrt_f32_e32 v144, v143
	s_nop 0
	v_add_u32_e32 v145, -1, v144
	v_fma_f32 v146, -v145, v144, v143
	v_cmp_ge_f32_e64 s[4:5], 0, v146
	v_add_u32_e32 v146, 1, v144
	s_nop 0
	v_cndmask_b32_e64 v145, v144, v145, s[4:5]
	v_fma_f32 v144, -v146, v144, v143
	v_cmp_lt_f32_e64 s[4:5], 0, v144
	s_nop 1
	v_cndmask_b32_e64 v144, v145, v146, s[4:5]
	v_mul_f32_e32 v145, 0x37800000, v144
	v_cndmask_b32_e32 v144, v144, v145, vcc
	v_cmp_class_f32_e32 vcc, v143, v238
	s_nop 1
	v_cndmask_b32_e32 v143, v144, v143, vcc
	v_div_scale_f32 v144, s[4:5], v143, v143, 1.0
	v_rcp_f32_e32 v145, v144
	s_nop 0
	v_fma_f32 v146, -v144, v145, 1.0
	v_fmac_f32_e32 v145, v146, v145
	v_div_scale_f32 v146, vcc, 1.0, v143, 1.0
	v_mul_f32_e32 v147, v146, v145
	v_fma_f32 v148, -v144, v147, v146
	v_fmac_f32_e32 v147, v148, v145
	v_fma_f32 v144, -v144, v147, v146
	v_div_fmas_f32 v144, v144, v145, v147
	v_div_fixup_f32 v143, v144, v143, 1.0
	v_mul_f32_e32 v144, v111, v111
	v_fmac_f32_e32 v144, v127, v127
	v_fmac_f32_e32 v144, v95, v95
	v_fmac_f32_e32 v144, v79, v79
	v_fmac_f32_e32 v144, v63, v63
	v_fmac_f32_e32 v144, v47, v47
	v_mbcnt_lo_u32_b32 v145, -1, 0
	v_mbcnt_hi_u32_b32 v145, -1, v145
	v_fmac_f32_e32 v144, v31, v31
	v_lshlrev_b32_e32 v145, 2, v145
	v_fmac_f32_e32 v144, v15, v15
	v_xor_b32_e32 v145, 4, v145
	ds_bpermute_b32 v145, v145, v144
	s_waitcnt lgkmcnt(0)
	v_add_f32_e32 v144, v144, v145
	v_mbcnt_lo_u32_b32 v145, -1, 0
	v_mbcnt_hi_u32_b32 v145, -1, v145
	s_nop 0
	v_lshlrev_b32_e32 v145, 2, v145
	v_xor_b32_e32 v145, 8, v145
	ds_bpermute_b32 v145, v145, v144
	s_waitcnt lgkmcnt(0)
	v_add_f32_e32 v144, v144, v145
	v_mbcnt_lo_u32_b32 v145, -1, 0
	v_mbcnt_hi_u32_b32 v145, -1, v145
	s_nop 0
	v_lshlrev_b32_e32 v145, 2, v145
	v_xor_b32_e32 v145, 16, v145
	ds_bpermute_b32 v145, v145, v144
	s_waitcnt lgkmcnt(0)
	v_add_f32_e32 v144, v144, v145
	v_mbcnt_lo_u32_b32 v145, -1, 0
	v_mbcnt_hi_u32_b32 v145, -1, v145
	s_nop 0
	v_lshlrev_b32_e32 v145, 2, v145
	v_xor_b32_e32 v145, 32, v145
	ds_bpermute_b32 v145, v145, v144
	s_waitcnt lgkmcnt(0)
	v_add_f32_e32 v144, v144, v145
	v_mbcnt_lo_u32_b32 v145, -1, 0
	v_mbcnt_hi_u32_b32 v145, -1, v145
	s_waitcnt vmcnt(0)
	v_lshlrev_b32_e32 v145, 2, v145
	v_xor_b32_e32 v145, 64, v145
	ds_bpermute_b32 v145, v145, v144
	s_barrier
	s_waitcnt lgkmcnt(0)
	v_add_f32_e32 v144, v144, v145
	v_fmamk_f32 v144, v144, 0x3b800000, v237
	v_cmp_gt_f32_e32 vcc, s11, v144
	v_mul_f32_e32 v145, 0x4f800000, v144
	s_movk_i32 s11, 0x110
	v_cndmask_b32_e32 v144, v144, v145, vcc
	v_sqrt_f32_e32 v145, v144
	s_nop 0
	v_add_u32_e32 v146, -1, v145
	v_fma_f32 v147, -v146, v145, v144
	v_cmp_ge_f32_e64 s[4:5], 0, v147
	v_add_u32_e32 v147, 1, v145
	s_nop 0
	v_cndmask_b32_e64 v146, v145, v146, s[4:5]
	v_fma_f32 v145, -v147, v145, v144
	v_cmp_lt_f32_e64 s[4:5], 0, v145
	s_nop 1
	v_cndmask_b32_e64 v145, v146, v147, s[4:5]
	v_mul_f32_e32 v146, 0x37800000, v145
	v_cndmask_b32_e32 v145, v145, v146, vcc
	v_cmp_class_f32_e32 vcc, v144, v238
	s_nop 1
	v_cndmask_b32_e32 v144, v145, v144, vcc
	v_div_scale_f32 v145, s[4:5], v144, v144, 1.0
	v_rcp_f32_e32 v146, v145
	s_add_u32 s5, s62, s47
	s_addc_u32 s4, 0, s52
	s_addk_i32 s10, 0x4000
	v_fma_f32 v147, -v145, v146, 1.0
	v_fmac_f32_e32 v146, v147, v146
	v_div_scale_f32 v147, vcc, 1.0, v144, 1.0
	v_mul_f32_e32 v148, v147, v146
	v_fma_f32 v149, -v145, v148, v147
	v_fmac_f32_e32 v148, v149, v146
	v_fma_f32 v145, -v145, v148, v147
	v_div_fmas_f32 v145, v145, v146, v148
	v_div_fixup_f32 v144, v145, v144, 1.0
	v_lshrrev_b32_e32 v145, 3, v137
	v_and_b32_e32 v145, 4, v145
	v_lshlrev_b32_e32 v146, 1, v137
	v_and_b32_e32 v146, 62, v146
	v_mul_u32_u24_e32 v145, 0x110, v145
	v_add3_u32 v145, s46, v146, v145
	v_bfe_u32 v146, v112, 16, 1
	v_add3_u32 v112, v112, v146, s12
	ds_write_b16_d16_hi v145, v112
	v_bfe_u32 v112, v96, 16, 1
	v_add3_u32 v96, v96, v112, s12
	ds_write_b16_d16_hi v145, v96 offset:64
	v_bfe_u32 v96, v80, 16, 1
	v_add3_u32 v80, v80, v96, s12
	ds_write_b16_d16_hi v145, v80 offset:128
	v_bfe_u32 v80, v64, 16, 1
	v_add3_u32 v64, v64, v80, s12
	ds_write_b16_d16_hi v145, v64 offset:192
	v_mul_f32_e32 v64, v113, v129
	v_bfe_u32 v80, v64, 16, 1
	v_add3_u32 v64, v64, v80, s12
	ds_write_b16_d16_hi v145, v64 offset:272
	v_mul_f32_e32 v64, v97, v129
	v_bfe_u32 v80, v64, 16, 1
	v_add3_u32 v64, v64, v80, s12
	ds_write_b16_d16_hi v145, v64 offset:336
	v_mul_f32_e32 v64, v81, v129
	v_bfe_u32 v80, v64, 16, 1
	v_add3_u32 v64, v64, v80, s12
	ds_write_b16_d16_hi v145, v64 offset:400
	v_mul_f32_e32 v64, v65, v129
	v_bfe_u32 v65, v64, 16, 1
	v_add3_u32 v64, v64, v65, s12
	ds_write_b16_d16_hi v145, v64 offset:464
	v_mul_f32_e32 v64, v114, v130
	v_bfe_u32 v65, v64, 16, 1
	v_add3_u32 v64, v64, v65, s12
	ds_write_b16_d16_hi v145, v64 offset:544
	v_mul_f32_e32 v64, v98, v130
	v_bfe_u32 v65, v64, 16, 1
	v_add3_u32 v64, v64, v65, s12
	ds_write_b16_d16_hi v145, v64 offset:608
	v_mul_f32_e32 v64, v82, v130
	v_bfe_u32 v65, v64, 16, 1
	v_add3_u32 v64, v64, v65, s12
	ds_write_b16_d16_hi v145, v64 offset:672
	v_mul_f32_e32 v64, v66, v130
	v_bfe_u32 v65, v64, 16, 1
	v_add3_u32 v64, v64, v65, s12
	ds_write_b16_d16_hi v145, v64 offset:736
	v_mul_f32_e32 v64, v115, v131
	v_bfe_u32 v65, v64, 16, 1
	v_add3_u32 v64, v64, v65, s12
	ds_write_b16_d16_hi v145, v64 offset:816
	v_mul_f32_e32 v64, v99, v131
	v_bfe_u32 v65, v64, 16, 1
	v_add3_u32 v64, v64, v65, s12
	ds_write_b16_d16_hi v145, v64 offset:880
	v_mul_f32_e32 v64, v83, v131
	v_bfe_u32 v65, v64, 16, 1
	v_add3_u32 v64, v64, v65, s12
; #define LAS __attribute__((address_space(3)))
; DI unsigned f2bf(float f) { unsigned u = __builtin_bit_cast(unsigned, f); return (u + 0x7fffu + ((u >> 16) & 1u)) >> 16; }
; DI void ret_unit(LAS unsigned char* lds, bf16_t* MX, const bf16_t* VT, bf16_t* ST, int b, int hh, int qt, float lgf, float nlgb, int wave, const int mode) {
;     ...
;     for (int hf = 0; hf < 2; ++hf) {
; #pragma unroll
;         for (int i = 0; i < 16; ++i) { const int q = (i & 3) + 8 * (i >> 2) + 4 * he;
; #pragma unroll
;             for (int d4 = 0; d4 < 4; ++d4) *(LAS bf16_t*)(T + q * 272 + (d4 * 32 + re) * 2) = (bf16_t)f2bf(z[hf * 4 + d4][i] * nrm[i]); }
;         asm volatile("s_waitcnt lgkmcnt(0)" ::: "memory");
; #pragma unroll
;         for (int k = 0; k < 8; ++k) { const int id = le + 64 * k, q = id >> 4, ch = id & 15;
;             const u32x4 ov = *(const LAS u32x4*)(T + q * 272 + ch * 16);
;             bf16_t* gp = MX + (tok0 + q0w + q) * MXW + C_RG + hh * 256 + hf * 128 + ch * 8;
	ds_write_b16_d16_hi v145, v64 offset:944
	v_mul_f32_e32 v64, v67, v131
	v_bfe_u32 v65, v64, 16, 1
	v_add3_u32 v64, v64, v65, s12
	ds_write_b16_d16_hi v145, v64 offset:1008
	v_mul_f32_e32 v64, v116, v132
	v_bfe_u32 v65, v64, 16, 1
	v_add3_u32 v64, v64, v65, s12
	ds_write_b16_d16_hi v145, v64 offset:2176
	v_mul_f32_e32 v64, v100, v132
	v_bfe_u32 v65, v64, 16, 1
	v_add3_u32 v64, v64, v65, s12
	ds_write_b16_d16_hi v145, v64 offset:2240
	v_mul_f32_e32 v64, v84, v132
	v_bfe_u32 v65, v64, 16, 1
	v_add3_u32 v64, v64, v65, s12
	ds_write_b16_d16_hi v145, v64 offset:2304
	v_mul_f32_e32 v64, v68, v132
	v_bfe_u32 v65, v64, 16, 1
	v_add3_u32 v64, v64, v65, s12
	ds_write_b16_d16_hi v145, v64 offset:2368
	v_mul_f32_e32 v64, v117, v133
	v_bfe_u32 v65, v64, 16, 1
	v_add3_u32 v64, v64, v65, s12
	ds_write_b16_d16_hi v145, v64 offset:2448
	v_mul_f32_e32 v64, v101, v133
	v_bfe_u32 v65, v64, 16, 1
	v_add3_u32 v64, v64, v65, s12
	ds_write_b16_d16_hi v145, v64 offset:2512
	v_mul_f32_e32 v64, v85, v133
	v_bfe_u32 v65, v64, 16, 1
	v_add3_u32 v64, v64, v65, s12
	ds_write_b16_d16_hi v145, v64 offset:2576
	v_mul_f32_e32 v64, v69, v133
	v_bfe_u32 v65, v64, 16, 1
	v_add3_u32 v64, v64, v65, s12
	ds_write_b16_d16_hi v145, v64 offset:2640
	v_mul_f32_e32 v64, v118, v134
	v_bfe_u32 v65, v64, 16, 1
	v_add3_u32 v64, v64, v65, s12
	ds_write_b16_d16_hi v145, v64 offset:2720
	v_mul_f32_e32 v64, v102, v134
	v_bfe_u32 v65, v64, 16, 1
	v_add3_u32 v64, v64, v65, s12
	ds_write_b16_d16_hi v145, v64 offset:2784
	v_mul_f32_e32 v64, v86, v134
	v_bfe_u32 v65, v64, 16, 1
	v_add3_u32 v64, v64, v65, s12
	ds_write_b16_d16_hi v145, v64 offset:2848
	v_mul_f32_e32 v64, v70, v134
	v_bfe_u32 v65, v64, 16, 1
	v_add3_u32 v64, v64, v65, s12
	ds_write_b16_d16_hi v145, v64 offset:2912
	v_mul_f32_e32 v64, v119, v135
	v_bfe_u32 v65, v64, 16, 1
	v_add3_u32 v64, v64, v65, s12
	ds_write_b16_d16_hi v145, v64 offset:2992
	v_mul_f32_e32 v64, v103, v135
	v_bfe_u32 v65, v64, 16, 1
	v_add3_u32 v64, v64, v65, s12
	ds_write_b16_d16_hi v145, v64 offset:3056
	v_mul_f32_e32 v64, v87, v135
	v_bfe_u32 v65, v64, 16, 1
	v_add3_u32 v64, v64, v65, s12
	ds_write_b16_d16_hi v145, v64 offset:3120
	v_mul_f32_e32 v64, v71, v135
	v_bfe_u32 v65, v64, 16, 1
	v_add3_u32 v64, v64, v65, s12
	ds_write_b16_d16_hi v145, v64 offset:3184
	v_mul_f32_e32 v64, v120, v136
	v_bfe_u32 v65, v64, 16, 1
	v_add3_u32 v64, v64, v65, s12
	ds_write_b16_d16_hi v145, v64 offset:4352
	v_mul_f32_e32 v64, v104, v136
	v_bfe_u32 v65, v64, 16, 1
	v_add3_u32 v64, v64, v65, s12
	ds_write_b16_d16_hi v145, v64 offset:4416
	v_mul_f32_e32 v64, v88, v136
	v_bfe_u32 v65, v64, 16, 1
	v_add3_u32 v64, v64, v65, s12
	ds_write_b16_d16_hi v145, v64 offset:4480
	v_mul_f32_e32 v64, v72, v136
	v_bfe_u32 v65, v64, 16, 1
	v_add3_u32 v64, v64, v65, s12
	ds_write_b16_d16_hi v145, v64 offset:4544
	v_mul_f32_e32 v64, v121, v138
	v_bfe_u32 v65, v64, 16, 1
	v_add3_u32 v64, v64, v65, s12
	ds_write_b16_d16_hi v145, v64 offset:4624
	v_mul_f32_e32 v64, v105, v138
	v_bfe_u32 v65, v64, 16, 1
	v_add3_u32 v64, v64, v65, s12
	ds_write_b16_d16_hi v145, v64 offset:4688
	v_mul_f32_e32 v64, v89, v138
	v_bfe_u32 v65, v64, 16, 1
	v_add3_u32 v64, v64, v65, s12
	ds_write_b16_d16_hi v145, v64 offset:4752
	v_mul_f32_e32 v64, v73, v138
	v_bfe_u32 v65, v64, 16, 1
	v_add3_u32 v64, v64, v65, s12
	ds_write_b16_d16_hi v145, v64 offset:4816
	v_mul_f32_e32 v64, v122, v139
	v_bfe_u32 v65, v64, 16, 1
	v_add3_u32 v64, v64, v65, s12
	ds_write_b16_d16_hi v145, v64 offset:4896
	v_mul_f32_e32 v64, v106, v139
	v_bfe_u32 v65, v64, 16, 1
	v_add3_u32 v64, v64, v65, s12
	ds_write_b16_d16_hi v145, v64 offset:4960
	v_mul_f32_e32 v64, v90, v139
	v_bfe_u32 v65, v64, 16, 1
	v_add3_u32 v64, v64, v65, s12
	ds_write_b16_d16_hi v145, v64 offset:5024
	v_mul_f32_e32 v64, v74, v139
	v_bfe_u32 v65, v64, 16, 1
	v_add3_u32 v64, v64, v65, s12
	ds_write_b16_d16_hi v145, v64 offset:5088
	v_mul_f32_e32 v64, v123, v140
	v_bfe_u32 v65, v64, 16, 1
	v_add3_u32 v64, v64, v65, s12
	ds_write_b16_d16_hi v145, v64 offset:5168
	v_mul_f32_e32 v64, v107, v140
	v_bfe_u32 v65, v64, 16, 1
	v_add3_u32 v64, v64, v65, s12
	ds_write_b16_d16_hi v145, v64 offset:5232
	v_mul_f32_e32 v64, v91, v140
	v_bfe_u32 v65, v64, 16, 1
	v_add3_u32 v64, v64, v65, s12
	ds_write_b16_d16_hi v145, v64 offset:5296
	v_mul_f32_e32 v64, v75, v140
	v_bfe_u32 v65, v64, 16, 1
	v_add3_u32 v64, v64, v65, s12
	ds_write_b16_d16_hi v145, v64 offset:5360
	v_mul_f32_e32 v64, v124, v141
	v_bfe_u32 v65, v64, 16, 1
	v_add3_u32 v64, v64, v65, s12
	ds_write_b16_d16_hi v145, v64 offset:6528
	v_mul_f32_e32 v64, v108, v141
	v_bfe_u32 v65, v64, 16, 1
	v_add3_u32 v64, v64, v65, s12
	ds_write_b16_d16_hi v145, v64 offset:6592
	v_mul_f32_e32 v64, v92, v141
	v_bfe_u32 v65, v64, 16, 1
	v_add3_u32 v64, v64, v65, s12
	ds_write_b16_d16_hi v145, v64 offset:6656
	v_mul_f32_e32 v64, v76, v141
	v_bfe_u32 v65, v64, 16, 1
	v_add3_u32 v64, v64, v65, s12
	ds_write_b16_d16_hi v145, v64 offset:6720
	v_mul_f32_e32 v64, v125, v142
	v_bfe_u32 v65, v64, 16, 1
	v_add3_u32 v64, v64, v65, s12
	ds_write_b16_d16_hi v145, v64 offset:6800
	v_mul_f32_e32 v64, v109, v142
	v_bfe_u32 v65, v64, 16, 1
	v_add3_u32 v64, v64, v65, s12
	ds_write_b16_d16_hi v145, v64 offset:6864
	v_mul_f32_e32 v64, v93, v142
	v_bfe_u32 v65, v64, 16, 1
	v_add3_u32 v64, v64, v65, s12
	ds_write_b16_d16_hi v145, v64 offset:6928
	v_mul_f32_e32 v64, v77, v142
	v_bfe_u32 v65, v64, 16, 1
	v_add3_u32 v64, v64, v65, s12
	ds_write_b16_d16_hi v145, v64 offset:6992
	v_mul_f32_e32 v64, v126, v143
	v_bfe_u32 v65, v64, 16, 1
	v_add3_u32 v64, v64, v65, s12
	ds_write_b16_d16_hi v145, v64 offset:7072
	v_mul_f32_e32 v64, v110, v143
	v_bfe_u32 v65, v64, 16, 1
	v_add3_u32 v64, v64, v65, s12
	ds_write_b16_d16_hi v145, v64 offset:7136
	v_mul_f32_e32 v64, v94, v143
	v_bfe_u32 v65, v64, 16, 1
	v_add3_u32 v64, v64, v65, s12
	ds_write_b16_d16_hi v145, v64 offset:7200
	v_mul_f32_e32 v64, v78, v143
	v_bfe_u32 v65, v64, 16, 1
	v_add3_u32 v64, v64, v65, s12
	ds_write_b16_d16_hi v145, v64 offset:7264
	v_mul_f32_e32 v64, v127, v144
	v_bfe_u32 v65, v64, 16, 1
	v_add3_u32 v64, v64, v65, s12
	ds_write_b16_d16_hi v145, v64 offset:7344
	v_mul_f32_e32 v64, v111, v144
	v_bfe_u32 v65, v64, 16, 1
	v_add3_u32 v64, v64, v65, s12
	ds_write_b16_d16_hi v145, v64 offset:7408
	v_mul_f32_e32 v64, v95, v144
	v_bfe_u32 v65, v64, 16, 1
	v_add3_u32 v64, v64, v65, s12
	v_bfe_u32 v148, v137, 4, 2
	ds_write_b16_d16_hi v145, v64 offset:7472
	v_mul_f32_e32 v64, v79, v144
	v_bfe_u32 v65, v64, 16, 1
	v_or_b32_e32 v70, s5, v148
	v_mov_b64_e32 v[68:69], s[8:9]
	v_lshlrev_b32_e32 v147, 4, v137
	v_add3_u32 v64, v64, v65, s12
	v_mad_u64_u32 v[72:73], s[14:15], v70, s50, v[68:69]
	v_and_b32_e32 v176, 0xf0, v147
	ds_write_b16_d16_hi v145, v64 offset:7536
	v_mad_i32_i24 v73, s4, v244, v73
	s_waitcnt lgkmcnt(0)
; __device__ __forceinline__ unsigned cvtpk(float lo, float hi) { f32x2_t v = {lo, hi}; bf16x2_t b = __builtin_convertvector(v, bf16x2_t); return __builtin_bit_cast(unsigned, b); }
; __device__ __forceinline__ float bf_lo(unsigned w) { return __uint_as_float(w << 16); }
; __device__ __forceinline__ float bf_hi(unsigned w) { return __uint_as_float(w & 0xffff0000u); }
; #define LAS __attribute__((address_space(3)))
; DI void ret_unit(LAS unsigned char* lds, bf16_t* MX, const bf16_t* VT, bf16_t* ST, int b, int hh, int qt, float lgf, float nlgb, int wave, const int mode) {
;     ...
;         for (int k = 0; k < 8; ++k) { const int id = le + 64 * k, q = id >> 4, ch = id & 15;
;             const u32x4 ov = *(const LAS u32x4*)(T + q * 272 + ch * 16);
;             bf16_t* gp = MX + (tok0 + q0w + q) * MXW + C_RG + hh * 256 + hf * 128 + ch * 8;
;             const u32x4 gv = *(const u32x4*)gp;
;             u32x4 w; w.x = cvtpk(bf_lo(ov.x) * bf_lo(gv.x), bf_hi(ov.x) * bf_hi(gv.x)); w.y = cvtpk(bf_lo(ov.y) * bf_lo(gv.y), bf_hi(ov.y) * bf_hi(gv.y));
;             w.z = cvtpk(bf_lo(ov.z) * bf_lo(gv.z), bf_hi(ov.z) * bf_hi(gv.z)); w.w = cvtpk(bf_lo(ov.w) * bf_lo(gv.w), bf_hi(ov.w) * bf_hi(gv.w));
;             *(u32x4*)gp = w; }
	v_lshl_add_u64 v[74:75], v[72:73], 0, v[176:177]
	v_mad_u64_u32 v[90:91], s[14:15], v70, s50, v[68:69]
	v_mad_i32_i24 v91, s4, v244, v91
	v_lshl_add_u64 v[90:91], v[90:91], 0, v[176:177]
	global_load_dwordx4 v[96:99], v[90:91], off offset:2048
	v_or_b32_e32 v92, 4, v70
	v_mad_u64_u32 v[90:91], s[14:15], v92, s50, v[68:69]
	v_mad_i32_i24 v91, s4, v244, v91
	v_lshl_add_u64 v[90:91], v[90:91], 0, v[176:177]
	global_load_dwordx4 v[100:103], v[90:91], off offset:2048
	v_or_b32_e32 v92, 8, v70
	v_mad_u64_u32 v[90:91], s[14:15], v92, s50, v[68:69]
	v_mad_i32_i24 v91, s4, v244, v91
	v_lshl_add_u64 v[90:91], v[90:91], 0, v[176:177]
	global_load_dwordx4 v[104:107], v[90:91], off offset:2048
	v_or_b32_e32 v92, 12, v70
	v_mad_u64_u32 v[90:91], s[14:15], v92, s50, v[68:69]
	v_mad_i32_i24 v91, s4, v244, v91
	v_lshl_add_u64 v[90:91], v[90:91], 0, v[176:177]
	global_load_dwordx4 v[108:111], v[90:91], off offset:2048
	v_or_b32_e32 v92, 16, v70
	v_mad_u64_u32 v[90:91], s[14:15], v92, s50, v[68:69]
	v_mad_i32_i24 v91, s4, v244, v91
	v_lshl_add_u64 v[90:91], v[90:91], 0, v[176:177]
	global_load_dwordx4 v[112:115], v[90:91], off offset:2048
	v_or_b32_e32 v92, 20, v70
	v_mad_u64_u32 v[90:91], s[14:15], v92, s50, v[68:69]
	v_mad_i32_i24 v91, s4, v244, v91
	v_lshl_add_u64 v[90:91], v[90:91], 0, v[176:177]
	global_load_dwordx4 v[116:119], v[90:91], off offset:2048
	v_or_b32_e32 v92, 24, v70
	v_mad_u64_u32 v[90:91], s[14:15], v92, s50, v[68:69]
	v_mad_i32_i24 v91, s4, v244, v91
	v_lshl_add_u64 v[90:91], v[90:91], 0, v[176:177]
	global_load_dwordx4 v[120:123], v[90:91], off offset:2048
	v_or_b32_e32 v92, 28, v70
	v_mad_u64_u32 v[90:91], s[14:15], v92, s50, v[68:69]
	v_mad_i32_i24 v91, s4, v244, v91
	v_lshl_add_u64 v[90:91], v[90:91], 0, v[176:177]
	global_load_dwordx4 v[124:127], v[90:91], off offset:2048
	v_add_u32_e32 v147, s46, v176
	v_mad_u32_u24 v137, v148, s11, v147
	ds_read_b128 v[64:67], v137
	v_or_b32_e32 v71, 4, v148
	v_mad_u32_u24 v88, v71, s11, v147
	v_or_b32_e32 v71, s5, v71
	s_waitcnt lgkmcnt(0)
	v_lshlrev_b32_e32 v72, 16, v64
	v_and_b32_e32 v73, 0xffff0000, v64
	s_waitcnt vmcnt(7)
	v_mov_b32_e32 v76, v96
	v_mov_b32_e32 v77, v97
	v_mov_b32_e32 v78, v98
	v_mov_b32_e32 v79, v99
	v_lshlrev_b32_e32 v80, 16, v76
	v_and_b32_e32 v81, 0xffff0000, v76
	v_pk_mul_f32 v[72:73], v[72:73], v[80:81]
	v_lshlrev_b32_e32 v76, 16, v77
	v_cvt_pk_bf16_f32 v64, v72, v73
	v_lshlrev_b32_e32 v72, 16, v65
	v_and_b32_e32 v73, 0xffff0000, v65
	v_and_b32_e32 v77, 0xffff0000, v77
	v_pk_mul_f32 v[72:73], v[72:73], v[76:77]
	v_lshlrev_b32_e32 v76, 16, v78
	v_cvt_pk_bf16_f32 v65, v72, v73
	v_lshlrev_b32_e32 v72, 16, v66
	v_and_b32_e32 v73, 0xffff0000, v66
	v_and_b32_e32 v77, 0xffff0000, v78
	v_pk_mul_f32 v[72:73], v[72:73], v[76:77]
	v_lshlrev_b32_e32 v76, 16, v79
	v_cvt_pk_bf16_f32 v66, v72, v73
	v_lshlrev_b32_e32 v72, 16, v67
	v_and_b32_e32 v73, 0xffff0000, v67
	v_and_b32_e32 v77, 0xffff0000, v79
	v_pk_mul_f32 v[72:73], v[72:73], v[76:77]
	s_nop 0
	v_cvt_pk_bf16_f32 v67, v72, v73
	v_mad_u64_u32 v[72:73], s[14:15], v71, s50, v[68:69]
	v_mad_i32_i24 v73, s4, v244, v73
	v_lshl_add_u64 v[76:77], v[72:73], 0, v[176:177]
	v_or_b32_e32 v71, 8, v70
	flat_store_dwordx4 v[74:75], v[64:67] offset:2048
	ds_read_b128 v[64:67], v88
	s_waitcnt lgkmcnt(0)
	v_lshlrev_b32_e32 v72, 16, v64
	v_and_b32_e32 v73, 0xffff0000, v64
	s_waitcnt vmcnt(7)
	v_mov_b32_e32 v78, v100
	v_mov_b32_e32 v79, v101
	v_mov_b32_e32 v80, v102
	v_mov_b32_e32 v81, v103
	v_lshlrev_b32_e32 v82, 16, v78
	v_and_b32_e32 v83, 0xffff0000, v78
	v_pk_mul_f32 v[72:73], v[72:73], v[82:83]
	v_lshlrev_b32_e32 v78, 16, v79
	v_cvt_pk_bf16_f32 v64, v72, v73
	v_lshlrev_b32_e32 v72, 16, v65
	v_and_b32_e32 v73, 0xffff0000, v65
	v_and_b32_e32 v79, 0xffff0000, v79
	v_pk_mul_f32 v[72:73], v[72:73], v[78:79]
	v_lshlrev_b32_e32 v78, 16, v80
	v_cvt_pk_bf16_f32 v65, v72, v73
	v_lshlrev_b32_e32 v72, 16, v66
	v_and_b32_e32 v73, 0xffff0000, v66
	v_and_b32_e32 v79, 0xffff0000, v80
	v_pk_mul_f32 v[72:73], v[72:73], v[78:79]
	v_lshlrev_b32_e32 v78, 16, v81
	v_cvt_pk_bf16_f32 v66, v72, v73
	v_lshlrev_b32_e32 v72, 16, v67
	v_and_b32_e32 v73, 0xffff0000, v67
	v_and_b32_e32 v79, 0xffff0000, v81
	v_pk_mul_f32 v[72:73], v[72:73], v[78:79]
	s_nop 0
	v_cvt_pk_bf16_f32 v67, v72, v73
	v_mad_u64_u32 v[72:73], s[14:15], v71, s50, v[68:69]
	v_mad_i32_i24 v73, s4, v244, v73
	v_lshl_add_u64 v[78:79], v[72:73], 0, v[176:177]
	v_or_b32_e32 v71, 12, v70
	flat_store_dwordx4 v[76:77], v[64:67] offset:2048
	ds_read_b128 v[64:67], v88 offset:1088
	s_waitcnt lgkmcnt(0)
	v_lshlrev_b32_e32 v72, 16, v64
	v_and_b32_e32 v73, 0xffff0000, v64
	s_waitcnt vmcnt(7)
	v_mov_b32_e32 v80, v104
	v_mov_b32_e32 v81, v105
	v_mov_b32_e32 v82, v106
	v_mov_b32_e32 v83, v107
	v_lshlrev_b32_e32 v84, 16, v80
	v_and_b32_e32 v85, 0xffff0000, v80
	v_pk_mul_f32 v[72:73], v[72:73], v[84:85]
	v_lshlrev_b32_e32 v80, 16, v81
	v_cvt_pk_bf16_f32 v64, v72, v73
	v_lshlrev_b32_e32 v72, 16, v65
	v_and_b32_e32 v73, 0xffff0000, v65
	v_and_b32_e32 v81, 0xffff0000, v81
	v_pk_mul_f32 v[72:73], v[72:73], v[80:81]
	v_lshlrev_b32_e32 v80, 16, v82
	v_cvt_pk_bf16_f32 v65, v72, v73
	v_lshlrev_b32_e32 v72, 16, v66
	v_and_b32_e32 v73, 0xffff0000, v66
	v_and_b32_e32 v81, 0xffff0000, v82
	v_pk_mul_f32 v[72:73], v[72:73], v[80:81]
	v_lshlrev_b32_e32 v80, 16, v83
	v_cvt_pk_bf16_f32 v66, v72, v73
	v_lshlrev_b32_e32 v72, 16, v67
	v_and_b32_e32 v73, 0xffff0000, v67
	v_and_b32_e32 v81, 0xffff0000, v83
	v_pk_mul_f32 v[72:73], v[72:73], v[80:81]
	s_nop 0
	v_cvt_pk_bf16_f32 v67, v72, v73
	v_mad_u64_u32 v[72:73], s[14:15], v71, s50, v[68:69]
	v_mad_i32_i24 v73, s4, v244, v73
	v_lshl_add_u64 v[82:83], v[72:73], 0, v[176:177]
	v_or_b32_e32 v71, 16, v70
	flat_store_dwordx4 v[78:79], v[64:67] offset:2048
	ds_read_b128 v[64:67], v88 offset:2176
	s_waitcnt lgkmcnt(0)
; __device__ __forceinline__ unsigned cvtpk(float lo, float hi) { f32x2_t v = {lo, hi}; bf16x2_t b = __builtin_convertvector(v, bf16x2_t); return __builtin_bit_cast(unsigned, b); }
; __device__ __forceinline__ float bf_lo(unsigned w) { return __uint_as_float(w << 16); }
; __device__ __forceinline__ float bf_hi(unsigned w) { return __uint_as_float(w & 0xffff0000u); }
; #define LAS __attribute__((address_space(3)))
; DI void ret_unit(LAS unsigned char* lds, bf16_t* MX, const bf16_t* VT, bf16_t* ST, int b, int hh, int qt, float lgf, float nlgb, int wave, const int mode) {
;     ...
;         for (int k = 0; k < 8; ++k) { const int id = le + 64 * k, q = id >> 4, ch = id & 15;
;             const u32x4 ov = *(const LAS u32x4*)(T + q * 272 + ch * 16);
;             bf16_t* gp = MX + (tok0 + q0w + q) * MXW + C_RG + hh * 256 + hf * 128 + ch * 8;
;             const u32x4 gv = *(const u32x4*)gp;
;             u32x4 w; w.x = cvtpk(bf_lo(ov.x) * bf_lo(gv.x), bf_hi(ov.x) * bf_hi(gv.x)); w.y = cvtpk(bf_lo(ov.y) * bf_lo(gv.y), bf_hi(ov.y) * bf_hi(gv.y));
;             w.z = cvtpk(bf_lo(ov.z) * bf_lo(gv.z), bf_hi(ov.z) * bf_hi(gv.z)); w.w = cvtpk(bf_lo(ov.w) * bf_lo(gv.w), bf_hi(ov.w) * bf_hi(gv.w));
;             *(u32x4*)gp = w; }
	v_lshlrev_b32_e32 v72, 16, v64
	v_and_b32_e32 v73, 0xffff0000, v64
	s_waitcnt vmcnt(7)
	v_mov_b32_e32 v84, v108
	v_mov_b32_e32 v85, v109
	v_mov_b32_e32 v86, v110
	v_mov_b32_e32 v87, v111
	v_lshlrev_b32_e32 v80, 16, v84
	v_and_b32_e32 v81, 0xffff0000, v84
	v_pk_mul_f32 v[72:73], v[72:73], v[80:81]
	v_lshlrev_b32_e32 v80, 16, v85
	v_cvt_pk_bf16_f32 v64, v72, v73
	v_lshlrev_b32_e32 v72, 16, v65
	v_and_b32_e32 v73, 0xffff0000, v65
	v_and_b32_e32 v81, 0xffff0000, v85
	v_pk_mul_f32 v[72:73], v[72:73], v[80:81]
	v_lshlrev_b32_e32 v80, 16, v86
	v_cvt_pk_bf16_f32 v65, v72, v73
	v_lshlrev_b32_e32 v72, 16, v66
	v_and_b32_e32 v73, 0xffff0000, v66
	v_and_b32_e32 v81, 0xffff0000, v86
	v_pk_mul_f32 v[72:73], v[72:73], v[80:81]
	v_lshlrev_b32_e32 v80, 16, v87
	v_cvt_pk_bf16_f32 v66, v72, v73
	v_lshlrev_b32_e32 v72, 16, v67
	v_and_b32_e32 v73, 0xffff0000, v67
	v_and_b32_e32 v81, 0xffff0000, v87
	v_pk_mul_f32 v[72:73], v[72:73], v[80:81]
	s_nop 0
	v_cvt_pk_bf16_f32 v67, v72, v73
	v_mad_u64_u32 v[72:73], s[14:15], v71, s50, v[68:69]
	v_mad_i32_i24 v73, s4, v244, v73
	v_lshl_add_u64 v[84:85], v[72:73], 0, v[176:177]
	v_or_b32_e32 v71, 20, v70
	flat_store_dwordx4 v[82:83], v[64:67] offset:2048
	ds_read_b128 v[64:67], v88 offset:3264
	s_waitcnt lgkmcnt(0)
	v_lshlrev_b32_e32 v72, 16, v64
	v_and_b32_e32 v73, 0xffff0000, v64
	s_waitcnt vmcnt(7)
	v_mov_b32_e32 v90, v112
	v_mov_b32_e32 v91, v113
	v_mov_b32_e32 v92, v114
	v_mov_b32_e32 v93, v115
	v_lshlrev_b32_e32 v80, 16, v90
	v_and_b32_e32 v81, 0xffff0000, v90
	v_pk_mul_f32 v[72:73], v[72:73], v[80:81]
	v_lshlrev_b32_e32 v80, 16, v91
	v_cvt_pk_bf16_f32 v64, v72, v73
	v_lshlrev_b32_e32 v72, 16, v65
	v_and_b32_e32 v73, 0xffff0000, v65
	v_and_b32_e32 v81, 0xffff0000, v91
	v_pk_mul_f32 v[72:73], v[72:73], v[80:81]
	v_lshlrev_b32_e32 v80, 16, v92
	v_cvt_pk_bf16_f32 v65, v72, v73
	v_lshlrev_b32_e32 v72, 16, v66
	v_and_b32_e32 v73, 0xffff0000, v66
	v_and_b32_e32 v81, 0xffff0000, v92
	v_pk_mul_f32 v[72:73], v[72:73], v[80:81]
	v_lshlrev_b32_e32 v80, 16, v93
	v_cvt_pk_bf16_f32 v66, v72, v73
	v_lshlrev_b32_e32 v72, 16, v67
	v_and_b32_e32 v73, 0xffff0000, v67
	v_and_b32_e32 v81, 0xffff0000, v93
	v_pk_mul_f32 v[72:73], v[72:73], v[80:81]
	s_nop 0
	v_cvt_pk_bf16_f32 v67, v72, v73
	v_mad_u64_u32 v[72:73], s[14:15], v71, s50, v[68:69]
	v_mad_i32_i24 v73, s4, v244, v73
	v_lshl_add_u64 v[86:87], v[72:73], 0, v[176:177]
	v_or_b32_e32 v71, 24, v70
	flat_store_dwordx4 v[84:85], v[64:67] offset:2048
	ds_read_b128 v[64:67], v88 offset:4352
	v_or_b32_e32 v70, 28, v70
	s_waitcnt lgkmcnt(0)
	v_lshlrev_b32_e32 v72, 16, v64
	v_and_b32_e32 v73, 0xffff0000, v64
	s_waitcnt vmcnt(7)
	v_mov_b32_e32 v90, v116
	v_mov_b32_e32 v91, v117
	v_mov_b32_e32 v92, v118
	v_mov_b32_e32 v93, v119
	v_lshlrev_b32_e32 v80, 16, v90
	v_and_b32_e32 v81, 0xffff0000, v90
	v_pk_mul_f32 v[72:73], v[72:73], v[80:81]
	v_lshlrev_b32_e32 v80, 16, v91
	v_cvt_pk_bf16_f32 v64, v72, v73
	v_lshlrev_b32_e32 v72, 16, v65
	v_and_b32_e32 v73, 0xffff0000, v65
	v_and_b32_e32 v81, 0xffff0000, v91
	v_pk_mul_f32 v[72:73], v[72:73], v[80:81]
	v_lshlrev_b32_e32 v80, 16, v92
	v_cvt_pk_bf16_f32 v65, v72, v73
	v_lshlrev_b32_e32 v72, 16, v66
	v_and_b32_e32 v73, 0xffff0000, v66
	v_and_b32_e32 v81, 0xffff0000, v92
	v_pk_mul_f32 v[72:73], v[72:73], v[80:81]
	v_lshlrev_b32_e32 v80, 16, v93
	v_cvt_pk_bf16_f32 v66, v72, v73
	v_lshlrev_b32_e32 v72, 16, v67
	v_and_b32_e32 v73, 0xffff0000, v67
	v_and_b32_e32 v81, 0xffff0000, v93
	v_pk_mul_f32 v[72:73], v[72:73], v[80:81]
	s_nop 0
	v_cvt_pk_bf16_f32 v67, v72, v73
	v_mad_u64_u32 v[72:73], s[14:15], v71, s50, v[68:69]
	v_mad_i32_i24 v73, s4, v244, v73
	v_lshl_add_u64 v[80:81], v[72:73], 0, v[176:177]
	v_mad_u64_u32 v[68:69], s[14:15], v70, s50, v[68:69]
	flat_store_dwordx4 v[86:87], v[64:67] offset:2048
	ds_read_b128 v[64:67], v88 offset:5440
	v_mad_i32_i24 v69, s4, v244, v69
	s_add_i32 s4, s72, 0x100
	s_cmpk_gt_u32 s72, 0x2ff
	s_mov_b32 s72, s4
	s_waitcnt lgkmcnt(0)
	v_lshlrev_b32_e32 v72, 16, v64
	v_and_b32_e32 v73, 0xffff0000, v64
	s_waitcnt vmcnt(7)
	v_mov_b32_e32 v90, v120
	v_mov_b32_e32 v91, v121
	v_mov_b32_e32 v92, v122
	v_mov_b32_e32 v93, v123
	v_lshlrev_b32_e32 v94, 16, v90
	v_and_b32_e32 v95, 0xffff0000, v90
	v_pk_mul_f32 v[72:73], v[72:73], v[94:95]
	v_lshlrev_b32_e32 v90, 16, v91
	v_cvt_pk_bf16_f32 v64, v72, v73
	v_lshlrev_b32_e32 v72, 16, v65
	v_and_b32_e32 v73, 0xffff0000, v65
	v_and_b32_e32 v91, 0xffff0000, v91
	v_pk_mul_f32 v[72:73], v[72:73], v[90:91]
	v_lshlrev_b32_e32 v90, 16, v92
	v_cvt_pk_bf16_f32 v65, v72, v73
	v_lshlrev_b32_e32 v72, 16, v66
	v_and_b32_e32 v73, 0xffff0000, v66
	v_and_b32_e32 v91, 0xffff0000, v92
	v_pk_mul_f32 v[72:73], v[72:73], v[90:91]
	v_lshlrev_b32_e32 v90, 16, v93
	v_cvt_pk_bf16_f32 v66, v72, v73
	v_lshlrev_b32_e32 v72, 16, v67
	v_and_b32_e32 v73, 0xffff0000, v67
	v_and_b32_e32 v91, 0xffff0000, v93
	v_pk_mul_f32 v[72:73], v[72:73], v[90:91]
	s_nop 0
	v_cvt_pk_bf16_f32 v67, v72, v73
	v_lshl_add_u64 v[72:73], v[68:69], 0, v[176:177]
	s_waitcnt vmcnt(6) lgkmcnt(0)
	v_mov_b32_e32 v68, v124
	v_mov_b32_e32 v69, v125
	v_mov_b32_e32 v70, v126
	v_mov_b32_e32 v71, v127
	v_lshlrev_b32_e32 v92, 16, v68
	flat_store_dwordx4 v[80:81], v[64:67] offset:2048
	ds_read_b128 v[64:67], v88 offset:6528
	v_and_b32_e32 v93, 0xffff0000, v68
	v_lshlrev_b32_e32 v68, 16, v69
	v_and_b32_e32 v69, 0xffff0000, v69
	s_waitcnt lgkmcnt(0)
; __device__ __forceinline__ unsigned cvtpk(float lo, float hi) { f32x2_t v = {lo, hi}; bf16x2_t b = __builtin_convertvector(v, bf16x2_t); return __builtin_bit_cast(unsigned, b); }
; __device__ __forceinline__ float bf_lo(unsigned w) { return __uint_as_float(w << 16); }
; __device__ __forceinline__ float bf_hi(unsigned w) { return __uint_as_float(w & 0xffff0000u); }
; #define LAS __attribute__((address_space(3)))
; DI unsigned f2bf(float f) { unsigned u = __builtin_bit_cast(unsigned, f); return (u + 0x7fffu + ((u >> 16) & 1u)) >> 16; }
; DI void ret_unit(LAS unsigned char* lds, bf16_t* MX, const bf16_t* VT, bf16_t* ST, int b, int hh, int qt, float lgf, float nlgb, int wave, const int mode) {
;     ...
;     for (int hf = 0; hf < 2; ++hf) {
; #pragma unroll
;         for (int i = 0; i < 16; ++i) { const int q = (i & 3) + 8 * (i >> 2) + 4 * he;
; #pragma unroll
;             for (int d4 = 0; d4 < 4; ++d4) *(LAS bf16_t*)(T + q * 272 + (d4 * 32 + re) * 2) = (bf16_t)f2bf(z[hf * 4 + d4][i] * nrm[i]); }
;     ...
;         for (int k = 0; k < 8; ++k) { const int id = le + 64 * k, q = id >> 4, ch = id & 15;
;             const u32x4 ov = *(const LAS u32x4*)(T + q * 272 + ch * 16);
;             bf16_t* gp = MX + (tok0 + q0w + q) * MXW + C_RG + hh * 256 + hf * 128 + ch * 8;
;             const u32x4 gv = *(const u32x4*)gp;
;             u32x4 w; w.x = cvtpk(bf_lo(ov.x) * bf_lo(gv.x), bf_hi(ov.x) * bf_hi(gv.x)); w.y = cvtpk(bf_lo(ov.y) * bf_lo(gv.y), bf_hi(ov.y) * bf_hi(gv.y));
;             w.z = cvtpk(bf_lo(ov.z) * bf_lo(gv.z), bf_hi(ov.z) * bf_hi(gv.z)); w.w = cvtpk(bf_lo(ov.w) * bf_lo(gv.w), bf_hi(ov.w) * bf_hi(gv.w));
;             *(u32x4*)gp = w; }
	v_lshlrev_b32_e32 v90, 16, v64
	v_and_b32_e32 v91, 0xffff0000, v64
	v_pk_mul_f32 v[90:91], v[90:91], v[92:93]
	s_nop 0
	v_cvt_pk_bf16_f32 v64, v90, v91
	v_lshlrev_b32_e32 v90, 16, v65
	v_and_b32_e32 v91, 0xffff0000, v65
	v_pk_mul_f32 v[68:69], v[90:91], v[68:69]
	v_lshlrev_b32_e32 v90, 16, v70
	v_cvt_pk_bf16_f32 v65, v68, v69
	v_lshlrev_b32_e32 v68, 16, v66
	v_and_b32_e32 v69, 0xffff0000, v66
	v_and_b32_e32 v91, 0xffff0000, v70
	v_pk_mul_f32 v[68:69], v[68:69], v[90:91]
	v_lshlrev_b32_e32 v70, 16, v71
	v_cvt_pk_bf16_f32 v66, v68, v69
	v_lshlrev_b32_e32 v68, 16, v67
	v_and_b32_e32 v69, 0xffff0000, v67
	v_and_b32_e32 v71, 0xffff0000, v71
	v_pk_mul_f32 v[68:69], v[68:69], v[70:71]
	s_nop 0
	v_cvt_pk_bf16_f32 v67, v68, v69
	flat_store_dwordx4 v[72:73], v[64:67] offset:2048
	s_waitcnt lgkmcnt(0)
	s_nop 1
	v_bfe_u32 v64, v48, 16, 1
	v_add3_u32 v48, v48, v64, s12
	ds_write_b16_d16_hi v145, v48
	v_bfe_u32 v48, v32, 16, 1
	v_add3_u32 v32, v32, v48, s12
	ds_write_b16_d16_hi v145, v32 offset:64
	v_bfe_u32 v32, v16, 16, 1
	v_add3_u32 v16, v16, v32, s12
	ds_write_b16_d16_hi v145, v16 offset:128
	v_bfe_u32 v16, v0, 16, 1
	v_add3_u32 v0, v0, v16, s12
	ds_write_b16_d16_hi v145, v0 offset:192
	v_mul_f32_e32 v0, v49, v129
	v_bfe_u32 v16, v0, 16, 1
	v_add3_u32 v0, v0, v16, s12
	ds_write_b16_d16_hi v145, v0 offset:272
	v_mul_f32_e32 v0, v33, v129
	v_bfe_u32 v16, v0, 16, 1
	v_add3_u32 v0, v0, v16, s12
	ds_write_b16_d16_hi v145, v0 offset:336
	v_mul_f32_e32 v0, v17, v129
	v_bfe_u32 v16, v0, 16, 1
	v_add3_u32 v0, v0, v16, s12
	ds_write_b16_d16_hi v145, v0 offset:400
	v_mul_f32_e32 v0, v1, v129
	v_bfe_u32 v1, v0, 16, 1
	v_add3_u32 v0, v0, v1, s12
	ds_write_b16_d16_hi v145, v0 offset:464
	v_mul_f32_e32 v0, v50, v130
	v_bfe_u32 v1, v0, 16, 1
	v_add3_u32 v0, v0, v1, s12
	ds_write_b16_d16_hi v145, v0 offset:544
	v_mul_f32_e32 v0, v34, v130
	v_bfe_u32 v1, v0, 16, 1
	v_add3_u32 v0, v0, v1, s12
	ds_write_b16_d16_hi v145, v0 offset:608
	v_mul_f32_e32 v0, v18, v130
	v_bfe_u32 v1, v0, 16, 1
	v_add3_u32 v0, v0, v1, s12
	ds_write_b16_d16_hi v145, v0 offset:672
	v_mul_f32_e32 v0, v2, v130
	v_bfe_u32 v1, v0, 16, 1
	v_add3_u32 v0, v0, v1, s12
	ds_write_b16_d16_hi v145, v0 offset:736
	v_mul_f32_e32 v0, v51, v131
	v_bfe_u32 v1, v0, 16, 1
	v_add3_u32 v0, v0, v1, s12
	ds_write_b16_d16_hi v145, v0 offset:816
	v_mul_f32_e32 v0, v35, v131
	v_bfe_u32 v1, v0, 16, 1
	v_add3_u32 v0, v0, v1, s12
	ds_write_b16_d16_hi v145, v0 offset:880
	v_mul_f32_e32 v0, v19, v131
	v_bfe_u32 v1, v0, 16, 1
	v_add3_u32 v0, v0, v1, s12
	ds_write_b16_d16_hi v145, v0 offset:944
	v_mul_f32_e32 v0, v3, v131
	v_bfe_u32 v1, v0, 16, 1
	v_add3_u32 v0, v0, v1, s12
	ds_write_b16_d16_hi v145, v0 offset:1008
	v_mul_f32_e32 v0, v52, v132
	v_bfe_u32 v1, v0, 16, 1
	v_add3_u32 v0, v0, v1, s12
	ds_write_b16_d16_hi v145, v0 offset:2176
	v_mul_f32_e32 v0, v36, v132
	v_bfe_u32 v1, v0, 16, 1
	v_add3_u32 v0, v0, v1, s12
	ds_write_b16_d16_hi v145, v0 offset:2240
	v_mul_f32_e32 v0, v20, v132
	v_bfe_u32 v1, v0, 16, 1
	v_add3_u32 v0, v0, v1, s12
	ds_write_b16_d16_hi v145, v0 offset:2304
	v_mul_f32_e32 v0, v4, v132
	v_bfe_u32 v1, v0, 16, 1
	v_add3_u32 v0, v0, v1, s12
	ds_write_b16_d16_hi v145, v0 offset:2368
	v_mul_f32_e32 v0, v53, v133
	v_bfe_u32 v1, v0, 16, 1
	v_add3_u32 v0, v0, v1, s12
	ds_write_b16_d16_hi v145, v0 offset:2448
	v_mul_f32_e32 v0, v37, v133
	v_bfe_u32 v1, v0, 16, 1
	v_add3_u32 v0, v0, v1, s12
	ds_write_b16_d16_hi v145, v0 offset:2512
	v_mul_f32_e32 v0, v21, v133
	v_bfe_u32 v1, v0, 16, 1
	v_add3_u32 v0, v0, v1, s12
	ds_write_b16_d16_hi v145, v0 offset:2576
	v_mul_f32_e32 v0, v5, v133
	v_bfe_u32 v1, v0, 16, 1
	v_add3_u32 v0, v0, v1, s12
	ds_write_b16_d16_hi v145, v0 offset:2640
	v_mul_f32_e32 v0, v54, v134
	v_bfe_u32 v1, v0, 16, 1
	v_add3_u32 v0, v0, v1, s12
	ds_write_b16_d16_hi v145, v0 offset:2720
	v_mul_f32_e32 v0, v38, v134
	v_bfe_u32 v1, v0, 16, 1
	v_add3_u32 v0, v0, v1, s12
	ds_write_b16_d16_hi v145, v0 offset:2784
	v_mul_f32_e32 v0, v22, v134
	v_bfe_u32 v1, v0, 16, 1
	v_add3_u32 v0, v0, v1, s12
	ds_write_b16_d16_hi v145, v0 offset:2848
	v_mul_f32_e32 v0, v6, v134
	v_bfe_u32 v1, v0, 16, 1
	v_add3_u32 v0, v0, v1, s12
	ds_write_b16_d16_hi v145, v0 offset:2912
	v_mul_f32_e32 v0, v55, v135
	v_bfe_u32 v1, v0, 16, 1
	v_add3_u32 v0, v0, v1, s12
	ds_write_b16_d16_hi v145, v0 offset:2992
	v_mul_f32_e32 v0, v39, v135
	v_bfe_u32 v1, v0, 16, 1
	v_add3_u32 v0, v0, v1, s12
	ds_write_b16_d16_hi v145, v0 offset:3056
	v_mul_f32_e32 v0, v23, v135
	v_bfe_u32 v1, v0, 16, 1
	v_add3_u32 v0, v0, v1, s12
	ds_write_b16_d16_hi v145, v0 offset:3120
	v_mul_f32_e32 v0, v7, v135
	v_bfe_u32 v1, v0, 16, 1
	v_add3_u32 v0, v0, v1, s12
	ds_write_b16_d16_hi v145, v0 offset:3184
	v_mul_f32_e32 v0, v56, v136
	v_bfe_u32 v1, v0, 16, 1
	v_add3_u32 v0, v0, v1, s12
	ds_write_b16_d16_hi v145, v0 offset:4352
	v_mul_f32_e32 v0, v40, v136
	v_bfe_u32 v1, v0, 16, 1
	v_add3_u32 v0, v0, v1, s12
	ds_write_b16_d16_hi v145, v0 offset:4416
	v_mul_f32_e32 v0, v24, v136
	v_bfe_u32 v1, v0, 16, 1
	v_add3_u32 v0, v0, v1, s12
	ds_write_b16_d16_hi v145, v0 offset:4480
	v_mul_f32_e32 v0, v8, v136
	v_bfe_u32 v1, v0, 16, 1
	v_add3_u32 v0, v0, v1, s12
	ds_write_b16_d16_hi v145, v0 offset:4544
	v_mul_f32_e32 v0, v57, v138
	v_bfe_u32 v1, v0, 16, 1
	v_add3_u32 v0, v0, v1, s12
	ds_write_b16_d16_hi v145, v0 offset:4624
	v_mul_f32_e32 v0, v41, v138
	v_bfe_u32 v1, v0, 16, 1
	v_add3_u32 v0, v0, v1, s12
	ds_write_b16_d16_hi v145, v0 offset:4688
	v_mul_f32_e32 v0, v25, v138
	v_bfe_u32 v1, v0, 16, 1
	v_add3_u32 v0, v0, v1, s12
	ds_write_b16_d16_hi v145, v0 offset:4752
	v_mul_f32_e32 v0, v9, v138
	v_bfe_u32 v1, v0, 16, 1
	v_add3_u32 v0, v0, v1, s12
	ds_write_b16_d16_hi v145, v0 offset:4816
; __device__ __forceinline__ unsigned cvtpk(float lo, float hi) { f32x2_t v = {lo, hi}; bf16x2_t b = __builtin_convertvector(v, bf16x2_t); return __builtin_bit_cast(unsigned, b); }
; __device__ __forceinline__ float bf_lo(unsigned w) { return __uint_as_float(w << 16); }
; __device__ __forceinline__ float bf_hi(unsigned w) { return __uint_as_float(w & 0xffff0000u); }
; #define LAS __attribute__((address_space(3)))
; DI unsigned f2bf(float f) { unsigned u = __builtin_bit_cast(unsigned, f); return (u + 0x7fffu + ((u >> 16) & 1u)) >> 16; }
; DI void ret_unit(LAS unsigned char* lds, bf16_t* MX, const bf16_t* VT, bf16_t* ST, int b, int hh, int qt, float lgf, float nlgb, int wave, const int mode) {
;     ...
;         for (int i = 0; i < 16; ++i) { const int q = (i & 3) + 8 * (i >> 2) + 4 * he;
; #pragma unroll
;             for (int d4 = 0; d4 < 4; ++d4) *(LAS bf16_t*)(T + q * 272 + (d4 * 32 + re) * 2) = (bf16_t)f2bf(z[hf * 4 + d4][i] * nrm[i]); }
;         asm volatile("s_waitcnt lgkmcnt(0)" ::: "memory");
; #pragma unroll
;         for (int k = 0; k < 8; ++k) { const int id = le + 64 * k, q = id >> 4, ch = id & 15;
;             const u32x4 ov = *(const LAS u32x4*)(T + q * 272 + ch * 16);
;             bf16_t* gp = MX + (tok0 + q0w + q) * MXW + C_RG + hh * 256 + hf * 128 + ch * 8;
;             const u32x4 gv = *(const u32x4*)gp;
;             u32x4 w; w.x = cvtpk(bf_lo(ov.x) * bf_lo(gv.x), bf_hi(ov.x) * bf_hi(gv.x)); w.y = cvtpk(bf_lo(ov.y) * bf_lo(gv.y), bf_hi(ov.y) * bf_hi(gv.y));
;             w.z = cvtpk(bf_lo(ov.z) * bf_lo(gv.z), bf_hi(ov.z) * bf_hi(gv.z)); w.w = cvtpk(bf_lo(ov.w) * bf_lo(gv.w), bf_hi(ov.w) * bf_hi(gv.w));
;             *(u32x4*)gp = w; }
	v_mul_f32_e32 v0, v58, v139
	v_bfe_u32 v1, v0, 16, 1
	v_add3_u32 v0, v0, v1, s12
	ds_write_b16_d16_hi v145, v0 offset:4896
	v_mul_f32_e32 v0, v42, v139
	v_bfe_u32 v1, v0, 16, 1
	v_add3_u32 v0, v0, v1, s12
	ds_write_b16_d16_hi v145, v0 offset:4960
	v_mul_f32_e32 v0, v26, v139
	v_bfe_u32 v1, v0, 16, 1
	v_add3_u32 v0, v0, v1, s12
	ds_write_b16_d16_hi v145, v0 offset:5024
	v_mul_f32_e32 v0, v10, v139
	v_bfe_u32 v1, v0, 16, 1
	v_add3_u32 v0, v0, v1, s12
	ds_write_b16_d16_hi v145, v0 offset:5088
	v_mul_f32_e32 v0, v59, v140
	v_bfe_u32 v1, v0, 16, 1
	v_add3_u32 v0, v0, v1, s12
	ds_write_b16_d16_hi v145, v0 offset:5168
	v_mul_f32_e32 v0, v43, v140
	v_bfe_u32 v1, v0, 16, 1
	v_add3_u32 v0, v0, v1, s12
	ds_write_b16_d16_hi v145, v0 offset:5232
	v_mul_f32_e32 v0, v27, v140
	v_bfe_u32 v1, v0, 16, 1
	v_add3_u32 v0, v0, v1, s12
	ds_write_b16_d16_hi v145, v0 offset:5296
	v_mul_f32_e32 v0, v11, v140
	v_bfe_u32 v1, v0, 16, 1
	v_add3_u32 v0, v0, v1, s12
	ds_write_b16_d16_hi v145, v0 offset:5360
	v_mul_f32_e32 v0, v60, v141
	v_bfe_u32 v1, v0, 16, 1
	v_add3_u32 v0, v0, v1, s12
	ds_write_b16_d16_hi v145, v0 offset:6528
	v_mul_f32_e32 v0, v44, v141
	v_bfe_u32 v1, v0, 16, 1
	v_add3_u32 v0, v0, v1, s12
	ds_write_b16_d16_hi v145, v0 offset:6592
	v_mul_f32_e32 v0, v28, v141
	v_bfe_u32 v1, v0, 16, 1
	v_add3_u32 v0, v0, v1, s12
	ds_write_b16_d16_hi v145, v0 offset:6656
	v_mul_f32_e32 v0, v12, v141
	v_bfe_u32 v1, v0, 16, 1
	v_add3_u32 v0, v0, v1, s12
	ds_write_b16_d16_hi v145, v0 offset:6720
	v_mul_f32_e32 v0, v61, v142
	v_bfe_u32 v1, v0, 16, 1
	v_add3_u32 v0, v0, v1, s12
	ds_write_b16_d16_hi v145, v0 offset:6800
	v_mul_f32_e32 v0, v45, v142
	v_bfe_u32 v1, v0, 16, 1
	v_add3_u32 v0, v0, v1, s12
	ds_write_b16_d16_hi v145, v0 offset:6864
	v_mul_f32_e32 v0, v29, v142
	v_bfe_u32 v1, v0, 16, 1
	v_add3_u32 v0, v0, v1, s12
	ds_write_b16_d16_hi v145, v0 offset:6928
	v_mul_f32_e32 v0, v13, v142
	v_bfe_u32 v1, v0, 16, 1
	v_add3_u32 v0, v0, v1, s12
	ds_write_b16_d16_hi v145, v0 offset:6992
	v_mul_f32_e32 v0, v62, v143
	v_bfe_u32 v1, v0, 16, 1
	v_add3_u32 v0, v0, v1, s12
	ds_write_b16_d16_hi v145, v0 offset:7072
	v_mul_f32_e32 v0, v46, v143
	v_bfe_u32 v1, v0, 16, 1
	v_add3_u32 v0, v0, v1, s12
	ds_write_b16_d16_hi v145, v0 offset:7136
	v_mul_f32_e32 v0, v30, v143
	v_bfe_u32 v1, v0, 16, 1
	v_add3_u32 v0, v0, v1, s12
	ds_write_b16_d16_hi v145, v0 offset:7200
	v_mul_f32_e32 v0, v14, v143
	v_bfe_u32 v1, v0, 16, 1
	v_add3_u32 v0, v0, v1, s12
	ds_write_b16_d16_hi v145, v0 offset:7264
	v_mul_f32_e32 v0, v63, v144
	v_bfe_u32 v1, v0, 16, 1
	v_add3_u32 v0, v0, v1, s12
	ds_write_b16_d16_hi v145, v0 offset:7344
	v_mul_f32_e32 v0, v47, v144
	v_bfe_u32 v1, v0, 16, 1
	v_add3_u32 v0, v0, v1, s12
	ds_write_b16_d16_hi v145, v0 offset:7408
	v_mul_f32_e32 v0, v31, v144
	v_bfe_u32 v1, v0, 16, 1
	v_add3_u32 v0, v0, v1, s12
	ds_write_b16_d16_hi v145, v0 offset:7472
	v_mul_f32_e32 v0, v15, v144
	v_bfe_u32 v1, v0, 16, 1
	v_add3_u32 v0, v0, v1, s12
	ds_write_b16_d16_hi v145, v0 offset:7536
	s_waitcnt lgkmcnt(0)
	global_load_dwordx4 v[12:15], v[74:75], off offset:2304
	global_load_dwordx4 v[16:19], v[76:77], off offset:2304
	global_load_dwordx4 v[20:23], v[78:79], off offset:2304
	global_load_dwordx4 v[24:27], v[82:83], off offset:2304
	global_load_dwordx4 v[28:31], v[84:85], off offset:2304
	global_load_dwordx4 v[32:35], v[86:87], off offset:2304
	global_load_dwordx4 v[36:39], v[80:81], off offset:2304
	global_load_dwordx4 v[40:43], v[72:73], off offset:2304
	ds_read_b128 v[0:3], v137
	s_waitcnt lgkmcnt(0)
	v_lshlrev_b32_e32 v8, 16, v0
	v_and_b32_e32 v9, 0xffff0000, v0
	s_waitcnt vmcnt(7)
	v_mov_b32_e32 v4, v12
	v_mov_b32_e32 v5, v13
	v_mov_b32_e32 v6, v14
	v_mov_b32_e32 v7, v15
	v_lshlrev_b32_e32 v10, 16, v4
	v_and_b32_e32 v11, 0xffff0000, v4
	v_pk_mul_f32 v[8:9], v[8:9], v[10:11]
	v_lshlrev_b32_e32 v4, 16, v5
	v_cvt_pk_bf16_f32 v0, v8, v9
	v_lshlrev_b32_e32 v8, 16, v1
	v_and_b32_e32 v9, 0xffff0000, v1
	v_and_b32_e32 v5, 0xffff0000, v5
	v_pk_mul_f32 v[4:5], v[8:9], v[4:5]
	v_lshlrev_b32_e32 v8, 16, v6
	v_cvt_pk_bf16_f32 v1, v4, v5
	v_lshlrev_b32_e32 v4, 16, v2
	v_and_b32_e32 v5, 0xffff0000, v2
	v_and_b32_e32 v9, 0xffff0000, v6
	v_pk_mul_f32 v[4:5], v[4:5], v[8:9]
	v_lshlrev_b32_e32 v6, 16, v7
	v_cvt_pk_bf16_f32 v2, v4, v5
	v_lshlrev_b32_e32 v4, 16, v3
	v_and_b32_e32 v5, 0xffff0000, v3
	v_and_b32_e32 v7, 0xffff0000, v7
	v_pk_mul_f32 v[4:5], v[4:5], v[6:7]
	s_nop 0
	v_cvt_pk_bf16_f32 v3, v4, v5
	s_waitcnt vmcnt(6) lgkmcnt(0)
	v_mov_b32_e32 v4, v16
	v_mov_b32_e32 v5, v17
	v_mov_b32_e32 v6, v18
	v_mov_b32_e32 v7, v19
	v_lshlrev_b32_e32 v10, 16, v4
	flat_store_dwordx4 v[74:75], v[0:3] offset:2304
	ds_read_b128 v[0:3], v88
	v_and_b32_e32 v11, 0xffff0000, v4
	v_lshlrev_b32_e32 v4, 16, v5
	v_and_b32_e32 v5, 0xffff0000, v5
	s_waitcnt lgkmcnt(0)
	v_lshlrev_b32_e32 v8, 16, v0
	v_and_b32_e32 v9, 0xffff0000, v0
	v_pk_mul_f32 v[8:9], v[8:9], v[10:11]
	s_nop 0
	v_cvt_pk_bf16_f32 v0, v8, v9
	v_lshlrev_b32_e32 v8, 16, v1
	v_and_b32_e32 v9, 0xffff0000, v1
	v_pk_mul_f32 v[4:5], v[8:9], v[4:5]
	v_lshlrev_b32_e32 v8, 16, v6
	v_cvt_pk_bf16_f32 v1, v4, v5
	v_lshlrev_b32_e32 v4, 16, v2
	v_and_b32_e32 v5, 0xffff0000, v2
	v_and_b32_e32 v9, 0xffff0000, v6
	v_pk_mul_f32 v[4:5], v[4:5], v[8:9]
	v_lshlrev_b32_e32 v6, 16, v7
	v_cvt_pk_bf16_f32 v2, v4, v5
	v_lshlrev_b32_e32 v4, 16, v3
	v_and_b32_e32 v5, 0xffff0000, v3
	v_and_b32_e32 v7, 0xffff0000, v7
	v_pk_mul_f32 v[4:5], v[4:5], v[6:7]
	s_nop 0
	v_cvt_pk_bf16_f32 v3, v4, v5
	s_waitcnt vmcnt(6) lgkmcnt(0)
	v_mov_b32_e32 v4, v20
	v_mov_b32_e32 v5, v21
	v_mov_b32_e32 v6, v22
	v_mov_b32_e32 v7, v23
	v_lshlrev_b32_e32 v10, 16, v4
	flat_store_dwordx4 v[76:77], v[0:3] offset:2304
	ds_read_b128 v[0:3], v88 offset:1088
	v_and_b32_e32 v11, 0xffff0000, v4
	v_lshlrev_b32_e32 v4, 16, v5
	v_and_b32_e32 v5, 0xffff0000, v5
	s_waitcnt lgkmcnt(0)
; __device__ __forceinline__ unsigned cvtpk(float lo, float hi) { f32x2_t v = {lo, hi}; bf16x2_t b = __builtin_convertvector(v, bf16x2_t); return __builtin_bit_cast(unsigned, b); }
; __device__ __forceinline__ float bf_lo(unsigned w) { return __uint_as_float(w << 16); }
; __device__ __forceinline__ float bf_hi(unsigned w) { return __uint_as_float(w & 0xffff0000u); }
; #define LAS __attribute__((address_space(3)))
; DI void ret_unit(LAS unsigned char* lds, bf16_t* MX, const bf16_t* VT, bf16_t* ST, int b, int hh, int qt, float lgf, float nlgb, int wave, const int mode) {
;     ...
;         for (int k = 0; k < 8; ++k) { const int id = le + 64 * k, q = id >> 4, ch = id & 15;
;             const u32x4 ov = *(const LAS u32x4*)(T + q * 272 + ch * 16);
;             bf16_t* gp = MX + (tok0 + q0w + q) * MXW + C_RG + hh * 256 + hf * 128 + ch * 8;
;             const u32x4 gv = *(const u32x4*)gp;
;             u32x4 w; w.x = cvtpk(bf_lo(ov.x) * bf_lo(gv.x), bf_hi(ov.x) * bf_hi(gv.x)); w.y = cvtpk(bf_lo(ov.y) * bf_lo(gv.y), bf_hi(ov.y) * bf_hi(gv.y));
;             w.z = cvtpk(bf_lo(ov.z) * bf_lo(gv.z), bf_hi(ov.z) * bf_hi(gv.z)); w.w = cvtpk(bf_lo(ov.w) * bf_lo(gv.w), bf_hi(ov.w) * bf_hi(gv.w));
;             *(u32x4*)gp = w; }
;         asm volatile("s_waitcnt lgkmcnt(0)" ::: "memory");
;     }
	v_lshlrev_b32_e32 v8, 16, v0
	v_and_b32_e32 v9, 0xffff0000, v0
	v_pk_mul_f32 v[8:9], v[8:9], v[10:11]
	s_nop 0
	v_cvt_pk_bf16_f32 v0, v8, v9
	v_lshlrev_b32_e32 v8, 16, v1
	v_and_b32_e32 v9, 0xffff0000, v1
	v_pk_mul_f32 v[4:5], v[8:9], v[4:5]
	v_lshlrev_b32_e32 v8, 16, v6
	v_cvt_pk_bf16_f32 v1, v4, v5
	v_lshlrev_b32_e32 v4, 16, v2
	v_and_b32_e32 v5, 0xffff0000, v2
	v_and_b32_e32 v9, 0xffff0000, v6
	v_pk_mul_f32 v[4:5], v[4:5], v[8:9]
	v_lshlrev_b32_e32 v6, 16, v7
	v_cvt_pk_bf16_f32 v2, v4, v5
	v_lshlrev_b32_e32 v4, 16, v3
	v_and_b32_e32 v5, 0xffff0000, v3
	v_and_b32_e32 v7, 0xffff0000, v7
	v_pk_mul_f32 v[4:5], v[4:5], v[6:7]
	s_nop 0
	v_cvt_pk_bf16_f32 v3, v4, v5
	s_waitcnt vmcnt(6) lgkmcnt(0)
	v_mov_b32_e32 v4, v24
	v_mov_b32_e32 v5, v25
	v_mov_b32_e32 v6, v26
	v_mov_b32_e32 v7, v27
	v_lshlrev_b32_e32 v10, 16, v4
	flat_store_dwordx4 v[78:79], v[0:3] offset:2304
	ds_read_b128 v[0:3], v88 offset:2176
	v_and_b32_e32 v11, 0xffff0000, v4
	v_lshlrev_b32_e32 v4, 16, v5
	v_and_b32_e32 v5, 0xffff0000, v5
	s_waitcnt lgkmcnt(0)
	v_lshlrev_b32_e32 v8, 16, v0
	v_and_b32_e32 v9, 0xffff0000, v0
	v_pk_mul_f32 v[8:9], v[8:9], v[10:11]
	s_nop 0
	v_cvt_pk_bf16_f32 v0, v8, v9
	v_lshlrev_b32_e32 v8, 16, v1
	v_and_b32_e32 v9, 0xffff0000, v1
	v_pk_mul_f32 v[4:5], v[8:9], v[4:5]
	v_lshlrev_b32_e32 v8, 16, v6
	v_cvt_pk_bf16_f32 v1, v4, v5
	v_lshlrev_b32_e32 v4, 16, v2
	v_and_b32_e32 v5, 0xffff0000, v2
	v_and_b32_e32 v9, 0xffff0000, v6
	v_pk_mul_f32 v[4:5], v[4:5], v[8:9]
	v_lshlrev_b32_e32 v6, 16, v7
	v_cvt_pk_bf16_f32 v2, v4, v5
	v_lshlrev_b32_e32 v4, 16, v3
	v_and_b32_e32 v5, 0xffff0000, v3
	v_and_b32_e32 v7, 0xffff0000, v7
	v_pk_mul_f32 v[4:5], v[4:5], v[6:7]
	s_nop 0
	v_cvt_pk_bf16_f32 v3, v4, v5
	s_waitcnt vmcnt(6) lgkmcnt(0)
	v_mov_b32_e32 v4, v28
	v_mov_b32_e32 v5, v29
	v_mov_b32_e32 v6, v30
	v_mov_b32_e32 v7, v31
	v_lshlrev_b32_e32 v10, 16, v4
	flat_store_dwordx4 v[82:83], v[0:3] offset:2304
	ds_read_b128 v[0:3], v88 offset:3264
	v_and_b32_e32 v11, 0xffff0000, v4
	v_lshlrev_b32_e32 v4, 16, v5
	v_and_b32_e32 v5, 0xffff0000, v5
	s_waitcnt lgkmcnt(0)
	v_lshlrev_b32_e32 v8, 16, v0
	v_and_b32_e32 v9, 0xffff0000, v0
	v_pk_mul_f32 v[8:9], v[8:9], v[10:11]
	s_nop 0
	v_cvt_pk_bf16_f32 v0, v8, v9
	v_lshlrev_b32_e32 v8, 16, v1
	v_and_b32_e32 v9, 0xffff0000, v1
	v_pk_mul_f32 v[4:5], v[8:9], v[4:5]
	v_lshlrev_b32_e32 v8, 16, v6
	v_cvt_pk_bf16_f32 v1, v4, v5
	v_lshlrev_b32_e32 v4, 16, v2
	v_and_b32_e32 v5, 0xffff0000, v2
	v_and_b32_e32 v9, 0xffff0000, v6
	v_pk_mul_f32 v[4:5], v[4:5], v[8:9]
	v_lshlrev_b32_e32 v6, 16, v7
	v_cvt_pk_bf16_f32 v2, v4, v5
	v_lshlrev_b32_e32 v4, 16, v3
	v_and_b32_e32 v5, 0xffff0000, v3
	v_and_b32_e32 v7, 0xffff0000, v7
	v_pk_mul_f32 v[4:5], v[4:5], v[6:7]
	s_nop 0
	v_cvt_pk_bf16_f32 v3, v4, v5
	s_waitcnt vmcnt(6) lgkmcnt(0)
	v_mov_b32_e32 v4, v32
	v_mov_b32_e32 v5, v33
	v_mov_b32_e32 v6, v34
	v_mov_b32_e32 v7, v35
	v_lshlrev_b32_e32 v10, 16, v4
	flat_store_dwordx4 v[84:85], v[0:3] offset:2304
	ds_read_b128 v[0:3], v88 offset:4352
	v_and_b32_e32 v11, 0xffff0000, v4
	v_lshlrev_b32_e32 v4, 16, v5
	v_and_b32_e32 v5, 0xffff0000, v5
	s_waitcnt lgkmcnt(0)
	v_lshlrev_b32_e32 v8, 16, v0
	v_and_b32_e32 v9, 0xffff0000, v0
	v_pk_mul_f32 v[8:9], v[8:9], v[10:11]
	s_nop 0
	v_cvt_pk_bf16_f32 v0, v8, v9
	v_lshlrev_b32_e32 v8, 16, v1
	v_and_b32_e32 v9, 0xffff0000, v1
	v_pk_mul_f32 v[4:5], v[8:9], v[4:5]
	v_lshlrev_b32_e32 v8, 16, v6
	v_cvt_pk_bf16_f32 v1, v4, v5
	v_lshlrev_b32_e32 v4, 16, v2
	v_and_b32_e32 v5, 0xffff0000, v2
	v_and_b32_e32 v9, 0xffff0000, v6
	v_pk_mul_f32 v[4:5], v[4:5], v[8:9]
	v_lshlrev_b32_e32 v6, 16, v7
	v_cvt_pk_bf16_f32 v2, v4, v5
	v_lshlrev_b32_e32 v4, 16, v3
	v_and_b32_e32 v5, 0xffff0000, v3
	v_and_b32_e32 v7, 0xffff0000, v7
	v_pk_mul_f32 v[4:5], v[4:5], v[6:7]
	s_nop 0
	v_cvt_pk_bf16_f32 v3, v4, v5
	s_waitcnt vmcnt(6) lgkmcnt(0)
	v_mov_b32_e32 v4, v36
	v_mov_b32_e32 v5, v37
	v_mov_b32_e32 v6, v38
	v_mov_b32_e32 v7, v39
	v_lshlrev_b32_e32 v10, 16, v4
	flat_store_dwordx4 v[86:87], v[0:3] offset:2304
	ds_read_b128 v[0:3], v88 offset:5440
	v_and_b32_e32 v11, 0xffff0000, v4
	v_lshlrev_b32_e32 v4, 16, v5
	v_and_b32_e32 v5, 0xffff0000, v5
	s_waitcnt lgkmcnt(0)
	v_lshlrev_b32_e32 v8, 16, v0
	v_and_b32_e32 v9, 0xffff0000, v0
	v_pk_mul_f32 v[8:9], v[8:9], v[10:11]
	s_nop 0
	v_cvt_pk_bf16_f32 v0, v8, v9
	v_lshlrev_b32_e32 v8, 16, v1
	v_and_b32_e32 v9, 0xffff0000, v1
	v_pk_mul_f32 v[4:5], v[8:9], v[4:5]
	v_lshlrev_b32_e32 v8, 16, v6
	v_cvt_pk_bf16_f32 v1, v4, v5
	v_lshlrev_b32_e32 v4, 16, v2
	v_and_b32_e32 v5, 0xffff0000, v2
	v_and_b32_e32 v9, 0xffff0000, v6
	v_pk_mul_f32 v[4:5], v[4:5], v[8:9]
	v_lshlrev_b32_e32 v6, 16, v7
	v_cvt_pk_bf16_f32 v2, v4, v5
	v_lshlrev_b32_e32 v4, 16, v3
	v_and_b32_e32 v5, 0xffff0000, v3
	v_and_b32_e32 v7, 0xffff0000, v7
	v_pk_mul_f32 v[4:5], v[4:5], v[6:7]
	s_nop 0
	v_cvt_pk_bf16_f32 v3, v4, v5
	s_waitcnt vmcnt(6) lgkmcnt(0)
	v_mov_b32_e32 v4, v40
	v_mov_b32_e32 v5, v41
	v_mov_b32_e32 v6, v42
	v_mov_b32_e32 v7, v43
	v_lshlrev_b32_e32 v10, 16, v4
	flat_store_dwordx4 v[80:81], v[0:3] offset:2304
	ds_read_b128 v[0:3], v88 offset:6528
	v_and_b32_e32 v11, 0xffff0000, v4
	v_lshlrev_b32_e32 v4, 16, v5
	v_and_b32_e32 v5, 0xffff0000, v5
	s_waitcnt lgkmcnt(0)
	v_lshlrev_b32_e32 v8, 16, v0
	v_and_b32_e32 v9, 0xffff0000, v0
	v_pk_mul_f32 v[8:9], v[8:9], v[10:11]
	s_nop 0
	v_cvt_pk_bf16_f32 v0, v8, v9
	v_lshlrev_b32_e32 v8, 16, v1
	v_and_b32_e32 v9, 0xffff0000, v1
	v_pk_mul_f32 v[4:5], v[8:9], v[4:5]
	v_lshlrev_b32_e32 v8, 16, v6
	v_cvt_pk_bf16_f32 v1, v4, v5
	v_lshlrev_b32_e32 v4, 16, v2
	v_and_b32_e32 v5, 0xffff0000, v2
	v_and_b32_e32 v9, 0xffff0000, v6
	v_pk_mul_f32 v[4:5], v[4:5], v[8:9]
	v_lshlrev_b32_e32 v6, 16, v7
	v_cvt_pk_bf16_f32 v2, v4, v5
	v_lshlrev_b32_e32 v4, 16, v3
	v_and_b32_e32 v5, 0xffff0000, v3
	v_and_b32_e32 v7, 0xffff0000, v7
	v_pk_mul_f32 v[4:5], v[4:5], v[6:7]
	s_nop 0
	v_cvt_pk_bf16_f32 v3, v4, v5
	flat_store_dwordx4 v[72:73], v[0:3] offset:2304
	s_waitcnt lgkmcnt(0)
	s_cbranch_scc1 .LBB0_181

; __device__ __forceinline__ float bf_lo(unsigned w) { return __uint_as_float(w << 16); }
; __device__ __forceinline__ float bf_hi(unsigned w) { return __uint_as_float(w & 0xffff0000u); }
;     __device__ __forceinline__ void operator()(const f32x4 (&acc)[2][2][4][2], const Unit& u, int wr, int wc, int fr, int fq) const {
;     ...
;         } else {
; #pragma unroll
;             for (int ai = 0; ai < 2; ++ai)
; #pragma unroll
;                 for (int m = 0; m < 4; ++m) { const int row = row0 + ai * HALF + m * 16;
;                     bf16_t* rowp = O + (size_t)row * ldc + u.pn * BM + cw; const bf16_t* gp = gate + (size_t)row * ldg + u.pn * BM + cw;
; #pragma unroll
;                     for (int bj = 0; bj < 2; ++bj) { const u32x4 gw = *(const u32x4*)(gp + bj * HALF);
;                         f32x4 v0 = acc[ai][bj][m][0], v1 = acc[ai][bj][m][1];
;                         v0[0] *= bf_lo(gw.x); v0[1] *= bf_hi(gw.x); v0[2] *= bf_lo(gw.y); v0[3] *= bf_hi(gw.y);
;                         v1[0] *= bf_lo(gw.z); v1[1] *= bf_hi(gw.z); v1[2] *= bf_lo(gw.w); v1[3] *= bf_hi(gw.w);
;                         if (mode == M_NAOUT) { const u32x4 pw = *(const u32x4*)(rowp + bj * HALF);
;                             v0[0] += bf_lo(pw.x); v0[1] += bf_hi(pw.x); v0[2] += bf_lo(pw.y); v0[3] += bf_hi(pw.y);
;                             v1[0] += bf_lo(pw.z); v1[1] += bf_hi(pw.z); v1[2] += bf_lo(pw.w); v1[3] += bf_hi(pw.w); }
;                         store8(rowp + bj * HALF, v0, v1); } }
.LBB0_385:
	s_cmp_lt_i32 s37, 3
	s_cbranch_scc1 .LBB0_486
	s_cmp_lg_u32 s37, 3
	s_cbranch_scc0 .LBB0_420
	s_lshl_b32 s6, s40, 8
	s_ashr_i32 s7, s6, 31
	s_lshl_b64 s[38:39], s[6:7], 1
	v_lshlrev_b64 v[128:129], 1, v[148:149]
	s_and_b64 vcc, exec, s[74:75]
	s_cbranch_vccnz .Lgate_naout
	v_mov_b32_e32 v138, v164
	v_mov_b64_e32 v[132:133], s[78:79]
	v_mad_i64_i32 v[132:133], s[98:99], v138, s50, v[132:133]
	v_lshl_add_u64 v[132:133], v[132:133], 0, s[38:39]
	v_lshl_add_u64 v[132:133], v[132:133], 0, v[128:129]
	global_load_dwordx4 v[182:185], v[132:133], off
	global_load_dwordx4 v[186:189], v[132:133], off offset:256
	v_add_u32_e32 v138, 0x10, v164
	v_mov_b64_e32 v[132:133], s[78:79]
	v_mad_i64_i32 v[132:133], s[98:99], v138, s50, v[132:133]
	v_lshl_add_u64 v[132:133], v[132:133], 0, s[38:39]
	v_lshl_add_u64 v[132:133], v[132:133], 0, v[128:129]
	global_load_dwordx4 v[190:193], v[132:133], off
	global_load_dwordx4 v[194:197], v[132:133], off offset:256
	v_add_u32_e32 v138, 0x20, v164
	v_mov_b64_e32 v[132:133], s[78:79]
	v_mad_i64_i32 v[132:133], s[98:99], v138, s50, v[132:133]
	v_lshl_add_u64 v[132:133], v[132:133], 0, s[38:39]
	v_lshl_add_u64 v[132:133], v[132:133], 0, v[128:129]
	global_load_dwordx4 v[198:201], v[132:133], off
	global_load_dwordx4 v[202:205], v[132:133], off offset:256
	v_add_u32_e32 v138, 0x30, v164
	v_mov_b64_e32 v[132:133], s[78:79]
	v_mad_i64_i32 v[132:133], s[98:99], v138, s50, v[132:133]
	v_lshl_add_u64 v[132:133], v[132:133], 0, s[38:39]
	v_lshl_add_u64 v[132:133], v[132:133], 0, v[128:129]
	global_load_dwordx4 v[206:209], v[132:133], off
	global_load_dwordx4 v[212:215], v[132:133], off offset:256
	v_add_u32_e32 v138, 0x80, v164
	v_mov_b64_e32 v[132:133], s[78:79]
	v_mad_i64_i32 v[132:133], s[98:99], v138, s50, v[132:133]
	v_lshl_add_u64 v[132:133], v[132:133], 0, s[38:39]
	v_lshl_add_u64 v[132:133], v[132:133], 0, v[128:129]
	global_load_dwordx4 v[216:219], v[132:133], off
	global_load_dwordx4 v[220:223], v[132:133], off offset:256
	v_add_u32_e32 v138, 0x90, v164
	v_mov_b64_e32 v[132:133], s[78:79]
	v_mad_i64_i32 v[132:133], s[98:99], v138, s50, v[132:133]
	v_lshl_add_u64 v[132:133], v[132:133], 0, s[38:39]
	v_lshl_add_u64 v[132:133], v[132:133], 0, v[128:129]
	global_load_dwordx4 v[232:235], v[132:133], off
	global_load_dwordx4 v[246:249], v[132:133], off offset:256
	s_waitcnt vmcnt(10)
	v_mov_b32_e32 v138, v164
	v_mad_i64_i32 v[130:131], s[98:99], s82, v138, 0
	v_lshl_add_u64 v[130:131], v[130:131], 1, s[84:85]
	v_lshl_add_u64 v[130:131], v[130:131], 0, s[38:39]
	v_lshl_add_u64 v[130:131], v[130:131], 0, v[128:129]
	v_lshlrev_b32_e32 v166, 16, v182
	v_and_b32_e32 v167, 0xffff0000, v182
	v_lshlrev_b32_e32 v168, 16, v183
	v_and_b32_e32 v169, 0xffff0000, v183
	v_lshlrev_b32_e32 v170, 16, v184
	v_and_b32_e32 v171, 0xffff0000, v184
	v_lshlrev_b32_e32 v172, 16, v185
	v_and_b32_e32 v173, 0xffff0000, v185
	v_pk_mul_f32 v[166:167], v[124:125], v[166:167]
	v_pk_mul_f32 v[168:169], v[126:127], v[168:169]
	v_pk_mul_f32 v[170:171], v[120:121], v[170:171]
	v_pk_mul_f32 v[172:173], v[122:123], v[172:173]
	v_cvt_pk_bf16_f32 v134, v166, v167
	v_cvt_pk_bf16_f32 v135, v168, v169
	v_cvt_pk_bf16_f32 v136, v170, v171
	v_cvt_pk_bf16_f32 v137, v172, v173
	global_store_dwordx4 v[130:131], v[134:137], off
	v_lshlrev_b32_e32 v166, 16, v186
	v_and_b32_e32 v167, 0xffff0000, v186
	v_lshlrev_b32_e32 v168, 16, v187
	v_and_b32_e32 v169, 0xffff0000, v187
	v_lshlrev_b32_e32 v170, 16, v188
	v_and_b32_e32 v171, 0xffff0000, v188
	v_lshlrev_b32_e32 v172, 16, v189
	v_and_b32_e32 v173, 0xffff0000, v189
	v_pk_mul_f32 v[166:167], v[108:109], v[166:167]
	v_pk_mul_f32 v[168:169], v[110:111], v[168:169]
	v_pk_mul_f32 v[170:171], v[104:105], v[170:171]
	v_pk_mul_f32 v[172:173], v[106:107], v[172:173]
	v_cvt_pk_bf16_f32 v134, v166, v167
	v_cvt_pk_bf16_f32 v135, v168, v169
	v_cvt_pk_bf16_f32 v136, v170, v171
	v_cvt_pk_bf16_f32 v137, v172, v173
	global_store_dwordx4 v[130:131], v[134:137], off offset:256
	v_add_u32_e32 v138, 0xa0, v164
	v_mov_b64_e32 v[132:133], s[78:79]
	v_mad_i64_i32 v[132:133], s[98:99], v138, s50, v[132:133]
	v_lshl_add_u64 v[132:133], v[132:133], 0, s[38:39]
	v_lshl_add_u64 v[132:133], v[132:133], 0, v[128:129]
	global_load_dwordx4 v[182:185], v[132:133], off
	global_load_dwordx4 v[186:189], v[132:133], off offset:256
	s_waitcnt vmcnt(12)
	v_add_u32_e32 v138, 0x10, v164
	v_mad_i64_i32 v[130:131], s[98:99], s82, v138, 0
	v_lshl_add_u64 v[130:131], v[130:131], 1, s[84:85]
	v_lshl_add_u64 v[130:131], v[130:131], 0, s[38:39]
	v_lshl_add_u64 v[130:131], v[130:131], 0, v[128:129]
	v_lshlrev_b32_e32 v166, 16, v190
	v_and_b32_e32 v167, 0xffff0000, v190
	v_lshlrev_b32_e32 v168, 16, v191
	v_and_b32_e32 v169, 0xffff0000, v191
	v_lshlrev_b32_e32 v170, 16, v192
	v_and_b32_e32 v171, 0xffff0000, v192
	v_lshlrev_b32_e32 v172, 16, v193
	v_and_b32_e32 v173, 0xffff0000, v193
	v_pk_mul_f32 v[166:167], v[116:117], v[166:167]
	v_pk_mul_f32 v[168:169], v[118:119], v[168:169]
	v_pk_mul_f32 v[170:171], v[112:113], v[170:171]
	v_pk_mul_f32 v[172:173], v[114:115], v[172:173]
	v_cvt_pk_bf16_f32 v134, v166, v167
	v_cvt_pk_bf16_f32 v135, v168, v169
	v_cvt_pk_bf16_f32 v136, v170, v171
	v_cvt_pk_bf16_f32 v137, v172, v173
	global_store_dwordx4 v[130:131], v[134:137], off
	v_lshlrev_b32_e32 v166, 16, v194
	v_and_b32_e32 v167, 0xffff0000, v194
	v_lshlrev_b32_e32 v168, 16, v195
	v_and_b32_e32 v169, 0xffff0000, v195
	v_lshlrev_b32_e32 v170, 16, v196
	v_and_b32_e32 v171, 0xffff0000, v196
	v_lshlrev_b32_e32 v172, 16, v197
	v_and_b32_e32 v173, 0xffff0000, v197
	v_pk_mul_f32 v[166:167], v[92:93], v[166:167]
	v_pk_mul_f32 v[168:169], v[94:95], v[168:169]
	v_pk_mul_f32 v[170:171], v[88:89], v[170:171]
	v_pk_mul_f32 v[172:173], v[90:91], v[172:173]
	v_cvt_pk_bf16_f32 v134, v166, v167
	v_cvt_pk_bf16_f32 v135, v168, v169
	v_cvt_pk_bf16_f32 v136, v170, v171
	v_cvt_pk_bf16_f32 v137, v172, v173
	global_store_dwordx4 v[130:131], v[134:137], off offset:256
	v_add_u32_e32 v138, 0xb0, v164
	v_mov_b64_e32 v[132:133], s[78:79]
	v_mad_i64_i32 v[132:133], s[98:99], v138, s50, v[132:133]
	v_lshl_add_u64 v[132:133], v[132:133], 0, s[38:39]
	v_lshl_add_u64 v[132:133], v[132:133], 0, v[128:129]
	global_load_dwordx4 v[190:193], v[132:133], off
	global_load_dwordx4 v[194:197], v[132:133], off offset:256
	s_waitcnt vmcnt(14)
; __device__ __forceinline__ float bf_lo(unsigned w) { return __uint_as_float(w << 16); }
; __device__ __forceinline__ float bf_hi(unsigned w) { return __uint_as_float(w & 0xffff0000u); }
;     __device__ __forceinline__ void operator()(const f32x4 (&acc)[2][2][4][2], const Unit& u, int wr, int wc, int fr, int fq) const {
;     ...
;         } else {
; #pragma unroll
;             for (int ai = 0; ai < 2; ++ai)
; #pragma unroll
;                 for (int m = 0; m < 4; ++m) { const int row = row0 + ai * HALF + m * 16;
;                     bf16_t* rowp = O + (size_t)row * ldc + u.pn * BM + cw; const bf16_t* gp = gate + (size_t)row * ldg + u.pn * BM + cw;
; #pragma unroll
;                     for (int bj = 0; bj < 2; ++bj) { const u32x4 gw = *(const u32x4*)(gp + bj * HALF);
;                         f32x4 v0 = acc[ai][bj][m][0], v1 = acc[ai][bj][m][1];
;                         v0[0] *= bf_lo(gw.x); v0[1] *= bf_hi(gw.x); v0[2] *= bf_lo(gw.y); v0[3] *= bf_hi(gw.y);
;                         v1[0] *= bf_lo(gw.z); v1[1] *= bf_hi(gw.z); v1[2] *= bf_lo(gw.w); v1[3] *= bf_hi(gw.w);
;                         if (mode == M_NAOUT) { const u32x4 pw = *(const u32x4*)(rowp + bj * HALF);
;                             v0[0] += bf_lo(pw.x); v0[1] += bf_hi(pw.x); v0[2] += bf_lo(pw.y); v0[3] += bf_hi(pw.y);
;                             v1[0] += bf_lo(pw.z); v1[1] += bf_hi(pw.z); v1[2] += bf_lo(pw.w); v1[3] += bf_hi(pw.w); }
;                         store8(rowp + bj * HALF, v0, v1); } }
	v_add_u32_e32 v138, 0x20, v164
	v_mad_i64_i32 v[130:131], s[98:99], s82, v138, 0
	v_lshl_add_u64 v[130:131], v[130:131], 1, s[84:85]
	v_lshl_add_u64 v[130:131], v[130:131], 0, s[38:39]
	v_lshl_add_u64 v[130:131], v[130:131], 0, v[128:129]
	v_lshlrev_b32_e32 v166, 16, v198
	v_and_b32_e32 v167, 0xffff0000, v198
	v_lshlrev_b32_e32 v168, 16, v199
	v_and_b32_e32 v169, 0xffff0000, v199
	v_lshlrev_b32_e32 v170, 16, v200
	v_and_b32_e32 v171, 0xffff0000, v200
	v_lshlrev_b32_e32 v172, 16, v201
	v_and_b32_e32 v173, 0xffff0000, v201
	v_pk_mul_f32 v[166:167], v[100:101], v[166:167]
	v_pk_mul_f32 v[168:169], v[102:103], v[168:169]
	v_pk_mul_f32 v[170:171], v[96:97], v[170:171]
	v_pk_mul_f32 v[172:173], v[98:99], v[172:173]
	v_cvt_pk_bf16_f32 v134, v166, v167
	v_cvt_pk_bf16_f32 v135, v168, v169
	v_cvt_pk_bf16_f32 v136, v170, v171
	v_cvt_pk_bf16_f32 v137, v172, v173
	global_store_dwordx4 v[130:131], v[134:137], off
	v_lshlrev_b32_e32 v166, 16, v202
	v_and_b32_e32 v167, 0xffff0000, v202
	v_lshlrev_b32_e32 v168, 16, v203
	v_and_b32_e32 v169, 0xffff0000, v203
	v_lshlrev_b32_e32 v170, 16, v204
	v_and_b32_e32 v171, 0xffff0000, v204
	v_lshlrev_b32_e32 v172, 16, v205
	v_and_b32_e32 v173, 0xffff0000, v205
	v_pk_mul_f32 v[166:167], v[76:77], v[166:167]
	v_pk_mul_f32 v[168:169], v[78:79], v[168:169]
	v_pk_mul_f32 v[170:171], v[72:73], v[170:171]
	v_pk_mul_f32 v[172:173], v[74:75], v[172:173]
	v_cvt_pk_bf16_f32 v134, v166, v167
	v_cvt_pk_bf16_f32 v135, v168, v169
	v_cvt_pk_bf16_f32 v136, v170, v171
	v_cvt_pk_bf16_f32 v137, v172, v173
	global_store_dwordx4 v[130:131], v[134:137], off offset:256
	s_waitcnt vmcnt(14)
	v_add_u32_e32 v138, 0x30, v164
	v_mad_i64_i32 v[130:131], s[98:99], s82, v138, 0
	v_lshl_add_u64 v[130:131], v[130:131], 1, s[84:85]
	v_lshl_add_u64 v[130:131], v[130:131], 0, s[38:39]
	v_lshl_add_u64 v[130:131], v[130:131], 0, v[128:129]
	v_lshlrev_b32_e32 v166, 16, v206
	v_and_b32_e32 v167, 0xffff0000, v206
	v_lshlrev_b32_e32 v168, 16, v207
	v_and_b32_e32 v169, 0xffff0000, v207
	v_lshlrev_b32_e32 v170, 16, v208
	v_and_b32_e32 v171, 0xffff0000, v208
	v_lshlrev_b32_e32 v172, 16, v209
	v_and_b32_e32 v173, 0xffff0000, v209
	v_pk_mul_f32 v[166:167], v[84:85], v[166:167]
	v_pk_mul_f32 v[168:169], v[86:87], v[168:169]
	v_pk_mul_f32 v[170:171], v[80:81], v[170:171]
	v_pk_mul_f32 v[172:173], v[82:83], v[172:173]
	v_cvt_pk_bf16_f32 v134, v166, v167
	v_cvt_pk_bf16_f32 v135, v168, v169
	v_cvt_pk_bf16_f32 v136, v170, v171
	v_cvt_pk_bf16_f32 v137, v172, v173
	global_store_dwordx4 v[130:131], v[134:137], off
	v_lshlrev_b32_e32 v166, 16, v212
	v_and_b32_e32 v167, 0xffff0000, v212
	v_lshlrev_b32_e32 v168, 16, v213
	v_and_b32_e32 v169, 0xffff0000, v213
	v_lshlrev_b32_e32 v170, 16, v214
	v_and_b32_e32 v171, 0xffff0000, v214
	v_lshlrev_b32_e32 v172, 16, v215
	v_and_b32_e32 v173, 0xffff0000, v215
	v_pk_mul_f32 v[166:167], v[68:69], v[166:167]
	v_pk_mul_f32 v[168:169], v[70:71], v[168:169]
	v_pk_mul_f32 v[170:171], v[64:65], v[170:171]
	v_pk_mul_f32 v[172:173], v[66:67], v[172:173]
	v_cvt_pk_bf16_f32 v134, v166, v167
	v_cvt_pk_bf16_f32 v135, v168, v169
	v_cvt_pk_bf16_f32 v136, v170, v171
	v_cvt_pk_bf16_f32 v137, v172, v173
	global_store_dwordx4 v[130:131], v[134:137], off offset:256
	s_waitcnt vmcnt(14)
	v_add_u32_e32 v138, 0x80, v164
	v_mad_i64_i32 v[130:131], s[98:99], s82, v138, 0
	v_lshl_add_u64 v[130:131], v[130:131], 1, s[84:85]
	v_lshl_add_u64 v[130:131], v[130:131], 0, s[38:39]
	v_lshl_add_u64 v[130:131], v[130:131], 0, v[128:129]
	v_lshlrev_b32_e32 v166, 16, v216
	v_and_b32_e32 v167, 0xffff0000, v216
	v_lshlrev_b32_e32 v168, 16, v217
	v_and_b32_e32 v169, 0xffff0000, v217
	v_lshlrev_b32_e32 v170, 16, v218
	v_and_b32_e32 v171, 0xffff0000, v218
	v_lshlrev_b32_e32 v172, 16, v219
	v_and_b32_e32 v173, 0xffff0000, v219
	v_pk_mul_f32 v[166:167], v[60:61], v[166:167]
	v_pk_mul_f32 v[168:169], v[62:63], v[168:169]
	v_pk_mul_f32 v[170:171], v[56:57], v[170:171]
	v_pk_mul_f32 v[172:173], v[58:59], v[172:173]
	v_cvt_pk_bf16_f32 v134, v166, v167
	v_cvt_pk_bf16_f32 v135, v168, v169
	v_cvt_pk_bf16_f32 v136, v170, v171
	v_cvt_pk_bf16_f32 v137, v172, v173
	global_store_dwordx4 v[130:131], v[134:137], off
	v_lshlrev_b32_e32 v166, 16, v220
	v_and_b32_e32 v167, 0xffff0000, v220
	v_lshlrev_b32_e32 v168, 16, v221
	v_and_b32_e32 v169, 0xffff0000, v221
	v_lshlrev_b32_e32 v170, 16, v222
	v_and_b32_e32 v171, 0xffff0000, v222
	v_lshlrev_b32_e32 v172, 16, v223
	v_and_b32_e32 v173, 0xffff0000, v223
	v_pk_mul_f32 v[166:167], v[44:45], v[166:167]
	v_pk_mul_f32 v[168:169], v[46:47], v[168:169]
	v_pk_mul_f32 v[170:171], v[40:41], v[170:171]
	v_pk_mul_f32 v[172:173], v[42:43], v[172:173]
	v_cvt_pk_bf16_f32 v134, v166, v167
	v_cvt_pk_bf16_f32 v135, v168, v169
	v_cvt_pk_bf16_f32 v136, v170, v171
	v_cvt_pk_bf16_f32 v137, v172, v173
	global_store_dwordx4 v[130:131], v[134:137], off offset:256
	s_waitcnt vmcnt(14)
; __device__ __forceinline__ float bf_lo(unsigned w) { return __uint_as_float(w << 16); }
; __device__ __forceinline__ float bf_hi(unsigned w) { return __uint_as_float(w & 0xffff0000u); }
;     __device__ __forceinline__ void operator()(const f32x4 (&acc)[2][2][4][2], const Unit& u, int wr, int wc, int fr, int fq) const {
;     ...
;         } else {
; #pragma unroll
;             for (int ai = 0; ai < 2; ++ai)
; #pragma unroll
;                 for (int m = 0; m < 4; ++m) { const int row = row0 + ai * HALF + m * 16;
;                     bf16_t* rowp = O + (size_t)row * ldc + u.pn * BM + cw; const bf16_t* gp = gate + (size_t)row * ldg + u.pn * BM + cw;
; #pragma unroll
;                     for (int bj = 0; bj < 2; ++bj) { const u32x4 gw = *(const u32x4*)(gp + bj * HALF);
;                         f32x4 v0 = acc[ai][bj][m][0], v1 = acc[ai][bj][m][1];
;                         v0[0] *= bf_lo(gw.x); v0[1] *= bf_hi(gw.x); v0[2] *= bf_lo(gw.y); v0[3] *= bf_hi(gw.y);
;                         v1[0] *= bf_lo(gw.z); v1[1] *= bf_hi(gw.z); v1[2] *= bf_lo(gw.w); v1[3] *= bf_hi(gw.w);
;                         if (mode == M_NAOUT) { const u32x4 pw = *(const u32x4*)(rowp + bj * HALF);
;                             v0[0] += bf_lo(pw.x); v0[1] += bf_hi(pw.x); v0[2] += bf_lo(pw.y); v0[3] += bf_hi(pw.y);
;                             v1[0] += bf_lo(pw.z); v1[1] += bf_hi(pw.z); v1[2] += bf_lo(pw.w); v1[3] += bf_hi(pw.w); }
;                         store8(rowp + bj * HALF, v0, v1); } }
	v_add_u32_e32 v138, 0x90, v164
	v_mad_i64_i32 v[130:131], s[98:99], s82, v138, 0
	v_lshl_add_u64 v[130:131], v[130:131], 1, s[84:85]
	v_lshl_add_u64 v[130:131], v[130:131], 0, s[38:39]
	v_lshl_add_u64 v[130:131], v[130:131], 0, v[128:129]
	v_lshlrev_b32_e32 v166, 16, v232
	v_and_b32_e32 v167, 0xffff0000, v232
	v_lshlrev_b32_e32 v168, 16, v233
	v_and_b32_e32 v169, 0xffff0000, v233
	v_lshlrev_b32_e32 v170, 16, v234
	v_and_b32_e32 v171, 0xffff0000, v234
	v_lshlrev_b32_e32 v172, 16, v235
	v_and_b32_e32 v173, 0xffff0000, v235
	v_pk_mul_f32 v[166:167], v[52:53], v[166:167]
	v_pk_mul_f32 v[168:169], v[54:55], v[168:169]
	v_pk_mul_f32 v[170:171], v[48:49], v[170:171]
	v_pk_mul_f32 v[172:173], v[50:51], v[172:173]
	v_cvt_pk_bf16_f32 v134, v166, v167
	v_cvt_pk_bf16_f32 v135, v168, v169
	v_cvt_pk_bf16_f32 v136, v170, v171
	v_cvt_pk_bf16_f32 v137, v172, v173
	global_store_dwordx4 v[130:131], v[134:137], off
	v_lshlrev_b32_e32 v166, 16, v246
	v_and_b32_e32 v167, 0xffff0000, v246
	v_lshlrev_b32_e32 v168, 16, v247
	v_and_b32_e32 v169, 0xffff0000, v247
	v_lshlrev_b32_e32 v170, 16, v248
	v_and_b32_e32 v171, 0xffff0000, v248
	v_lshlrev_b32_e32 v172, 16, v249
	v_and_b32_e32 v173, 0xffff0000, v249
	v_pk_mul_f32 v[166:167], v[28:29], v[166:167]
	v_pk_mul_f32 v[168:169], v[30:31], v[168:169]
	v_pk_mul_f32 v[170:171], v[24:25], v[170:171]
	v_pk_mul_f32 v[172:173], v[26:27], v[172:173]
	v_cvt_pk_bf16_f32 v134, v166, v167
	v_cvt_pk_bf16_f32 v135, v168, v169
	v_cvt_pk_bf16_f32 v136, v170, v171
	v_cvt_pk_bf16_f32 v137, v172, v173
	global_store_dwordx4 v[130:131], v[134:137], off offset:256
	s_waitcnt vmcnt(12)
	v_add_u32_e32 v138, 0xa0, v164
	v_mad_i64_i32 v[130:131], s[98:99], s82, v138, 0
	v_lshl_add_u64 v[130:131], v[130:131], 1, s[84:85]
	v_lshl_add_u64 v[130:131], v[130:131], 0, s[38:39]
	v_lshl_add_u64 v[130:131], v[130:131], 0, v[128:129]
	v_lshlrev_b32_e32 v166, 16, v182
	v_and_b32_e32 v167, 0xffff0000, v182
	v_lshlrev_b32_e32 v168, 16, v183
	v_and_b32_e32 v169, 0xffff0000, v183
	v_lshlrev_b32_e32 v170, 16, v184
	v_and_b32_e32 v171, 0xffff0000, v184
	v_lshlrev_b32_e32 v172, 16, v185
	v_and_b32_e32 v173, 0xffff0000, v185
	v_pk_mul_f32 v[166:167], v[36:37], v[166:167]
	v_pk_mul_f32 v[168:169], v[38:39], v[168:169]
	v_pk_mul_f32 v[170:171], v[32:33], v[170:171]
	v_pk_mul_f32 v[172:173], v[34:35], v[172:173]
	v_cvt_pk_bf16_f32 v134, v166, v167
	v_cvt_pk_bf16_f32 v135, v168, v169
	v_cvt_pk_bf16_f32 v136, v170, v171
	v_cvt_pk_bf16_f32 v137, v172, v173
	global_store_dwordx4 v[130:131], v[134:137], off
	v_lshlrev_b32_e32 v166, 16, v186
	v_and_b32_e32 v167, 0xffff0000, v186
	v_lshlrev_b32_e32 v168, 16, v187
	v_and_b32_e32 v169, 0xffff0000, v187
	v_lshlrev_b32_e32 v170, 16, v188
	v_and_b32_e32 v171, 0xffff0000, v188
	v_lshlrev_b32_e32 v172, 16, v189
	v_and_b32_e32 v173, 0xffff0000, v189
	v_pk_mul_f32 v[166:167], v[12:13], v[166:167]
	v_pk_mul_f32 v[168:169], v[14:15], v[168:169]
	v_pk_mul_f32 v[170:171], v[8:9], v[170:171]
	v_pk_mul_f32 v[172:173], v[10:11], v[172:173]
	v_cvt_pk_bf16_f32 v134, v166, v167
	v_cvt_pk_bf16_f32 v135, v168, v169
	v_cvt_pk_bf16_f32 v136, v170, v171
	v_cvt_pk_bf16_f32 v137, v172, v173
	global_store_dwordx4 v[130:131], v[134:137], off offset:256
	s_waitcnt vmcnt(10)
	v_add_u32_e32 v138, 0xb0, v164
	v_mad_i64_i32 v[130:131], s[98:99], s82, v138, 0
	v_lshl_add_u64 v[130:131], v[130:131], 1, s[84:85]
	v_lshl_add_u64 v[130:131], v[130:131], 0, s[38:39]
	v_lshl_add_u64 v[130:131], v[130:131], 0, v[128:129]
	v_lshlrev_b32_e32 v166, 16, v190
	v_and_b32_e32 v167, 0xffff0000, v190
	v_lshlrev_b32_e32 v168, 16, v191
	v_and_b32_e32 v169, 0xffff0000, v191
	v_lshlrev_b32_e32 v170, 16, v192
	v_and_b32_e32 v171, 0xffff0000, v192
	v_lshlrev_b32_e32 v172, 16, v193
	v_and_b32_e32 v173, 0xffff0000, v193
	v_pk_mul_f32 v[166:167], v[20:21], v[166:167]
	v_pk_mul_f32 v[168:169], v[22:23], v[168:169]
	v_pk_mul_f32 v[170:171], v[16:17], v[170:171]
	v_pk_mul_f32 v[172:173], v[18:19], v[172:173]
	v_cvt_pk_bf16_f32 v134, v166, v167
	v_cvt_pk_bf16_f32 v135, v168, v169
	v_cvt_pk_bf16_f32 v136, v170, v171
	v_cvt_pk_bf16_f32 v137, v172, v173
	global_store_dwordx4 v[130:131], v[134:137], off
	v_lshlrev_b32_e32 v166, 16, v194
	v_and_b32_e32 v167, 0xffff0000, v194
	v_lshlrev_b32_e32 v168, 16, v195
	v_and_b32_e32 v169, 0xffff0000, v195
	v_lshlrev_b32_e32 v170, 16, v196
	v_and_b32_e32 v171, 0xffff0000, v196
	v_lshlrev_b32_e32 v172, 16, v197
	v_and_b32_e32 v173, 0xffff0000, v197
	v_pk_mul_f32 v[166:167], v[4:5], v[166:167]
	v_pk_mul_f32 v[168:169], v[6:7], v[168:169]
	v_pk_mul_f32 v[170:171], v[0:1], v[170:171]
	v_pk_mul_f32 v[172:173], v[2:3], v[172:173]
	v_cvt_pk_bf16_f32 v134, v166, v167
	v_cvt_pk_bf16_f32 v135, v168, v169
	v_cvt_pk_bf16_f32 v136, v170, v171
	v_cvt_pk_bf16_f32 v137, v172, v173
	global_store_dwordx4 v[130:131], v[134:137], off offset:256
	s_branch .Lgate_done
; __device__ __forceinline__ float bf_lo(unsigned w) { return __uint_as_float(w << 16); }
; __device__ __forceinline__ float bf_hi(unsigned w) { return __uint_as_float(w & 0xffff0000u); }
;     __device__ __forceinline__ void operator()(const f32x4 (&acc)[2][2][4][2], const Unit& u, int wr, int wc, int fr, int fq) const {
;     ...
;         } else {
; #pragma unroll
;             for (int ai = 0; ai < 2; ++ai)
; #pragma unroll
;                 for (int m = 0; m < 4; ++m) { const int row = row0 + ai * HALF + m * 16;
;                     bf16_t* rowp = O + (size_t)row * ldc + u.pn * BM + cw; const bf16_t* gp = gate + (size_t)row * ldg + u.pn * BM + cw;
; #pragma unroll
;                     for (int bj = 0; bj < 2; ++bj) { const u32x4 gw = *(const u32x4*)(gp + bj * HALF);
;                         f32x4 v0 = acc[ai][bj][m][0], v1 = acc[ai][bj][m][1];
;                         v0[0] *= bf_lo(gw.x); v0[1] *= bf_hi(gw.x); v0[2] *= bf_lo(gw.y); v0[3] *= bf_hi(gw.y);
;                         v1[0] *= bf_lo(gw.z); v1[1] *= bf_hi(gw.z); v1[2] *= bf_lo(gw.w); v1[3] *= bf_hi(gw.w);
;                         if (mode == M_NAOUT) { const u32x4 pw = *(const u32x4*)(rowp + bj * HALF);
;                             v0[0] += bf_lo(pw.x); v0[1] += bf_hi(pw.x); v0[2] += bf_lo(pw.y); v0[3] += bf_hi(pw.y);
;                             v1[0] += bf_lo(pw.z); v1[1] += bf_hi(pw.z); v1[2] += bf_lo(pw.w); v1[3] += bf_hi(pw.w); }
;                         store8(rowp + bj * HALF, v0, v1); } }
.Lgate_naout:
	v_mov_b32_e32 v138, v164
	v_mov_b64_e32 v[132:133], s[78:79]
	v_mad_i64_i32 v[132:133], s[98:99], v138, s50, v[132:133]
	v_lshl_add_u64 v[132:133], v[132:133], 0, s[38:39]
	v_lshl_add_u64 v[132:133], v[132:133], 0, v[128:129]
	global_load_dwordx4 v[182:185], v[132:133], off
	global_load_dwordx4 v[186:189], v[132:133], off offset:256
	v_mad_i64_i32 v[130:131], s[98:99], s82, v138, 0
	v_lshl_add_u64 v[130:131], v[130:131], 1, s[84:85]
	v_lshl_add_u64 v[130:131], v[130:131], 0, s[38:39]
	v_lshl_add_u64 v[130:131], v[130:131], 0, v[128:129]
	global_load_dwordx4 v[190:193], v[130:131], off
	global_load_dwordx4 v[194:197], v[130:131], off offset:256
	v_add_u32_e32 v138, 0x10, v164
	v_mov_b64_e32 v[132:133], s[78:79]
	v_mad_i64_i32 v[132:133], s[98:99], v138, s50, v[132:133]
	v_lshl_add_u64 v[132:133], v[132:133], 0, s[38:39]
	v_lshl_add_u64 v[132:133], v[132:133], 0, v[128:129]
	global_load_dwordx4 v[198:201], v[132:133], off
	global_load_dwordx4 v[202:205], v[132:133], off offset:256
	v_mad_i64_i32 v[130:131], s[98:99], s82, v138, 0
	v_lshl_add_u64 v[130:131], v[130:131], 1, s[84:85]
	v_lshl_add_u64 v[130:131], v[130:131], 0, s[38:39]
	v_lshl_add_u64 v[130:131], v[130:131], 0, v[128:129]
	global_load_dwordx4 v[206:209], v[130:131], off
	global_load_dwordx4 v[212:215], v[130:131], off offset:256
	v_add_u32_e32 v138, 0x20, v164
	v_mov_b64_e32 v[132:133], s[78:79]
	v_mad_i64_i32 v[132:133], s[98:99], v138, s50, v[132:133]
	v_lshl_add_u64 v[132:133], v[132:133], 0, s[38:39]
	v_lshl_add_u64 v[132:133], v[132:133], 0, v[128:129]
	global_load_dwordx4 v[216:219], v[132:133], off
	global_load_dwordx4 v[220:223], v[132:133], off offset:256
	v_mad_i64_i32 v[130:131], s[98:99], s82, v138, 0
	v_lshl_add_u64 v[130:131], v[130:131], 1, s[84:85]
	v_lshl_add_u64 v[130:131], v[130:131], 0, s[38:39]
	v_lshl_add_u64 v[130:131], v[130:131], 0, v[128:129]
	global_load_dwordx4 v[232:235], v[130:131], off
	global_load_dwordx4 v[246:249], v[130:131], off offset:256
	s_waitcnt vmcnt(8)
	v_mov_b32_e32 v138, v164
	v_mad_i64_i32 v[130:131], s[98:99], s82, v138, 0
	v_lshl_add_u64 v[130:131], v[130:131], 1, s[84:85]
	v_lshl_add_u64 v[130:131], v[130:131], 0, s[38:39]
	v_lshl_add_u64 v[130:131], v[130:131], 0, v[128:129]
	v_lshlrev_b32_e32 v166, 16, v182
	v_and_b32_e32 v167, 0xffff0000, v182
	v_lshlrev_b32_e32 v168, 16, v183
	v_and_b32_e32 v169, 0xffff0000, v183
	v_lshlrev_b32_e32 v170, 16, v184
	v_and_b32_e32 v171, 0xffff0000, v184
	v_lshlrev_b32_e32 v172, 16, v185
	v_and_b32_e32 v173, 0xffff0000, v185
	v_pk_mul_f32 v[166:167], v[124:125], v[166:167]
	v_pk_mul_f32 v[168:169], v[126:127], v[168:169]
	v_pk_mul_f32 v[170:171], v[120:121], v[170:171]
	v_pk_mul_f32 v[172:173], v[122:123], v[172:173]
	v_lshlrev_b32_e32 v174, 16, v190
	v_and_b32_e32 v175, 0xffff0000, v190
	v_pk_add_f32 v[166:167], v[166:167], v[174:175]
	v_lshlrev_b32_e32 v178, 16, v191
	v_and_b32_e32 v179, 0xffff0000, v191
	v_pk_add_f32 v[168:169], v[168:169], v[178:179]
	v_lshlrev_b32_e32 v174, 16, v192
	v_and_b32_e32 v175, 0xffff0000, v192
	v_pk_add_f32 v[170:171], v[170:171], v[174:175]
	v_lshlrev_b32_e32 v178, 16, v193
	v_and_b32_e32 v179, 0xffff0000, v193
	v_pk_add_f32 v[172:173], v[172:173], v[178:179]
	v_cvt_pk_bf16_f32 v134, v166, v167
	v_cvt_pk_bf16_f32 v135, v168, v169
	v_cvt_pk_bf16_f32 v136, v170, v171
	v_cvt_pk_bf16_f32 v137, v172, v173
	global_store_dwordx4 v[130:131], v[134:137], off
	v_lshlrev_b32_e32 v166, 16, v186
	v_and_b32_e32 v167, 0xffff0000, v186
	v_lshlrev_b32_e32 v168, 16, v187
	v_and_b32_e32 v169, 0xffff0000, v187
	v_lshlrev_b32_e32 v170, 16, v188
	v_and_b32_e32 v171, 0xffff0000, v188
	v_lshlrev_b32_e32 v172, 16, v189
	v_and_b32_e32 v173, 0xffff0000, v189
	v_pk_mul_f32 v[166:167], v[108:109], v[166:167]
	v_pk_mul_f32 v[168:169], v[110:111], v[168:169]
	v_pk_mul_f32 v[170:171], v[104:105], v[170:171]
	v_pk_mul_f32 v[172:173], v[106:107], v[172:173]
	v_lshlrev_b32_e32 v174, 16, v194
	v_and_b32_e32 v175, 0xffff0000, v194
	v_pk_add_f32 v[166:167], v[166:167], v[174:175]
	v_lshlrev_b32_e32 v178, 16, v195
	v_and_b32_e32 v179, 0xffff0000, v195
	v_pk_add_f32 v[168:169], v[168:169], v[178:179]
	v_lshlrev_b32_e32 v174, 16, v196
	v_and_b32_e32 v175, 0xffff0000, v196
	v_pk_add_f32 v[170:171], v[170:171], v[174:175]
	v_lshlrev_b32_e32 v178, 16, v197
	v_and_b32_e32 v179, 0xffff0000, v197
	v_pk_add_f32 v[172:173], v[172:173], v[178:179]
	v_cvt_pk_bf16_f32 v134, v166, v167
	v_cvt_pk_bf16_f32 v135, v168, v169
	v_cvt_pk_bf16_f32 v136, v170, v171
	v_cvt_pk_bf16_f32 v137, v172, v173
	global_store_dwordx4 v[130:131], v[134:137], off offset:256
	v_add_u32_e32 v138, 0x30, v164
	v_mov_b64_e32 v[132:133], s[78:79]
	v_mad_i64_i32 v[132:133], s[98:99], v138, s50, v[132:133]
	v_lshl_add_u64 v[132:133], v[132:133], 0, s[38:39]
	v_lshl_add_u64 v[132:133], v[132:133], 0, v[128:129]
	global_load_dwordx4 v[182:185], v[132:133], off
	global_load_dwordx4 v[186:189], v[132:133], off offset:256
	v_mad_i64_i32 v[130:131], s[98:99], s82, v138, 0
	v_lshl_add_u64 v[130:131], v[130:131], 1, s[84:85]
	v_lshl_add_u64 v[130:131], v[130:131], 0, s[38:39]
	v_lshl_add_u64 v[130:131], v[130:131], 0, v[128:129]
	global_load_dwordx4 v[190:193], v[130:131], off
	global_load_dwordx4 v[194:197], v[130:131], off offset:256
	s_waitcnt vmcnt(10)
; __device__ __forceinline__ float bf_lo(unsigned w) { return __uint_as_float(w << 16); }
; __device__ __forceinline__ float bf_hi(unsigned w) { return __uint_as_float(w & 0xffff0000u); }
;     __device__ __forceinline__ void operator()(const f32x4 (&acc)[2][2][4][2], const Unit& u, int wr, int wc, int fr, int fq) const {
;     ...
;         } else {
; #pragma unroll
;             for (int ai = 0; ai < 2; ++ai)
; #pragma unroll
;                 for (int m = 0; m < 4; ++m) { const int row = row0 + ai * HALF + m * 16;
;                     bf16_t* rowp = O + (size_t)row * ldc + u.pn * BM + cw; const bf16_t* gp = gate + (size_t)row * ldg + u.pn * BM + cw;
; #pragma unroll
;                     for (int bj = 0; bj < 2; ++bj) { const u32x4 gw = *(const u32x4*)(gp + bj * HALF);
;                         f32x4 v0 = acc[ai][bj][m][0], v1 = acc[ai][bj][m][1];
;                         v0[0] *= bf_lo(gw.x); v0[1] *= bf_hi(gw.x); v0[2] *= bf_lo(gw.y); v0[3] *= bf_hi(gw.y);
;                         v1[0] *= bf_lo(gw.z); v1[1] *= bf_hi(gw.z); v1[2] *= bf_lo(gw.w); v1[3] *= bf_hi(gw.w);
;                         if (mode == M_NAOUT) { const u32x4 pw = *(const u32x4*)(rowp + bj * HALF);
;                             v0[0] += bf_lo(pw.x); v0[1] += bf_hi(pw.x); v0[2] += bf_lo(pw.y); v0[3] += bf_hi(pw.y);
;                             v1[0] += bf_lo(pw.z); v1[1] += bf_hi(pw.z); v1[2] += bf_lo(pw.w); v1[3] += bf_hi(pw.w); }
;                         store8(rowp + bj * HALF, v0, v1); } }
	v_add_u32_e32 v138, 0x10, v164
	v_mad_i64_i32 v[130:131], s[98:99], s82, v138, 0
	v_lshl_add_u64 v[130:131], v[130:131], 1, s[84:85]
	v_lshl_add_u64 v[130:131], v[130:131], 0, s[38:39]
	v_lshl_add_u64 v[130:131], v[130:131], 0, v[128:129]
	v_lshlrev_b32_e32 v166, 16, v198
	v_and_b32_e32 v167, 0xffff0000, v198
	v_lshlrev_b32_e32 v168, 16, v199
	v_and_b32_e32 v169, 0xffff0000, v199
	v_lshlrev_b32_e32 v170, 16, v200
	v_and_b32_e32 v171, 0xffff0000, v200
	v_lshlrev_b32_e32 v172, 16, v201
	v_and_b32_e32 v173, 0xffff0000, v201
	v_pk_mul_f32 v[166:167], v[116:117], v[166:167]
	v_pk_mul_f32 v[168:169], v[118:119], v[168:169]
	v_pk_mul_f32 v[170:171], v[112:113], v[170:171]
	v_pk_mul_f32 v[172:173], v[114:115], v[172:173]
	v_lshlrev_b32_e32 v174, 16, v206
	v_and_b32_e32 v175, 0xffff0000, v206
	v_pk_add_f32 v[166:167], v[166:167], v[174:175]
	v_lshlrev_b32_e32 v178, 16, v207
	v_and_b32_e32 v179, 0xffff0000, v207
	v_pk_add_f32 v[168:169], v[168:169], v[178:179]
	v_lshlrev_b32_e32 v174, 16, v208
	v_and_b32_e32 v175, 0xffff0000, v208
	v_pk_add_f32 v[170:171], v[170:171], v[174:175]
	v_lshlrev_b32_e32 v178, 16, v209
	v_and_b32_e32 v179, 0xffff0000, v209
	v_pk_add_f32 v[172:173], v[172:173], v[178:179]
	v_cvt_pk_bf16_f32 v134, v166, v167
	v_cvt_pk_bf16_f32 v135, v168, v169
	v_cvt_pk_bf16_f32 v136, v170, v171
	v_cvt_pk_bf16_f32 v137, v172, v173
	global_store_dwordx4 v[130:131], v[134:137], off
	v_lshlrev_b32_e32 v166, 16, v202
	v_and_b32_e32 v167, 0xffff0000, v202
	v_lshlrev_b32_e32 v168, 16, v203
	v_and_b32_e32 v169, 0xffff0000, v203
	v_lshlrev_b32_e32 v170, 16, v204
	v_and_b32_e32 v171, 0xffff0000, v204
	v_lshlrev_b32_e32 v172, 16, v205
	v_and_b32_e32 v173, 0xffff0000, v205
	v_pk_mul_f32 v[166:167], v[92:93], v[166:167]
	v_pk_mul_f32 v[168:169], v[94:95], v[168:169]
	v_pk_mul_f32 v[170:171], v[88:89], v[170:171]
	v_pk_mul_f32 v[172:173], v[90:91], v[172:173]
	v_lshlrev_b32_e32 v174, 16, v212
	v_and_b32_e32 v175, 0xffff0000, v212
	v_pk_add_f32 v[166:167], v[166:167], v[174:175]
	v_lshlrev_b32_e32 v178, 16, v213
	v_and_b32_e32 v179, 0xffff0000, v213
	v_pk_add_f32 v[168:169], v[168:169], v[178:179]
	v_lshlrev_b32_e32 v174, 16, v214
	v_and_b32_e32 v175, 0xffff0000, v214
	v_pk_add_f32 v[170:171], v[170:171], v[174:175]
	v_lshlrev_b32_e32 v178, 16, v215
	v_and_b32_e32 v179, 0xffff0000, v215
	v_pk_add_f32 v[172:173], v[172:173], v[178:179]
	v_cvt_pk_bf16_f32 v134, v166, v167
	v_cvt_pk_bf16_f32 v135, v168, v169
	v_cvt_pk_bf16_f32 v136, v170, v171
	v_cvt_pk_bf16_f32 v137, v172, v173
	global_store_dwordx4 v[130:131], v[134:137], off offset:256
	v_add_u32_e32 v138, 0x80, v164
	v_mov_b64_e32 v[132:133], s[78:79]
	v_mad_i64_i32 v[132:133], s[98:99], v138, s50, v[132:133]
	v_lshl_add_u64 v[132:133], v[132:133], 0, s[38:39]
	v_lshl_add_u64 v[132:133], v[132:133], 0, v[128:129]
	global_load_dwordx4 v[198:201], v[132:133], off
	global_load_dwordx4 v[202:205], v[132:133], off offset:256
	v_mad_i64_i32 v[130:131], s[98:99], s82, v138, 0
	v_lshl_add_u64 v[130:131], v[130:131], 1, s[84:85]
	v_lshl_add_u64 v[130:131], v[130:131], 0, s[38:39]
	v_lshl_add_u64 v[130:131], v[130:131], 0, v[128:129]
	global_load_dwordx4 v[206:209], v[130:131], off
	global_load_dwordx4 v[212:215], v[130:131], off offset:256
	s_waitcnt vmcnt(12)
	v_add_u32_e32 v138, 0x20, v164
	v_mad_i64_i32 v[130:131], s[98:99], s82, v138, 0
	v_lshl_add_u64 v[130:131], v[130:131], 1, s[84:85]
	v_lshl_add_u64 v[130:131], v[130:131], 0, s[38:39]
	v_lshl_add_u64 v[130:131], v[130:131], 0, v[128:129]
	v_lshlrev_b32_e32 v166, 16, v216
	v_and_b32_e32 v167, 0xffff0000, v216
	v_lshlrev_b32_e32 v168, 16, v217
	v_and_b32_e32 v169, 0xffff0000, v217
	v_lshlrev_b32_e32 v170, 16, v218
	v_and_b32_e32 v171, 0xffff0000, v218
	v_lshlrev_b32_e32 v172, 16, v219
	v_and_b32_e32 v173, 0xffff0000, v219
	v_pk_mul_f32 v[166:167], v[100:101], v[166:167]
	v_pk_mul_f32 v[168:169], v[102:103], v[168:169]
	v_pk_mul_f32 v[170:171], v[96:97], v[170:171]
	v_pk_mul_f32 v[172:173], v[98:99], v[172:173]
	v_lshlrev_b32_e32 v174, 16, v232
	v_and_b32_e32 v175, 0xffff0000, v232
	v_pk_add_f32 v[166:167], v[166:167], v[174:175]
	v_lshlrev_b32_e32 v178, 16, v233
	v_and_b32_e32 v179, 0xffff0000, v233
	v_pk_add_f32 v[168:169], v[168:169], v[178:179]
	v_lshlrev_b32_e32 v174, 16, v234
	v_and_b32_e32 v175, 0xffff0000, v234
	v_pk_add_f32 v[170:171], v[170:171], v[174:175]
	v_lshlrev_b32_e32 v178, 16, v235
	v_and_b32_e32 v179, 0xffff0000, v235
	v_pk_add_f32 v[172:173], v[172:173], v[178:179]
	v_cvt_pk_bf16_f32 v134, v166, v167
	v_cvt_pk_bf16_f32 v135, v168, v169
	v_cvt_pk_bf16_f32 v136, v170, v171
	v_cvt_pk_bf16_f32 v137, v172, v173
	global_store_dwordx4 v[130:131], v[134:137], off
	v_lshlrev_b32_e32 v166, 16, v220
	v_and_b32_e32 v167, 0xffff0000, v220
	v_lshlrev_b32_e32 v168, 16, v221
	v_and_b32_e32 v169, 0xffff0000, v221
	v_lshlrev_b32_e32 v170, 16, v222
	v_and_b32_e32 v171, 0xffff0000, v222
	v_lshlrev_b32_e32 v172, 16, v223
	v_and_b32_e32 v173, 0xffff0000, v223
	v_pk_mul_f32 v[166:167], v[76:77], v[166:167]
	v_pk_mul_f32 v[168:169], v[78:79], v[168:169]
	v_pk_mul_f32 v[170:171], v[72:73], v[170:171]
	v_pk_mul_f32 v[172:173], v[74:75], v[172:173]
	v_lshlrev_b32_e32 v174, 16, v246
	v_and_b32_e32 v175, 0xffff0000, v246
	v_pk_add_f32 v[166:167], v[166:167], v[174:175]
	v_lshlrev_b32_e32 v178, 16, v247
	v_and_b32_e32 v179, 0xffff0000, v247
	v_pk_add_f32 v[168:169], v[168:169], v[178:179]
	v_lshlrev_b32_e32 v174, 16, v248
	v_and_b32_e32 v175, 0xffff0000, v248
	v_pk_add_f32 v[170:171], v[170:171], v[174:175]
	v_lshlrev_b32_e32 v178, 16, v249
	v_and_b32_e32 v179, 0xffff0000, v249
	v_pk_add_f32 v[172:173], v[172:173], v[178:179]
	v_cvt_pk_bf16_f32 v134, v166, v167
	v_cvt_pk_bf16_f32 v135, v168, v169
	v_cvt_pk_bf16_f32 v136, v170, v171
	v_cvt_pk_bf16_f32 v137, v172, v173
	global_store_dwordx4 v[130:131], v[134:137], off offset:256
	v_add_u32_e32 v138, 0x90, v164
	v_mov_b64_e32 v[132:133], s[78:79]
	v_mad_i64_i32 v[132:133], s[98:99], v138, s50, v[132:133]
	v_lshl_add_u64 v[132:133], v[132:133], 0, s[38:39]
	v_lshl_add_u64 v[132:133], v[132:133], 0, v[128:129]
	global_load_dwordx4 v[216:219], v[132:133], off
	global_load_dwordx4 v[220:223], v[132:133], off offset:256
	v_mad_i64_i32 v[130:131], s[98:99], s82, v138, 0
	v_lshl_add_u64 v[130:131], v[130:131], 1, s[84:85]
	v_lshl_add_u64 v[130:131], v[130:131], 0, s[38:39]
	v_lshl_add_u64 v[130:131], v[130:131], 0, v[128:129]
	global_load_dwordx4 v[232:235], v[130:131], off
	global_load_dwordx4 v[246:249], v[130:131], off offset:256
	s_waitcnt vmcnt(12)
; __device__ __forceinline__ float bf_lo(unsigned w) { return __uint_as_float(w << 16); }
; __device__ __forceinline__ float bf_hi(unsigned w) { return __uint_as_float(w & 0xffff0000u); }
;     __device__ __forceinline__ void operator()(const f32x4 (&acc)[2][2][4][2], const Unit& u, int wr, int wc, int fr, int fq) const {
;     ...
;         } else {
; #pragma unroll
;             for (int ai = 0; ai < 2; ++ai)
; #pragma unroll
;                 for (int m = 0; m < 4; ++m) { const int row = row0 + ai * HALF + m * 16;
;                     bf16_t* rowp = O + (size_t)row * ldc + u.pn * BM + cw; const bf16_t* gp = gate + (size_t)row * ldg + u.pn * BM + cw;
; #pragma unroll
;                     for (int bj = 0; bj < 2; ++bj) { const u32x4 gw = *(const u32x4*)(gp + bj * HALF);
;                         f32x4 v0 = acc[ai][bj][m][0], v1 = acc[ai][bj][m][1];
;                         v0[0] *= bf_lo(gw.x); v0[1] *= bf_hi(gw.x); v0[2] *= bf_lo(gw.y); v0[3] *= bf_hi(gw.y);
;                         v1[0] *= bf_lo(gw.z); v1[1] *= bf_hi(gw.z); v1[2] *= bf_lo(gw.w); v1[3] *= bf_hi(gw.w);
;                         if (mode == M_NAOUT) { const u32x4 pw = *(const u32x4*)(rowp + bj * HALF);
;                             v0[0] += bf_lo(pw.x); v0[1] += bf_hi(pw.x); v0[2] += bf_lo(pw.y); v0[3] += bf_hi(pw.y);
;                             v1[0] += bf_lo(pw.z); v1[1] += bf_hi(pw.z); v1[2] += bf_lo(pw.w); v1[3] += bf_hi(pw.w); }
;                         store8(rowp + bj * HALF, v0, v1); } }
	v_add_u32_e32 v138, 0x30, v164
	v_mad_i64_i32 v[130:131], s[98:99], s82, v138, 0
	v_lshl_add_u64 v[130:131], v[130:131], 1, s[84:85]
	v_lshl_add_u64 v[130:131], v[130:131], 0, s[38:39]
	v_lshl_add_u64 v[130:131], v[130:131], 0, v[128:129]
	v_lshlrev_b32_e32 v166, 16, v182
	v_and_b32_e32 v167, 0xffff0000, v182
	v_lshlrev_b32_e32 v168, 16, v183
	v_and_b32_e32 v169, 0xffff0000, v183
	v_lshlrev_b32_e32 v170, 16, v184
	v_and_b32_e32 v171, 0xffff0000, v184
	v_lshlrev_b32_e32 v172, 16, v185
	v_and_b32_e32 v173, 0xffff0000, v185
	v_pk_mul_f32 v[166:167], v[84:85], v[166:167]
	v_pk_mul_f32 v[168:169], v[86:87], v[168:169]
	v_pk_mul_f32 v[170:171], v[80:81], v[170:171]
	v_pk_mul_f32 v[172:173], v[82:83], v[172:173]
	v_lshlrev_b32_e32 v174, 16, v190
	v_and_b32_e32 v175, 0xffff0000, v190
	v_pk_add_f32 v[166:167], v[166:167], v[174:175]
	v_lshlrev_b32_e32 v178, 16, v191
	v_and_b32_e32 v179, 0xffff0000, v191
	v_pk_add_f32 v[168:169], v[168:169], v[178:179]
	v_lshlrev_b32_e32 v174, 16, v192
	v_and_b32_e32 v175, 0xffff0000, v192
	v_pk_add_f32 v[170:171], v[170:171], v[174:175]
	v_lshlrev_b32_e32 v178, 16, v193
	v_and_b32_e32 v179, 0xffff0000, v193
	v_pk_add_f32 v[172:173], v[172:173], v[178:179]
	v_cvt_pk_bf16_f32 v134, v166, v167
	v_cvt_pk_bf16_f32 v135, v168, v169
	v_cvt_pk_bf16_f32 v136, v170, v171
	v_cvt_pk_bf16_f32 v137, v172, v173
	global_store_dwordx4 v[130:131], v[134:137], off
	v_lshlrev_b32_e32 v166, 16, v186
	v_and_b32_e32 v167, 0xffff0000, v186
	v_lshlrev_b32_e32 v168, 16, v187
	v_and_b32_e32 v169, 0xffff0000, v187
	v_lshlrev_b32_e32 v170, 16, v188
	v_and_b32_e32 v171, 0xffff0000, v188
	v_lshlrev_b32_e32 v172, 16, v189
	v_and_b32_e32 v173, 0xffff0000, v189
	v_pk_mul_f32 v[166:167], v[68:69], v[166:167]
	v_pk_mul_f32 v[168:169], v[70:71], v[168:169]
	v_pk_mul_f32 v[170:171], v[64:65], v[170:171]
	v_pk_mul_f32 v[172:173], v[66:67], v[172:173]
	v_lshlrev_b32_e32 v174, 16, v194
	v_and_b32_e32 v175, 0xffff0000, v194
	v_pk_add_f32 v[166:167], v[166:167], v[174:175]
	v_lshlrev_b32_e32 v178, 16, v195
	v_and_b32_e32 v179, 0xffff0000, v195
	v_pk_add_f32 v[168:169], v[168:169], v[178:179]
	v_lshlrev_b32_e32 v174, 16, v196
	v_and_b32_e32 v175, 0xffff0000, v196
	v_pk_add_f32 v[170:171], v[170:171], v[174:175]
	v_lshlrev_b32_e32 v178, 16, v197
	v_and_b32_e32 v179, 0xffff0000, v197
	v_pk_add_f32 v[172:173], v[172:173], v[178:179]
	v_cvt_pk_bf16_f32 v134, v166, v167
	v_cvt_pk_bf16_f32 v135, v168, v169
	v_cvt_pk_bf16_f32 v136, v170, v171
	v_cvt_pk_bf16_f32 v137, v172, v173
	global_store_dwordx4 v[130:131], v[134:137], off offset:256
	v_add_u32_e32 v138, 0xa0, v164
	v_mov_b64_e32 v[132:133], s[78:79]
	v_mad_i64_i32 v[132:133], s[98:99], v138, s50, v[132:133]
	v_lshl_add_u64 v[132:133], v[132:133], 0, s[38:39]
	v_lshl_add_u64 v[132:133], v[132:133], 0, v[128:129]
	global_load_dwordx4 v[182:185], v[132:133], off
	global_load_dwordx4 v[186:189], v[132:133], off offset:256
	v_mad_i64_i32 v[130:131], s[98:99], s82, v138, 0
	v_lshl_add_u64 v[130:131], v[130:131], 1, s[84:85]
	v_lshl_add_u64 v[130:131], v[130:131], 0, s[38:39]
	v_lshl_add_u64 v[130:131], v[130:131], 0, v[128:129]
	global_load_dwordx4 v[190:193], v[130:131], off
	global_load_dwordx4 v[194:197], v[130:131], off offset:256
	s_waitcnt vmcnt(12)
	v_add_u32_e32 v138, 0x80, v164
	v_mad_i64_i32 v[130:131], s[98:99], s82, v138, 0
	v_lshl_add_u64 v[130:131], v[130:131], 1, s[84:85]
	v_lshl_add_u64 v[130:131], v[130:131], 0, s[38:39]
	v_lshl_add_u64 v[130:131], v[130:131], 0, v[128:129]
	v_lshlrev_b32_e32 v166, 16, v198
	v_and_b32_e32 v167, 0xffff0000, v198
	v_lshlrev_b32_e32 v168, 16, v199
	v_and_b32_e32 v169, 0xffff0000, v199
	v_lshlrev_b32_e32 v170, 16, v200
	v_and_b32_e32 v171, 0xffff0000, v200
	v_lshlrev_b32_e32 v172, 16, v201
	v_and_b32_e32 v173, 0xffff0000, v201
	v_pk_mul_f32 v[166:167], v[60:61], v[166:167]
	v_pk_mul_f32 v[168:169], v[62:63], v[168:169]
	v_pk_mul_f32 v[170:171], v[56:57], v[170:171]
	v_pk_mul_f32 v[172:173], v[58:59], v[172:173]
	v_lshlrev_b32_e32 v174, 16, v206
	v_and_b32_e32 v175, 0xffff0000, v206
	v_pk_add_f32 v[166:167], v[166:167], v[174:175]
	v_lshlrev_b32_e32 v178, 16, v207
	v_and_b32_e32 v179, 0xffff0000, v207
	v_pk_add_f32 v[168:169], v[168:169], v[178:179]
	v_lshlrev_b32_e32 v174, 16, v208
	v_and_b32_e32 v175, 0xffff0000, v208
	v_pk_add_f32 v[170:171], v[170:171], v[174:175]
	v_lshlrev_b32_e32 v178, 16, v209
	v_and_b32_e32 v179, 0xffff0000, v209
	v_pk_add_f32 v[172:173], v[172:173], v[178:179]
	v_cvt_pk_bf16_f32 v134, v166, v167
	v_cvt_pk_bf16_f32 v135, v168, v169
	v_cvt_pk_bf16_f32 v136, v170, v171
	v_cvt_pk_bf16_f32 v137, v172, v173
	global_store_dwordx4 v[130:131], v[134:137], off
	v_lshlrev_b32_e32 v166, 16, v202
	v_and_b32_e32 v167, 0xffff0000, v202
	v_lshlrev_b32_e32 v168, 16, v203
	v_and_b32_e32 v169, 0xffff0000, v203
	v_lshlrev_b32_e32 v170, 16, v204
	v_and_b32_e32 v171, 0xffff0000, v204
	v_lshlrev_b32_e32 v172, 16, v205
	v_and_b32_e32 v173, 0xffff0000, v205
	v_pk_mul_f32 v[166:167], v[44:45], v[166:167]
	v_pk_mul_f32 v[168:169], v[46:47], v[168:169]
	v_pk_mul_f32 v[170:171], v[40:41], v[170:171]
	v_pk_mul_f32 v[172:173], v[42:43], v[172:173]
	v_lshlrev_b32_e32 v174, 16, v212
	v_and_b32_e32 v175, 0xffff0000, v212
	v_pk_add_f32 v[166:167], v[166:167], v[174:175]
	v_lshlrev_b32_e32 v178, 16, v213
	v_and_b32_e32 v179, 0xffff0000, v213
	v_pk_add_f32 v[168:169], v[168:169], v[178:179]
	v_lshlrev_b32_e32 v174, 16, v214
	v_and_b32_e32 v175, 0xffff0000, v214
	v_pk_add_f32 v[170:171], v[170:171], v[174:175]
	v_lshlrev_b32_e32 v178, 16, v215
	v_and_b32_e32 v179, 0xffff0000, v215
	v_pk_add_f32 v[172:173], v[172:173], v[178:179]
	v_cvt_pk_bf16_f32 v134, v166, v167
	v_cvt_pk_bf16_f32 v135, v168, v169
	v_cvt_pk_bf16_f32 v136, v170, v171
	v_cvt_pk_bf16_f32 v137, v172, v173
	global_store_dwordx4 v[130:131], v[134:137], off offset:256
	v_add_u32_e32 v138, 0xb0, v164
	v_mov_b64_e32 v[132:133], s[78:79]
	v_mad_i64_i32 v[132:133], s[98:99], v138, s50, v[132:133]
	v_lshl_add_u64 v[132:133], v[132:133], 0, s[38:39]
	v_lshl_add_u64 v[132:133], v[132:133], 0, v[128:129]
	global_load_dwordx4 v[198:201], v[132:133], off
	global_load_dwordx4 v[202:205], v[132:133], off offset:256
	v_mad_i64_i32 v[130:131], s[98:99], s82, v138, 0
	v_lshl_add_u64 v[130:131], v[130:131], 1, s[84:85]
	v_lshl_add_u64 v[130:131], v[130:131], 0, s[38:39]
	v_lshl_add_u64 v[130:131], v[130:131], 0, v[128:129]
	global_load_dwordx4 v[206:209], v[130:131], off
	global_load_dwordx4 v[212:215], v[130:131], off offset:256
	s_waitcnt vmcnt(12)
; __device__ __forceinline__ float bf_lo(unsigned w) { return __uint_as_float(w << 16); }
; __device__ __forceinline__ float bf_hi(unsigned w) { return __uint_as_float(w & 0xffff0000u); }
;     __device__ __forceinline__ void operator()(const f32x4 (&acc)[2][2][4][2], const Unit& u, int wr, int wc, int fr, int fq) const {
;     ...
;         } else {
; #pragma unroll
;             for (int ai = 0; ai < 2; ++ai)
; #pragma unroll
;                 for (int m = 0; m < 4; ++m) { const int row = row0 + ai * HALF + m * 16;
;                     bf16_t* rowp = O + (size_t)row * ldc + u.pn * BM + cw; const bf16_t* gp = gate + (size_t)row * ldg + u.pn * BM + cw;
; #pragma unroll
;                     for (int bj = 0; bj < 2; ++bj) { const u32x4 gw = *(const u32x4*)(gp + bj * HALF);
;                         f32x4 v0 = acc[ai][bj][m][0], v1 = acc[ai][bj][m][1];
;                         v0[0] *= bf_lo(gw.x); v0[1] *= bf_hi(gw.x); v0[2] *= bf_lo(gw.y); v0[3] *= bf_hi(gw.y);
;                         v1[0] *= bf_lo(gw.z); v1[1] *= bf_hi(gw.z); v1[2] *= bf_lo(gw.w); v1[3] *= bf_hi(gw.w);
;                         if (mode == M_NAOUT) { const u32x4 pw = *(const u32x4*)(rowp + bj * HALF);
;                             v0[0] += bf_lo(pw.x); v0[1] += bf_hi(pw.x); v0[2] += bf_lo(pw.y); v0[3] += bf_hi(pw.y);
;                             v1[0] += bf_lo(pw.z); v1[1] += bf_hi(pw.z); v1[2] += bf_lo(pw.w); v1[3] += bf_hi(pw.w); }
;                         store8(rowp + bj * HALF, v0, v1); } }
	v_add_u32_e32 v138, 0x90, v164
	v_mad_i64_i32 v[130:131], s[98:99], s82, v138, 0
	v_lshl_add_u64 v[130:131], v[130:131], 1, s[84:85]
	v_lshl_add_u64 v[130:131], v[130:131], 0, s[38:39]
	v_lshl_add_u64 v[130:131], v[130:131], 0, v[128:129]
	v_lshlrev_b32_e32 v166, 16, v216
	v_and_b32_e32 v167, 0xffff0000, v216
	v_lshlrev_b32_e32 v168, 16, v217
	v_and_b32_e32 v169, 0xffff0000, v217
	v_lshlrev_b32_e32 v170, 16, v218
	v_and_b32_e32 v171, 0xffff0000, v218
	v_lshlrev_b32_e32 v172, 16, v219
	v_and_b32_e32 v173, 0xffff0000, v219
	v_pk_mul_f32 v[166:167], v[52:53], v[166:167]
	v_pk_mul_f32 v[168:169], v[54:55], v[168:169]
	v_pk_mul_f32 v[170:171], v[48:49], v[170:171]
	v_pk_mul_f32 v[172:173], v[50:51], v[172:173]
	v_lshlrev_b32_e32 v174, 16, v232
	v_and_b32_e32 v175, 0xffff0000, v232
	v_pk_add_f32 v[166:167], v[166:167], v[174:175]
	v_lshlrev_b32_e32 v178, 16, v233
	v_and_b32_e32 v179, 0xffff0000, v233
	v_pk_add_f32 v[168:169], v[168:169], v[178:179]
	v_lshlrev_b32_e32 v174, 16, v234
	v_and_b32_e32 v175, 0xffff0000, v234
	v_pk_add_f32 v[170:171], v[170:171], v[174:175]
	v_lshlrev_b32_e32 v178, 16, v235
	v_and_b32_e32 v179, 0xffff0000, v235
	v_pk_add_f32 v[172:173], v[172:173], v[178:179]
	v_cvt_pk_bf16_f32 v134, v166, v167
	v_cvt_pk_bf16_f32 v135, v168, v169
	v_cvt_pk_bf16_f32 v136, v170, v171
	v_cvt_pk_bf16_f32 v137, v172, v173
	global_store_dwordx4 v[130:131], v[134:137], off
	v_lshlrev_b32_e32 v166, 16, v220
	v_and_b32_e32 v167, 0xffff0000, v220
	v_lshlrev_b32_e32 v168, 16, v221
	v_and_b32_e32 v169, 0xffff0000, v221
	v_lshlrev_b32_e32 v170, 16, v222
	v_and_b32_e32 v171, 0xffff0000, v222
	v_lshlrev_b32_e32 v172, 16, v223
	v_and_b32_e32 v173, 0xffff0000, v223
	v_pk_mul_f32 v[166:167], v[28:29], v[166:167]
	v_pk_mul_f32 v[168:169], v[30:31], v[168:169]
	v_pk_mul_f32 v[170:171], v[24:25], v[170:171]
	v_pk_mul_f32 v[172:173], v[26:27], v[172:173]
	v_lshlrev_b32_e32 v174, 16, v246
	v_and_b32_e32 v175, 0xffff0000, v246
	v_pk_add_f32 v[166:167], v[166:167], v[174:175]
	v_lshlrev_b32_e32 v178, 16, v247
	v_and_b32_e32 v179, 0xffff0000, v247
	v_pk_add_f32 v[168:169], v[168:169], v[178:179]
	v_lshlrev_b32_e32 v174, 16, v248
	v_and_b32_e32 v175, 0xffff0000, v248
	v_pk_add_f32 v[170:171], v[170:171], v[174:175]
	v_lshlrev_b32_e32 v178, 16, v249
	v_and_b32_e32 v179, 0xffff0000, v249
	v_pk_add_f32 v[172:173], v[172:173], v[178:179]
	v_cvt_pk_bf16_f32 v134, v166, v167
	v_cvt_pk_bf16_f32 v135, v168, v169
	v_cvt_pk_bf16_f32 v136, v170, v171
	v_cvt_pk_bf16_f32 v137, v172, v173
	global_store_dwordx4 v[130:131], v[134:137], off offset:256
	s_waitcnt vmcnt(8)
; __device__ __forceinline__ float bf_lo(unsigned w) { return __uint_as_float(w << 16); }
; __device__ __forceinline__ float bf_hi(unsigned w) { return __uint_as_float(w & 0xffff0000u); }
;     __device__ __forceinline__ void operator()(const f32x4 (&acc)[2][2][4][2], const Unit& u, int wr, int wc, int fr, int fq) const {
;     ...
;         } else {
; #pragma unroll
;             for (int ai = 0; ai < 2; ++ai)
; #pragma unroll
;                 for (int m = 0; m < 4; ++m) { const int row = row0 + ai * HALF + m * 16;
;                     bf16_t* rowp = O + (size_t)row * ldc + u.pn * BM + cw; const bf16_t* gp = gate + (size_t)row * ldg + u.pn * BM + cw;
; #pragma unroll
;                     for (int bj = 0; bj < 2; ++bj) { const u32x4 gw = *(const u32x4*)(gp + bj * HALF);
;                         f32x4 v0 = acc[ai][bj][m][0], v1 = acc[ai][bj][m][1];
;                         v0[0] *= bf_lo(gw.x); v0[1] *= bf_hi(gw.x); v0[2] *= bf_lo(gw.y); v0[3] *= bf_hi(gw.y);
;                         v1[0] *= bf_lo(gw.z); v1[1] *= bf_hi(gw.z); v1[2] *= bf_lo(gw.w); v1[3] *= bf_hi(gw.w);
;                         if (mode == M_NAOUT) { const u32x4 pw = *(const u32x4*)(rowp + bj * HALF);
;                             v0[0] += bf_lo(pw.x); v0[1] += bf_hi(pw.x); v0[2] += bf_lo(pw.y); v0[3] += bf_hi(pw.y);
;                             v1[0] += bf_lo(pw.z); v1[1] += bf_hi(pw.z); v1[2] += bf_lo(pw.w); v1[3] += bf_hi(pw.w); }
;                         store8(rowp + bj * HALF, v0, v1); } }
	v_add_u32_e32 v138, 0xa0, v164
	v_mad_i64_i32 v[130:131], s[98:99], s82, v138, 0
	v_lshl_add_u64 v[130:131], v[130:131], 1, s[84:85]
	v_lshl_add_u64 v[130:131], v[130:131], 0, s[38:39]
	v_lshl_add_u64 v[130:131], v[130:131], 0, v[128:129]
	v_lshlrev_b32_e32 v166, 16, v182
	v_and_b32_e32 v167, 0xffff0000, v182
	v_lshlrev_b32_e32 v168, 16, v183
	v_and_b32_e32 v169, 0xffff0000, v183
	v_lshlrev_b32_e32 v170, 16, v184
	v_and_b32_e32 v171, 0xffff0000, v184
	v_lshlrev_b32_e32 v172, 16, v185
	v_and_b32_e32 v173, 0xffff0000, v185
	v_pk_mul_f32 v[166:167], v[36:37], v[166:167]
	v_pk_mul_f32 v[168:169], v[38:39], v[168:169]
	v_pk_mul_f32 v[170:171], v[32:33], v[170:171]
	v_pk_mul_f32 v[172:173], v[34:35], v[172:173]
	v_lshlrev_b32_e32 v174, 16, v190
	v_and_b32_e32 v175, 0xffff0000, v190
	v_pk_add_f32 v[166:167], v[166:167], v[174:175]
	v_lshlrev_b32_e32 v178, 16, v191
	v_and_b32_e32 v179, 0xffff0000, v191
	v_pk_add_f32 v[168:169], v[168:169], v[178:179]
	v_lshlrev_b32_e32 v174, 16, v192
	v_and_b32_e32 v175, 0xffff0000, v192
	v_pk_add_f32 v[170:171], v[170:171], v[174:175]
	v_lshlrev_b32_e32 v178, 16, v193
	v_and_b32_e32 v179, 0xffff0000, v193
	v_pk_add_f32 v[172:173], v[172:173], v[178:179]
	v_cvt_pk_bf16_f32 v134, v166, v167
	v_cvt_pk_bf16_f32 v135, v168, v169
	v_cvt_pk_bf16_f32 v136, v170, v171
	v_cvt_pk_bf16_f32 v137, v172, v173
	global_store_dwordx4 v[130:131], v[134:137], off
	v_lshlrev_b32_e32 v166, 16, v186
	v_and_b32_e32 v167, 0xffff0000, v186
	v_lshlrev_b32_e32 v168, 16, v187
	v_and_b32_e32 v169, 0xffff0000, v187
	v_lshlrev_b32_e32 v170, 16, v188
	v_and_b32_e32 v171, 0xffff0000, v188
	v_lshlrev_b32_e32 v172, 16, v189
	v_and_b32_e32 v173, 0xffff0000, v189
	v_pk_mul_f32 v[166:167], v[12:13], v[166:167]
	v_pk_mul_f32 v[168:169], v[14:15], v[168:169]
	v_pk_mul_f32 v[170:171], v[8:9], v[170:171]
	v_pk_mul_f32 v[172:173], v[10:11], v[172:173]
	v_lshlrev_b32_e32 v174, 16, v194
	v_and_b32_e32 v175, 0xffff0000, v194
	v_pk_add_f32 v[166:167], v[166:167], v[174:175]
	v_lshlrev_b32_e32 v178, 16, v195
	v_and_b32_e32 v179, 0xffff0000, v195
	v_pk_add_f32 v[168:169], v[168:169], v[178:179]
	v_lshlrev_b32_e32 v174, 16, v196
	v_and_b32_e32 v175, 0xffff0000, v196
	v_pk_add_f32 v[170:171], v[170:171], v[174:175]
	v_lshlrev_b32_e32 v178, 16, v197
	v_and_b32_e32 v179, 0xffff0000, v197
	v_pk_add_f32 v[172:173], v[172:173], v[178:179]
	v_cvt_pk_bf16_f32 v134, v166, v167
	v_cvt_pk_bf16_f32 v135, v168, v169
	v_cvt_pk_bf16_f32 v136, v170, v171
	v_cvt_pk_bf16_f32 v137, v172, v173
	global_store_dwordx4 v[130:131], v[134:137], off offset:256
	s_waitcnt vmcnt(4)
	v_add_u32_e32 v138, 0xb0, v164
	v_mad_i64_i32 v[130:131], s[98:99], s82, v138, 0
	v_lshl_add_u64 v[130:131], v[130:131], 1, s[84:85]
	v_lshl_add_u64 v[130:131], v[130:131], 0, s[38:39]
	v_lshl_add_u64 v[130:131], v[130:131], 0, v[128:129]
	v_lshlrev_b32_e32 v166, 16, v198
	v_and_b32_e32 v167, 0xffff0000, v198
	v_lshlrev_b32_e32 v168, 16, v199
	v_and_b32_e32 v169, 0xffff0000, v199
	v_lshlrev_b32_e32 v170, 16, v200
	v_and_b32_e32 v171, 0xffff0000, v200
	v_lshlrev_b32_e32 v172, 16, v201
	v_and_b32_e32 v173, 0xffff0000, v201
	v_pk_mul_f32 v[166:167], v[20:21], v[166:167]
	v_pk_mul_f32 v[168:169], v[22:23], v[168:169]
	v_pk_mul_f32 v[170:171], v[16:17], v[170:171]
	v_pk_mul_f32 v[172:173], v[18:19], v[172:173]
	v_lshlrev_b32_e32 v174, 16, v206
	v_and_b32_e32 v175, 0xffff0000, v206
	v_pk_add_f32 v[166:167], v[166:167], v[174:175]
	v_lshlrev_b32_e32 v178, 16, v207
	v_and_b32_e32 v179, 0xffff0000, v207
	v_pk_add_f32 v[168:169], v[168:169], v[178:179]
	v_lshlrev_b32_e32 v174, 16, v208
	v_and_b32_e32 v175, 0xffff0000, v208
	v_pk_add_f32 v[170:171], v[170:171], v[174:175]
	v_lshlrev_b32_e32 v178, 16, v209
	v_and_b32_e32 v179, 0xffff0000, v209
	v_pk_add_f32 v[172:173], v[172:173], v[178:179]
	v_cvt_pk_bf16_f32 v134, v166, v167
	v_cvt_pk_bf16_f32 v135, v168, v169
	v_cvt_pk_bf16_f32 v136, v170, v171
	v_cvt_pk_bf16_f32 v137, v172, v173
	global_store_dwordx4 v[130:131], v[134:137], off
	v_lshlrev_b32_e32 v166, 16, v202
	v_and_b32_e32 v167, 0xffff0000, v202
	v_lshlrev_b32_e32 v168, 16, v203
	v_and_b32_e32 v169, 0xffff0000, v203
	v_lshlrev_b32_e32 v170, 16, v204
	v_and_b32_e32 v171, 0xffff0000, v204
	v_lshlrev_b32_e32 v172, 16, v205
	v_and_b32_e32 v173, 0xffff0000, v205
	v_pk_mul_f32 v[166:167], v[4:5], v[166:167]
	v_pk_mul_f32 v[168:169], v[6:7], v[168:169]
	v_pk_mul_f32 v[170:171], v[0:1], v[170:171]
	v_pk_mul_f32 v[172:173], v[2:3], v[172:173]
	v_lshlrev_b32_e32 v174, 16, v212
	v_and_b32_e32 v175, 0xffff0000, v212
	v_pk_add_f32 v[166:167], v[166:167], v[174:175]
	v_lshlrev_b32_e32 v178, 16, v213
	v_and_b32_e32 v179, 0xffff0000, v213
	v_pk_add_f32 v[168:169], v[168:169], v[178:179]
	v_lshlrev_b32_e32 v174, 16, v214
	v_and_b32_e32 v175, 0xffff0000, v214
	v_pk_add_f32 v[170:171], v[170:171], v[174:175]
	v_lshlrev_b32_e32 v178, 16, v215
	v_and_b32_e32 v179, 0xffff0000, v215
	v_pk_add_f32 v[172:173], v[172:173], v[178:179]
	v_cvt_pk_bf16_f32 v134, v166, v167
	v_cvt_pk_bf16_f32 v135, v168, v169
	v_cvt_pk_bf16_f32 v136, v170, v171
	v_cvt_pk_bf16_f32 v137, v172, v173
	global_store_dwordx4 v[130:131], v[134:137], off offset:256
